# K-loop: closing barrier signalled 1 MFMA early, 1-MFMA tail at s_setprio 2 (hide barrier hand-off)
# speedup vs baseline: 1.0022x; 1.0022x over previous
; #define PG8_STAGE_T(bufoff, gbase, voff, AUX) do { _Pragma("unroll") for (int _i = 0; _i < 2; ++_i) \
;         __builtin_amdgcn_global_load_lds((const unsigned*)((const char*)(gbase) + (voff)[_i]), (PG8_LAS unsigned*)(lds + (bufoff) + ldsw + _i * 8192), 16, 0, AUX); } while (0)
; #define PG8_LDA(dst, b, h) do { _Pragma("unroll") for (int m = 0; m < 4; ++m) _Pragma("unroll") for (int k = 0; k < 2; ++k) dst[m][k] = *(const PG8_LAS bf16x8*)(lds + PG8_SA(b, h) + aoff + m * 2048 + k * 1024); } while (0)
; #define PG8_LDB(dst, b, h) do { _Pragma("unroll") for (int n = 0; n < 2; ++n) _Pragma("unroll") for (int k = 0; k < 2; ++k) dst[n][k] = *(const PG8_LAS bf16x8*)(lds + PG8_SB(b, h) + boff + n * 2048 + k * 1024); } while (0)
; #define PG8_MMA(ai, bj, At, Bt) do { __builtin_amdgcn_s_setprio(1); _Pragma("unroll") for (int m = 0; m < 4; ++m) _Pragma("unroll") for (int n = 0; n < 2; ++n) _Pragma("unroll") for (int k = 0; k < 2; ++k) \
;         acc[ai][bj][m][n] = __builtin_amdgcn_mfma_f32_16x16x32_bf16(Bt[n][k], At[m][k], acc[ai][bj][m][n], 0, 0, 0); __builtin_amdgcn_s_setprio(0); } while (0)
; #define PG8_WAIT_V(n) asm volatile("s_waitcnt vmcnt(" #n ")" ::: "memory")
; #define PG8_WAIT_L(n) asm volatile("s_waitcnt lgkmcnt(" #n ")" ::: "memory")
; #define PG8_BAR __builtin_amdgcn_s_barrier()
;     ...
;             const bool last = (t == nt - 2);
;             const char* a1 = cA + (ptrdiff_t)(t + 1) * ck;
;             const char* a2 = last ? nA : cA + (ptrdiff_t)(t + 2) * ck; const char* b2 = last ? nB : cB + (ptrdiff_t)(t + 2) * ck;
;             const ptrdiff_t k3 = last ? nk : ck;
;             const char* a3 = a2 + k3; const char* b3 = b2 + k3;
;             if (last && has_next) S.a_ready(nxt);
;             if constexpr (SP2) {
;             int pei = 0; if constexpr (PEEL) { pei = __builtin_amdgcn_readfirstlane((t == 0 && ui > 0) ? 1 : 0); asm volatile("" : "+s"(pei)); }
;             const bool pe = pei != 0;
;             PG8_LDB(B0, 0, 0); PG8_LDB(B1, 0, 1); PG8_SCHED; PG8_LDA(At, 0, 0); if (!pe) { PG8_STAGE_T(PG8_SA(1, 1), a1 + hstep, voffA, AUX_A); }
;             if (!pe) { PG8_WAIT_V(8); } PG8_WAIT_L(0); PG8_BAR; PG8_MMA(0, 0, At, B0); PG8_MMA(0, 1, At, B1); PG8_BAR; PG8_SCHED;
;             PG8_LDA(At, 0, 1); PG8_STAGE_T(PG8_SB(0, 0), b2, voffB, AUX_B); PG8_STAGE_T(PG8_SB(0, 1), b2 + hstep, voffB, AUX_B); PG8_STAGE_T(PG8_SA(0, 0), a2, voffA, AUX_A);
.LBB0_244:
	ds_read_b128 v[146:149], v166
	ds_read_b128 v[162:165], v166 offset:1024
	ds_read_b128 v[170:173], v166 offset:2048
	ds_read_b128 v[174:177], v166 offset:3072
	ds_read_b128 v[178:181], v167
	ds_read_b128 v[182:185], v167 offset:1024
	ds_read_b128 v[186:189], v167 offset:2048
	ds_read_b128 v[190:193], v167 offset:3072
	s_add_u32 s44, s40, 0xfffc0080
	s_addc_u32 s45, s41, -1
	s_cmp_eq_u32 s70, 12
	s_cselect_b32 s49, s21, s45
	s_cselect_b32 s48, s37, s44
	s_cselect_b32 s45, s23, s69
	s_cselect_b32 s44, s67, s68
	v_lshl_add_u64 v[150:151], s[40:41], 0, v[136:137]
	s_add_i32 m0, s51, 0xc000
	ds_read_b128 v[196:199], v168
	ds_read_b128 v[200:203], v168 offset:1024
	ds_read_b128 v[204:207], v168 offset:2048
	ds_read_b128 v[208:211], v168 offset:3072
	ds_read_b128 v[212:215], v168 offset:4096
	ds_read_b128 v[216:219], v168 offset:5120
	ds_read_b128 v[220:223], v168 offset:6144
	ds_read_b128 v[224:227], v168 offset:7168
	global_load_lds_dwordx4 v[150:151], off
	v_lshl_add_u64 v[150:151], s[40:41], 0, v[138:139]
	s_add_i32 m0, s51, 0xe000
	s_nop 0
	global_load_lds_dwordx4 v[150:151], off
	s_waitcnt vmcnt(8)
	s_waitcnt lgkmcnt(0)
	s_barrier
	s_waitcnt lgkmcnt(0)
	v_mfma_f32_16x16x32_bf16 v[124:127], v[146:149], v[196:199], v[124:127]
	v_mfma_f32_16x16x32_bf16 v[120:123], v[170:173], v[196:199], v[120:123]
	v_mfma_f32_16x16x32_bf16 v[108:111], v[146:149], v[204:207], v[108:111]
	v_mfma_f32_16x16x32_bf16 v[104:107], v[170:173], v[204:207], v[104:107]
	v_mfma_f32_16x16x32_bf16 v[92:95], v[146:149], v[212:215], v[92:95]
	v_mfma_f32_16x16x32_bf16 v[88:91], v[170:173], v[212:215], v[88:91]
	v_mfma_f32_16x16x32_bf16 v[76:79], v[146:149], v[220:223], v[76:79]
	v_mfma_f32_16x16x32_bf16 v[72:75], v[170:173], v[220:223], v[72:75]
	v_mfma_f32_16x16x32_bf16 v[124:127], v[162:165], v[200:203], v[124:127]
	v_mfma_f32_16x16x32_bf16 v[120:123], v[174:177], v[200:203], v[120:123]
	v_mfma_f32_16x16x32_bf16 v[108:111], v[162:165], v[208:211], v[108:111]
	v_mfma_f32_16x16x32_bf16 v[104:107], v[174:177], v[208:211], v[104:107]
	v_mfma_f32_16x16x32_bf16 v[92:95], v[162:165], v[216:219], v[92:95]
	v_mfma_f32_16x16x32_bf16 v[88:91], v[174:177], v[216:219], v[88:91]
	v_mfma_f32_16x16x32_bf16 v[76:79], v[162:165], v[224:227], v[76:79]
	v_mfma_f32_16x16x32_bf16 v[72:75], v[174:177], v[224:227], v[72:75]
	v_mfma_f32_16x16x32_bf16 v[116:119], v[178:181], v[196:199], v[116:119]
	v_mfma_f32_16x16x32_bf16 v[112:115], v[186:189], v[196:199], v[112:115]
	v_mfma_f32_16x16x32_bf16 v[100:103], v[178:181], v[204:207], v[100:103]
	v_mfma_f32_16x16x32_bf16 v[96:99], v[186:189], v[204:207], v[96:99]
	v_mfma_f32_16x16x32_bf16 v[84:87], v[178:181], v[212:215], v[84:87]
	v_mfma_f32_16x16x32_bf16 v[80:83], v[186:189], v[212:215], v[80:83]
	v_mfma_f32_16x16x32_bf16 v[68:71], v[178:181], v[220:223], v[68:71]
	v_mfma_f32_16x16x32_bf16 v[64:67], v[186:189], v[220:223], v[64:67]
	v_mfma_f32_16x16x32_bf16 v[116:119], v[182:185], v[200:203], v[116:119]
	v_mfma_f32_16x16x32_bf16 v[112:115], v[190:193], v[200:203], v[112:115]
	v_mfma_f32_16x16x32_bf16 v[100:103], v[182:185], v[208:211], v[100:103]
	v_mfma_f32_16x16x32_bf16 v[96:99], v[190:193], v[208:211], v[96:99]
	v_mfma_f32_16x16x32_bf16 v[84:87], v[182:185], v[216:219], v[84:87]
	v_mfma_f32_16x16x32_bf16 v[80:83], v[190:193], v[216:219], v[80:83]
	v_mfma_f32_16x16x32_bf16 v[68:71], v[182:185], v[224:227], v[68:71]
	s_setprio 2
	s_barrier
	v_mfma_f32_16x16x32_bf16 v[64:67], v[190:193], v[224:227], v[64:67]
	s_setprio 0
	s_add_i32 s71, s58, s9
	v_lshl_add_u64 v[150:151], s[44:45], 0, v[132:133]
	s_mov_b32 m0, s71
	ds_read_b128 v[196:199], v168 offset:16384
	ds_read_b128 v[200:203], v168 offset:17408
	ds_read_b128 v[204:207], v168 offset:18432
	ds_read_b128 v[208:211], v168 offset:19456
	ds_read_b128 v[212:215], v168 offset:20480
	ds_read_b128 v[216:219], v168 offset:21504
	ds_read_b128 v[220:223], v168 offset:22528
	ds_read_b128 v[224:227], v168 offset:23552
	global_load_lds_dwordx4 v[150:151], off
	s_add_i32 m0, s71, 0x2000
	s_add_u32 s76, s44, 0x40000
	v_lshl_add_u64 v[154:155], s[44:45], 0, v[128:129]
	s_addc_u32 s77, s45, 0
	s_add_i32 s71, s59, s9
	global_load_lds_dwordx4 v[154:155], off
	v_lshl_add_u64 v[158:159], s[76:77], 0, v[132:133]
	s_mov_b32 m0, s71
	v_lshl_add_u64 v[228:229], s[48:49], 0, v[130:131]
	global_load_lds_dwordx4 v[158:159], off
	v_lshl_add_u64 v[158:159], s[76:77], 0, v[128:129]
	s_add_i32 m0, s71, 0x2000
	s_nop 0
	global_load_lds_dwordx4 v[158:159], off
	v_lshl_add_u64 v[158:159], s[48:49], 0, v[134:135]
	s_mov_b32 m0, s51
	s_nop 0
	global_load_lds_dwordx4 v[158:159], off
	s_mov_b32 m0, s52
	s_nop 0
	global_load_lds_dwordx4 v[228:229], off
	s_waitcnt vmcnt(8)
	s_waitcnt lgkmcnt(0)
	s_barrier
; #define PG8_STAGE_T(bufoff, gbase, voff, AUX) do { _Pragma("unroll") for (int _i = 0; _i < 2; ++_i) \
;         __builtin_amdgcn_global_load_lds((const unsigned*)((const char*)(gbase) + (voff)[_i]), (PG8_LAS unsigned*)(lds + (bufoff) + ldsw + _i * 8192), 16, 0, AUX); } while (0)
; #define PG8_LDA(dst, b, h) do { _Pragma("unroll") for (int m = 0; m < 4; ++m) _Pragma("unroll") for (int k = 0; k < 2; ++k) dst[m][k] = *(const PG8_LAS bf16x8*)(lds + PG8_SA(b, h) + aoff + m * 2048 + k * 1024); } while (0)
; #define PG8_LDB(dst, b, h) do { _Pragma("unroll") for (int n = 0; n < 2; ++n) _Pragma("unroll") for (int k = 0; k < 2; ++k) dst[n][k] = *(const PG8_LAS bf16x8*)(lds + PG8_SB(b, h) + boff + n * 2048 + k * 1024); } while (0)
; #define PG8_MMA(ai, bj, At, Bt) do { __builtin_amdgcn_s_setprio(1); _Pragma("unroll") for (int m = 0; m < 4; ++m) _Pragma("unroll") for (int n = 0; n < 2; ++n) _Pragma("unroll") for (int k = 0; k < 2; ++k) \
;         acc[ai][bj][m][n] = __builtin_amdgcn_mfma_f32_16x16x32_bf16(Bt[n][k], At[m][k], acc[ai][bj][m][n], 0, 0, 0); __builtin_amdgcn_s_setprio(0); } while (0)
; #define PG8_WAIT_V(n) asm volatile("s_waitcnt vmcnt(" #n ")" ::: "memory")
; #define PG8_WAIT_L(n) asm volatile("s_waitcnt lgkmcnt(" #n ")" ::: "memory")
; #define PG8_BAR __builtin_amdgcn_s_barrier()
; #define PG8_SCHED __builtin_amdgcn_sched_barrier(0)
;     ...
;             if (!pe) { PG8_WAIT_V(8); } PG8_WAIT_L(0); PG8_BAR; PG8_MMA(1, 0, At, B0); PG8_MMA(1, 1, At, B1); PG8_BAR; PG8_SCHED;
;             PG8_LDB(B0, 1, 0); PG8_LDB(B1, 1, 1); PG8_SCHED; PG8_LDA(At, 1, 0); PG8_STAGE_T(PG8_SA(0, 1), a2 + hstep, voffA, AUX_A);
;             if (!pe) { PG8_WAIT_V(8); } PG8_WAIT_L(0); PG8_BAR; PG8_MMA(0, 0, At, B0); PG8_MMA(0, 1, At, B1); PG8_BAR; PG8_SCHED;
	s_waitcnt lgkmcnt(0)
	v_mfma_f32_16x16x32_bf16 v[60:63], v[146:149], v[196:199], v[60:63]
	v_mfma_f32_16x16x32_bf16 v[56:59], v[170:173], v[196:199], v[56:59]
	v_mfma_f32_16x16x32_bf16 v[44:47], v[146:149], v[204:207], v[44:47]
	v_mfma_f32_16x16x32_bf16 v[40:43], v[170:173], v[204:207], v[40:43]
	v_mfma_f32_16x16x32_bf16 v[28:31], v[146:149], v[212:215], v[28:31]
	v_mfma_f32_16x16x32_bf16 v[24:27], v[170:173], v[212:215], v[24:27]
	v_mfma_f32_16x16x32_bf16 v[12:15], v[146:149], v[220:223], v[12:15]
	v_mfma_f32_16x16x32_bf16 v[8:11], v[170:173], v[220:223], v[8:11]
	v_mfma_f32_16x16x32_bf16 v[60:63], v[162:165], v[200:203], v[60:63]
	v_mfma_f32_16x16x32_bf16 v[56:59], v[174:177], v[200:203], v[56:59]
	v_mfma_f32_16x16x32_bf16 v[44:47], v[162:165], v[208:211], v[44:47]
	v_mfma_f32_16x16x32_bf16 v[40:43], v[174:177], v[208:211], v[40:43]
	v_mfma_f32_16x16x32_bf16 v[28:31], v[162:165], v[216:219], v[28:31]
	v_mfma_f32_16x16x32_bf16 v[24:27], v[174:177], v[216:219], v[24:27]
	v_mfma_f32_16x16x32_bf16 v[12:15], v[162:165], v[224:227], v[12:15]
	v_mfma_f32_16x16x32_bf16 v[8:11], v[174:177], v[224:227], v[8:11]
	v_mfma_f32_16x16x32_bf16 v[52:55], v[178:181], v[196:199], v[52:55]
	v_mfma_f32_16x16x32_bf16 v[48:51], v[186:189], v[196:199], v[48:51]
	v_mfma_f32_16x16x32_bf16 v[36:39], v[178:181], v[204:207], v[36:39]
	v_mfma_f32_16x16x32_bf16 v[32:35], v[186:189], v[204:207], v[32:35]
	v_mfma_f32_16x16x32_bf16 v[20:23], v[178:181], v[212:215], v[20:23]
	v_mfma_f32_16x16x32_bf16 v[16:19], v[186:189], v[212:215], v[16:19]
	v_mfma_f32_16x16x32_bf16 v[4:7], v[178:181], v[220:223], v[4:7]
	v_mfma_f32_16x16x32_bf16 v[0:3], v[186:189], v[220:223], v[0:3]
	v_mfma_f32_16x16x32_bf16 v[52:55], v[182:185], v[200:203], v[52:55]
	v_mfma_f32_16x16x32_bf16 v[48:51], v[190:193], v[200:203], v[48:51]
	v_mfma_f32_16x16x32_bf16 v[36:39], v[182:185], v[208:211], v[36:39]
	v_mfma_f32_16x16x32_bf16 v[32:35], v[190:193], v[208:211], v[32:35]
	v_mfma_f32_16x16x32_bf16 v[20:23], v[182:185], v[216:219], v[20:23]
	v_mfma_f32_16x16x32_bf16 v[16:19], v[190:193], v[216:219], v[16:19]
	v_mfma_f32_16x16x32_bf16 v[4:7], v[182:185], v[224:227], v[4:7]
	s_setprio 2
	s_barrier
	v_mfma_f32_16x16x32_bf16 v[0:3], v[190:193], v[224:227], v[0:3]
	s_setprio 0
	s_add_i32 s71, 0, 0x18000
	v_add_u32_e32 v144, s71, v153
	s_add_i32 s76, 0, 0x1c000
	ds_read_b128 v[146:149], v144
	ds_read_b128 v[162:165], v144 offset:1024
	ds_read_b128 v[170:173], v144 offset:2048
	ds_read_b128 v[174:177], v144 offset:3072
	v_add_u32_e32 v144, s76, v153
	ds_read_b128 v[178:181], v144
	ds_read_b128 v[182:185], v144 offset:1024
	ds_read_b128 v[186:189], v144 offset:2048
	ds_read_b128 v[190:193], v144 offset:3072
	s_add_u32 s48, s48, 0x40000
	s_addc_u32 s49, s49, 0
	s_mov_b32 m0, s53
	v_lshl_add_u64 v[230:231], s[48:49], 0, v[134:135]
	ds_read_b128 v[196:199], v168 offset:32768
	ds_read_b128 v[200:203], v168 offset:33792
	ds_read_b128 v[204:207], v168 offset:34816
	ds_read_b128 v[208:211], v168 offset:35840
	ds_read_b128 v[212:215], v168 offset:36864
	ds_read_b128 v[216:219], v168 offset:37888
	ds_read_b128 v[220:223], v168 offset:38912
	ds_read_b128 v[224:227], v168 offset:39936
	global_load_lds_dwordx4 v[230:231], off
	v_lshl_add_u64 v[230:231], s[48:49], 0, v[130:131]
	s_mov_b32 m0, s54
	s_nop 0
	global_load_lds_dwordx4 v[230:231], off
	s_waitcnt vmcnt(8)
	s_waitcnt lgkmcnt(0)
	s_barrier
	s_waitcnt lgkmcnt(0)
	v_mfma_f32_16x16x32_bf16 v[124:127], v[146:149], v[196:199], v[124:127]
	v_mfma_f32_16x16x32_bf16 v[120:123], v[170:173], v[196:199], v[120:123]
	v_mfma_f32_16x16x32_bf16 v[108:111], v[146:149], v[204:207], v[108:111]
	v_mfma_f32_16x16x32_bf16 v[104:107], v[170:173], v[204:207], v[104:107]
	v_mfma_f32_16x16x32_bf16 v[92:95], v[146:149], v[212:215], v[92:95]
	v_mfma_f32_16x16x32_bf16 v[88:91], v[170:173], v[212:215], v[88:91]
	v_mfma_f32_16x16x32_bf16 v[76:79], v[146:149], v[220:223], v[76:79]
	v_mfma_f32_16x16x32_bf16 v[72:75], v[170:173], v[220:223], v[72:75]
	v_mfma_f32_16x16x32_bf16 v[124:127], v[162:165], v[200:203], v[124:127]
	v_mfma_f32_16x16x32_bf16 v[120:123], v[174:177], v[200:203], v[120:123]
	v_mfma_f32_16x16x32_bf16 v[108:111], v[162:165], v[208:211], v[108:111]
	v_mfma_f32_16x16x32_bf16 v[104:107], v[174:177], v[208:211], v[104:107]
	v_mfma_f32_16x16x32_bf16 v[92:95], v[162:165], v[216:219], v[92:95]
	v_mfma_f32_16x16x32_bf16 v[88:91], v[174:177], v[216:219], v[88:91]
	v_mfma_f32_16x16x32_bf16 v[76:79], v[162:165], v[224:227], v[76:79]
	v_mfma_f32_16x16x32_bf16 v[72:75], v[174:177], v[224:227], v[72:75]
	v_mfma_f32_16x16x32_bf16 v[116:119], v[178:181], v[196:199], v[116:119]
	v_mfma_f32_16x16x32_bf16 v[112:115], v[186:189], v[196:199], v[112:115]
	v_mfma_f32_16x16x32_bf16 v[100:103], v[178:181], v[204:207], v[100:103]
	v_mfma_f32_16x16x32_bf16 v[96:99], v[186:189], v[204:207], v[96:99]
	v_mfma_f32_16x16x32_bf16 v[84:87], v[178:181], v[212:215], v[84:87]
	v_mfma_f32_16x16x32_bf16 v[80:83], v[186:189], v[212:215], v[80:83]
	v_mfma_f32_16x16x32_bf16 v[68:71], v[178:181], v[220:223], v[68:71]
	v_mfma_f32_16x16x32_bf16 v[64:67], v[186:189], v[220:223], v[64:67]
	v_mfma_f32_16x16x32_bf16 v[116:119], v[182:185], v[200:203], v[116:119]
	v_mfma_f32_16x16x32_bf16 v[112:115], v[190:193], v[200:203], v[112:115]
	v_mfma_f32_16x16x32_bf16 v[100:103], v[182:185], v[208:211], v[100:103]
	v_mfma_f32_16x16x32_bf16 v[96:99], v[190:193], v[208:211], v[96:99]
	v_mfma_f32_16x16x32_bf16 v[84:87], v[182:185], v[216:219], v[84:87]
	v_mfma_f32_16x16x32_bf16 v[80:83], v[190:193], v[216:219], v[80:83]
	v_mfma_f32_16x16x32_bf16 v[68:71], v[182:185], v[224:227], v[68:71]
	s_setprio 2
	s_barrier
; #define PG8_STAGE_T(bufoff, gbase, voff, AUX) do { _Pragma("unroll") for (int _i = 0; _i < 2; ++_i) \
;         __builtin_amdgcn_global_load_lds((const unsigned*)((const char*)(gbase) + (voff)[_i]), (PG8_LAS unsigned*)(lds + (bufoff) + ldsw + _i * 8192), 16, 0, AUX); } while (0)
; #define PG8_LDA(dst, b, h) do { _Pragma("unroll") for (int m = 0; m < 4; ++m) _Pragma("unroll") for (int k = 0; k < 2; ++k) dst[m][k] = *(const PG8_LAS bf16x8*)(lds + PG8_SA(b, h) + aoff + m * 2048 + k * 1024); } while (0)
; #define PG8_MMA(ai, bj, At, Bt) do { __builtin_amdgcn_s_setprio(1); _Pragma("unroll") for (int m = 0; m < 4; ++m) _Pragma("unroll") for (int n = 0; n < 2; ++n) _Pragma("unroll") for (int k = 0; k < 2; ++k) \
;         acc[ai][bj][m][n] = __builtin_amdgcn_mfma_f32_16x16x32_bf16(Bt[n][k], At[m][k], acc[ai][bj][m][n], 0, 0, 0); __builtin_amdgcn_s_setprio(0); } while (0)
; #define PG8_WAIT_V(n) asm volatile("s_waitcnt vmcnt(" #n ")" ::: "memory")
; #define PG8_WAIT_L(n) asm volatile("s_waitcnt lgkmcnt(" #n ")" ::: "memory")
; #define PG8_BAR __builtin_amdgcn_s_barrier()
; #define PG8_SCHED __builtin_amdgcn_sched_barrier(0)
;     ...
;             if (!pe) { PG8_WAIT_V(8); } PG8_WAIT_L(0); PG8_BAR; PG8_MMA(0, 0, At, B0); PG8_MMA(0, 1, At, B1); PG8_BAR; PG8_SCHED;
;             PG8_LDA(At, 1, 1); PG8_STAGE_T(PG8_SB(1, 0), b3, voffB, AUX_B); PG8_STAGE_T(PG8_SB(1, 1), b3 + hstep, voffB, AUX_B); PG8_STAGE_T(PG8_SA(1, 0), a3, voffA, AUX_A);
;             PG8_WAIT_V(8); PG8_WAIT_L(0); PG8_BAR; PG8_MMA(1, 0, At, B0); PG8_MMA(1, 1, At, B1); PG8_BAR; PG8_SCHED;
	v_mfma_f32_16x16x32_bf16 v[64:67], v[190:193], v[224:227], v[64:67]
	s_setprio 0
	s_add_i32 s48, s71, s9
	v_lshl_add_u64 v[150:151], v[150:151], 0, s[14:15]
	s_mov_b32 m0, s48
	ds_read_b128 v[196:199], v168 offset:49152
	ds_read_b128 v[200:203], v168 offset:50176
	ds_read_b128 v[204:207], v168 offset:51200
	ds_read_b128 v[208:211], v168 offset:52224
	ds_read_b128 v[212:215], v168 offset:53248
	ds_read_b128 v[216:219], v168 offset:54272
	ds_read_b128 v[220:223], v168 offset:55296
	ds_read_b128 v[224:227], v168 offset:56320
	global_load_lds_dwordx4 v[150:151], off
	s_add_i32 m0, s48, 0x2000
	s_add_u32 s44, s44, 0x40080
	v_lshl_add_u64 v[150:151], v[154:155], 0, s[14:15]
	s_addc_u32 s45, s45, 0
	s_add_i32 s48, s76, s9
	global_load_lds_dwordx4 v[150:151], off
	v_lshl_add_u64 v[150:151], s[44:45], 0, v[132:133]
	s_mov_b32 m0, s48
	s_nop 0
	global_load_lds_dwordx4 v[150:151], off
	v_lshl_add_u64 v[150:151], s[44:45], 0, v[128:129]
	s_add_i32 m0, s48, 0x2000
	s_nop 0
	global_load_lds_dwordx4 v[150:151], off
	v_lshl_add_u64 v[150:151], v[158:159], 0, s[14:15]
	s_mov_b32 m0, s56
	s_nop 0
	global_load_lds_dwordx4 v[150:151], off
	v_lshl_add_u64 v[150:151], v[228:229], 0, s[14:15]
	s_mov_b32 m0, s57
	s_nop 0
	global_load_lds_dwordx4 v[150:151], off
	s_waitcnt vmcnt(8)
	s_waitcnt lgkmcnt(0)
	s_barrier
	s_waitcnt lgkmcnt(0)
	v_mfma_f32_16x16x32_bf16 v[60:63], v[146:149], v[196:199], v[60:63]
	v_mfma_f32_16x16x32_bf16 v[56:59], v[170:173], v[196:199], v[56:59]
	v_mfma_f32_16x16x32_bf16 v[44:47], v[146:149], v[204:207], v[44:47]
	v_mfma_f32_16x16x32_bf16 v[40:43], v[170:173], v[204:207], v[40:43]
	v_mfma_f32_16x16x32_bf16 v[28:31], v[146:149], v[212:215], v[28:31]
	v_mfma_f32_16x16x32_bf16 v[24:27], v[170:173], v[212:215], v[24:27]
	v_mfma_f32_16x16x32_bf16 v[12:15], v[146:149], v[220:223], v[12:15]
	v_mfma_f32_16x16x32_bf16 v[8:11], v[170:173], v[220:223], v[8:11]
	v_mfma_f32_16x16x32_bf16 v[60:63], v[162:165], v[200:203], v[60:63]
	v_mfma_f32_16x16x32_bf16 v[56:59], v[174:177], v[200:203], v[56:59]
	v_mfma_f32_16x16x32_bf16 v[44:47], v[162:165], v[208:211], v[44:47]
	v_mfma_f32_16x16x32_bf16 v[40:43], v[174:177], v[208:211], v[40:43]
	v_mfma_f32_16x16x32_bf16 v[28:31], v[162:165], v[216:219], v[28:31]
	v_mfma_f32_16x16x32_bf16 v[24:27], v[174:177], v[216:219], v[24:27]
	v_mfma_f32_16x16x32_bf16 v[12:15], v[162:165], v[224:227], v[12:15]
	v_mfma_f32_16x16x32_bf16 v[8:11], v[174:177], v[224:227], v[8:11]
	v_mfma_f32_16x16x32_bf16 v[52:55], v[178:181], v[196:199], v[52:55]
	v_mfma_f32_16x16x32_bf16 v[48:51], v[186:189], v[196:199], v[48:51]
	v_mfma_f32_16x16x32_bf16 v[36:39], v[178:181], v[204:207], v[36:39]
	v_mfma_f32_16x16x32_bf16 v[32:35], v[186:189], v[204:207], v[32:35]
	v_mfma_f32_16x16x32_bf16 v[20:23], v[178:181], v[212:215], v[20:23]
	v_mfma_f32_16x16x32_bf16 v[16:19], v[186:189], v[212:215], v[16:19]
	v_mfma_f32_16x16x32_bf16 v[4:7], v[178:181], v[220:223], v[4:7]
	v_mfma_f32_16x16x32_bf16 v[0:3], v[186:189], v[220:223], v[0:3]
	v_mfma_f32_16x16x32_bf16 v[52:55], v[182:185], v[200:203], v[52:55]
	v_mfma_f32_16x16x32_bf16 v[48:51], v[190:193], v[200:203], v[48:51]
	v_mfma_f32_16x16x32_bf16 v[36:39], v[182:185], v[208:211], v[36:39]
	v_mfma_f32_16x16x32_bf16 v[32:35], v[190:193], v[208:211], v[32:35]
	v_mfma_f32_16x16x32_bf16 v[20:23], v[182:185], v[216:219], v[20:23]
	v_mfma_f32_16x16x32_bf16 v[16:19], v[190:193], v[216:219], v[16:19]
	v_mfma_f32_16x16x32_bf16 v[4:7], v[182:185], v[224:227], v[4:7]
	s_setprio 2
	s_barrier
	v_mfma_f32_16x16x32_bf16 v[0:3], v[190:193], v[224:227], v[0:3]
	s_setprio 0
	s_add_i32 s70, s70, 2
	s_add_u32 s40, s40, 0x100
	s_addc_u32 s41, s41, 0
	s_add_u32 s68, s68, 0x100
	s_addc_u32 s69, s69, 0
	s_cmp_gt_u32 s70, 13
	s_cbranch_scc0 .LBB0_244
	s_and_b64 vcc, exec, s[18:19]
	s_cbranch_vccz .LBB0_247
	s_barrier

; #define PG8_STAGE_T(bufoff, gbase, voff, AUX) do { _Pragma("unroll") for (int _i = 0; _i < 2; ++_i) \
;         __builtin_amdgcn_global_load_lds((const unsigned*)((const char*)(gbase) + (voff)[_i]), (PG8_LAS unsigned*)(lds + (bufoff) + ldsw + _i * 8192), 16, 0, AUX); } while (0)
; #define PG8_LDA(dst, b, h) do { _Pragma("unroll") for (int m = 0; m < 4; ++m) _Pragma("unroll") for (int k = 0; k < 2; ++k) dst[m][k] = *(const PG8_LAS bf16x8*)(lds + PG8_SA(b, h) + aoff + m * 2048 + k * 1024); } while (0)
; #define PG8_LDB(dst, b, h) do { _Pragma("unroll") for (int n = 0; n < 2; ++n) _Pragma("unroll") for (int k = 0; k < 2; ++k) dst[n][k] = *(const PG8_LAS bf16x8*)(lds + PG8_SB(b, h) + boff + n * 2048 + k * 1024); } while (0)
; #define PG8_MMA(ai, bj, At, Bt) do { __builtin_amdgcn_s_setprio(1); _Pragma("unroll") for (int m = 0; m < 4; ++m) _Pragma("unroll") for (int n = 0; n < 2; ++n) _Pragma("unroll") for (int k = 0; k < 2; ++k) \
;         acc[ai][bj][m][n] = __builtin_amdgcn_mfma_f32_16x16x32_bf16(Bt[n][k], At[m][k], acc[ai][bj][m][n], 0, 0, 0); __builtin_amdgcn_s_setprio(0); } while (0)
; #define PG8_WAIT_V(n) asm volatile("s_waitcnt vmcnt(" #n ")" ::: "memory")
; #define PG8_WAIT_L(n) asm volatile("s_waitcnt lgkmcnt(" #n ")" ::: "memory")
; #define PG8_BAR __builtin_amdgcn_s_barrier()
;     ...
;             const bool last = (t == nt - 2);
;             const char* a1 = cA + (ptrdiff_t)(t + 1) * ck;
;             const char* a2 = last ? nA : cA + (ptrdiff_t)(t + 2) * ck; const char* b2 = last ? nB : cB + (ptrdiff_t)(t + 2) * ck;
;             const ptrdiff_t k3 = last ? nk : ck;
;             const char* a3 = a2 + k3; const char* b3 = b2 + k3;
;             if (last && has_next) S.a_ready(nxt);
;             if constexpr (SP2) {
;             int pei = 0; if constexpr (PEEL) { pei = __builtin_amdgcn_readfirstlane((t == 0 && ui > 0) ? 1 : 0); asm volatile("" : "+s"(pei)); }
;             const bool pe = pei != 0;
;             PG8_LDB(B0, 0, 0); PG8_LDB(B1, 0, 1); PG8_SCHED; PG8_LDA(At, 0, 0); if (!pe) { PG8_STAGE_T(PG8_SA(1, 1), a1 + hstep, voffA, AUX_A); }
;             if (!pe) { PG8_WAIT_V(8); } PG8_WAIT_L(0); PG8_BAR; PG8_MMA(0, 0, At, B0); PG8_MMA(0, 1, At, B1); PG8_BAR; PG8_SCHED;
;             PG8_LDA(At, 0, 1); PG8_STAGE_T(PG8_SB(0, 0), b2, voffB, AUX_B); PG8_STAGE_T(PG8_SB(0, 1), b2 + hstep, voffB, AUX_B); PG8_STAGE_T(PG8_SA(0, 0), a2, voffA, AUX_A);
.LBB0_329:
	ds_read_b128 v[154:157], v149
	ds_read_b128 v[158:161], v149 offset:1024
	ds_read_b128 v[162:165], v149 offset:2048
	ds_read_b128 v[166:169], v149 offset:3072
	ds_read_b128 v[170:173], v150
	ds_read_b128 v[174:177], v150 offset:1024
	ds_read_b128 v[178:181], v150 offset:2048
	ds_read_b128 v[182:185], v150 offset:3072
	s_add_u32 s44, s40, 0xfff50080
	s_addc_u32 s45, s41, -1
	s_cmp_eq_u32 s67, 40
	s_cselect_b32 s49, s5, s45
	s_cselect_b32 s48, s4, s44
	s_cselect_b32 s45, s37, s66
	s_cselect_b32 s44, s36, s63
	v_lshl_add_u64 v[144:145], s[40:41], 0, v[136:137]
	s_add_i32 m0, s9, 0xc000
	ds_read_b128 v[186:189], v151
	ds_read_b128 v[190:193], v151 offset:1024
	ds_read_b128 v[196:199], v151 offset:2048
	ds_read_b128 v[200:203], v151 offset:3072
	ds_read_b128 v[204:207], v151 offset:4096
	ds_read_b128 v[208:211], v151 offset:5120
	ds_read_b128 v[212:215], v151 offset:6144
	ds_read_b128 v[216:219], v151 offset:7168
	global_load_lds_dwordx4 v[144:145], off
	v_lshl_add_u64 v[144:145], s[40:41], 0, v[138:139]
	s_add_i32 m0, s9, 0xe000
	s_nop 0
	global_load_lds_dwordx4 v[144:145], off
	s_waitcnt vmcnt(8)
	s_waitcnt lgkmcnt(0)
	s_barrier
	s_waitcnt lgkmcnt(0)
	v_mfma_f32_16x16x32_bf16 v[124:127], v[154:157], v[186:189], v[124:127]
	v_mfma_f32_16x16x32_bf16 v[120:123], v[162:165], v[186:189], v[120:123]
	v_mfma_f32_16x16x32_bf16 v[108:111], v[154:157], v[196:199], v[108:111]
	v_mfma_f32_16x16x32_bf16 v[104:107], v[162:165], v[196:199], v[104:107]
	v_mfma_f32_16x16x32_bf16 v[92:95], v[154:157], v[204:207], v[92:95]
	v_mfma_f32_16x16x32_bf16 v[88:91], v[162:165], v[204:207], v[88:91]
	v_mfma_f32_16x16x32_bf16 v[76:79], v[154:157], v[212:215], v[76:79]
	v_mfma_f32_16x16x32_bf16 v[72:75], v[162:165], v[212:215], v[72:75]
	v_mfma_f32_16x16x32_bf16 v[124:127], v[158:161], v[190:193], v[124:127]
	v_mfma_f32_16x16x32_bf16 v[120:123], v[166:169], v[190:193], v[120:123]
	v_mfma_f32_16x16x32_bf16 v[108:111], v[158:161], v[200:203], v[108:111]
	v_mfma_f32_16x16x32_bf16 v[104:107], v[166:169], v[200:203], v[104:107]
	v_mfma_f32_16x16x32_bf16 v[92:95], v[158:161], v[208:211], v[92:95]
	v_mfma_f32_16x16x32_bf16 v[88:91], v[166:169], v[208:211], v[88:91]
	v_mfma_f32_16x16x32_bf16 v[76:79], v[158:161], v[216:219], v[76:79]
	v_mfma_f32_16x16x32_bf16 v[72:75], v[166:169], v[216:219], v[72:75]
	v_mfma_f32_16x16x32_bf16 v[116:119], v[170:173], v[186:189], v[116:119]
	v_mfma_f32_16x16x32_bf16 v[112:115], v[178:181], v[186:189], v[112:115]
	v_mfma_f32_16x16x32_bf16 v[100:103], v[170:173], v[196:199], v[100:103]
	v_mfma_f32_16x16x32_bf16 v[96:99], v[178:181], v[196:199], v[96:99]
	v_mfma_f32_16x16x32_bf16 v[84:87], v[170:173], v[204:207], v[84:87]
	v_mfma_f32_16x16x32_bf16 v[80:83], v[178:181], v[204:207], v[80:83]
	v_mfma_f32_16x16x32_bf16 v[68:71], v[170:173], v[212:215], v[68:71]
	v_mfma_f32_16x16x32_bf16 v[64:67], v[178:181], v[212:215], v[64:67]
	v_mfma_f32_16x16x32_bf16 v[116:119], v[174:177], v[190:193], v[116:119]
	v_mfma_f32_16x16x32_bf16 v[112:115], v[182:185], v[190:193], v[112:115]
	v_mfma_f32_16x16x32_bf16 v[100:103], v[174:177], v[200:203], v[100:103]
	v_mfma_f32_16x16x32_bf16 v[96:99], v[182:185], v[200:203], v[96:99]
	v_mfma_f32_16x16x32_bf16 v[84:87], v[174:177], v[208:211], v[84:87]
	v_mfma_f32_16x16x32_bf16 v[80:83], v[182:185], v[208:211], v[80:83]
	v_mfma_f32_16x16x32_bf16 v[68:71], v[174:177], v[216:219], v[68:71]
	s_setprio 2
	s_barrier
	v_mfma_f32_16x16x32_bf16 v[64:67], v[182:185], v[216:219], v[64:67]
	s_setprio 0
	s_add_i32 s68, s56, s8
	v_lshl_add_u64 v[144:145], s[44:45], 0, v[130:131]
	s_mov_b32 m0, s68
	ds_read_b128 v[186:189], v151 offset:16384
	ds_read_b128 v[190:193], v151 offset:17408
	ds_read_b128 v[196:199], v151 offset:18432
	ds_read_b128 v[200:203], v151 offset:19456
	ds_read_b128 v[204:207], v151 offset:20480
	ds_read_b128 v[208:211], v151 offset:21504
	ds_read_b128 v[212:215], v151 offset:22528
	ds_read_b128 v[216:219], v151 offset:23552
	global_load_lds_dwordx4 v[144:145], off
	s_add_i32 m0, s68, 0x2000
	s_add_u32 s68, s44, 0xb0000
	v_lshl_add_u64 v[220:221], s[44:45], 0, v[134:135]
	s_addc_u32 s69, s45, 0
	s_add_i32 s70, s57, s8
	global_load_lds_dwordx4 v[220:221], off
	v_lshl_add_u64 v[222:223], s[68:69], 0, v[130:131]
	s_mov_b32 m0, s70
	v_lshl_add_u64 v[224:225], s[48:49], 0, v[132:133]
	global_load_lds_dwordx4 v[222:223], off
	v_lshl_add_u64 v[222:223], s[68:69], 0, v[134:135]
	s_add_i32 m0, s70, 0x2000
	s_nop 0
	global_load_lds_dwordx4 v[222:223], off
	v_lshl_add_u64 v[222:223], s[48:49], 0, v[128:129]
	s_mov_b32 m0, s9
	s_nop 0
	global_load_lds_dwordx4 v[222:223], off
	s_mov_b32 m0, s50
	s_nop 0
	global_load_lds_dwordx4 v[224:225], off
	s_waitcnt vmcnt(8)
	s_waitcnt lgkmcnt(0)
	s_barrier
; #define PG8_STAGE_T(bufoff, gbase, voff, AUX) do { _Pragma("unroll") for (int _i = 0; _i < 2; ++_i) \
;         __builtin_amdgcn_global_load_lds((const unsigned*)((const char*)(gbase) + (voff)[_i]), (PG8_LAS unsigned*)(lds + (bufoff) + ldsw + _i * 8192), 16, 0, AUX); } while (0)
; #define PG8_LDA(dst, b, h) do { _Pragma("unroll") for (int m = 0; m < 4; ++m) _Pragma("unroll") for (int k = 0; k < 2; ++k) dst[m][k] = *(const PG8_LAS bf16x8*)(lds + PG8_SA(b, h) + aoff + m * 2048 + k * 1024); } while (0)
; #define PG8_LDB(dst, b, h) do { _Pragma("unroll") for (int n = 0; n < 2; ++n) _Pragma("unroll") for (int k = 0; k < 2; ++k) dst[n][k] = *(const PG8_LAS bf16x8*)(lds + PG8_SB(b, h) + boff + n * 2048 + k * 1024); } while (0)
; #define PG8_MMA(ai, bj, At, Bt) do { __builtin_amdgcn_s_setprio(1); _Pragma("unroll") for (int m = 0; m < 4; ++m) _Pragma("unroll") for (int n = 0; n < 2; ++n) _Pragma("unroll") for (int k = 0; k < 2; ++k) \
;         acc[ai][bj][m][n] = __builtin_amdgcn_mfma_f32_16x16x32_bf16(Bt[n][k], At[m][k], acc[ai][bj][m][n], 0, 0, 0); __builtin_amdgcn_s_setprio(0); } while (0)
; #define PG8_WAIT_V(n) asm volatile("s_waitcnt vmcnt(" #n ")" ::: "memory")
; #define PG8_WAIT_L(n) asm volatile("s_waitcnt lgkmcnt(" #n ")" ::: "memory")
; #define PG8_BAR __builtin_amdgcn_s_barrier()
; #define PG8_SCHED __builtin_amdgcn_sched_barrier(0)
;     ...
;             if (!pe) { PG8_WAIT_V(8); } PG8_WAIT_L(0); PG8_BAR; PG8_MMA(1, 0, At, B0); PG8_MMA(1, 1, At, B1); PG8_BAR; PG8_SCHED;
;             PG8_LDB(B0, 1, 0); PG8_LDB(B1, 1, 1); PG8_SCHED; PG8_LDA(At, 1, 0); PG8_STAGE_T(PG8_SA(0, 1), a2 + hstep, voffA, AUX_A);
;             if (!pe) { PG8_WAIT_V(8); } PG8_WAIT_L(0); PG8_BAR; PG8_MMA(0, 0, At, B0); PG8_MMA(0, 1, At, B1); PG8_BAR; PG8_SCHED;
	s_waitcnt lgkmcnt(0)
	v_mfma_f32_16x16x32_bf16 v[60:63], v[154:157], v[186:189], v[60:63]
	v_mfma_f32_16x16x32_bf16 v[56:59], v[162:165], v[186:189], v[56:59]
	v_mfma_f32_16x16x32_bf16 v[44:47], v[154:157], v[196:199], v[44:47]
	v_mfma_f32_16x16x32_bf16 v[40:43], v[162:165], v[196:199], v[40:43]
	v_mfma_f32_16x16x32_bf16 v[28:31], v[154:157], v[204:207], v[28:31]
	v_mfma_f32_16x16x32_bf16 v[24:27], v[162:165], v[204:207], v[24:27]
	v_mfma_f32_16x16x32_bf16 v[12:15], v[154:157], v[212:215], v[12:15]
	v_mfma_f32_16x16x32_bf16 v[8:11], v[162:165], v[212:215], v[8:11]
	v_mfma_f32_16x16x32_bf16 v[60:63], v[158:161], v[190:193], v[60:63]
	v_mfma_f32_16x16x32_bf16 v[56:59], v[166:169], v[190:193], v[56:59]
	v_mfma_f32_16x16x32_bf16 v[44:47], v[158:161], v[200:203], v[44:47]
	v_mfma_f32_16x16x32_bf16 v[40:43], v[166:169], v[200:203], v[40:43]
	v_mfma_f32_16x16x32_bf16 v[28:31], v[158:161], v[208:211], v[28:31]
	v_mfma_f32_16x16x32_bf16 v[24:27], v[166:169], v[208:211], v[24:27]
	v_mfma_f32_16x16x32_bf16 v[12:15], v[158:161], v[216:219], v[12:15]
	v_mfma_f32_16x16x32_bf16 v[8:11], v[166:169], v[216:219], v[8:11]
	v_mfma_f32_16x16x32_bf16 v[52:55], v[170:173], v[186:189], v[52:55]
	v_mfma_f32_16x16x32_bf16 v[48:51], v[178:181], v[186:189], v[48:51]
	v_mfma_f32_16x16x32_bf16 v[36:39], v[170:173], v[196:199], v[36:39]
	v_mfma_f32_16x16x32_bf16 v[32:35], v[178:181], v[196:199], v[32:35]
	v_mfma_f32_16x16x32_bf16 v[20:23], v[170:173], v[204:207], v[20:23]
	v_mfma_f32_16x16x32_bf16 v[16:19], v[178:181], v[204:207], v[16:19]
	v_mfma_f32_16x16x32_bf16 v[4:7], v[170:173], v[212:215], v[4:7]
	v_mfma_f32_16x16x32_bf16 v[0:3], v[178:181], v[212:215], v[0:3]
	v_mfma_f32_16x16x32_bf16 v[52:55], v[174:177], v[190:193], v[52:55]
	v_mfma_f32_16x16x32_bf16 v[48:51], v[182:185], v[190:193], v[48:51]
	v_mfma_f32_16x16x32_bf16 v[36:39], v[174:177], v[200:203], v[36:39]
	v_mfma_f32_16x16x32_bf16 v[32:35], v[182:185], v[200:203], v[32:35]
	v_mfma_f32_16x16x32_bf16 v[20:23], v[174:177], v[208:211], v[20:23]
	v_mfma_f32_16x16x32_bf16 v[16:19], v[182:185], v[208:211], v[16:19]
	v_mfma_f32_16x16x32_bf16 v[4:7], v[174:177], v[216:219], v[4:7]
	s_setprio 2
	s_barrier
	v_mfma_f32_16x16x32_bf16 v[0:3], v[182:185], v[216:219], v[0:3]
	s_setprio 0
	s_add_i32 s68, 0, 0x18000
	v_add_u32_e32 v153, s68, v147
	s_add_i32 s69, 0, 0x1c000
	ds_read_b128 v[154:157], v153
	ds_read_b128 v[158:161], v153 offset:1024
	ds_read_b128 v[162:165], v153 offset:2048
	ds_read_b128 v[166:169], v153 offset:3072
	v_add_u32_e32 v153, s69, v147
	ds_read_b128 v[170:173], v153
	ds_read_b128 v[174:177], v153 offset:1024
	ds_read_b128 v[178:181], v153 offset:2048
	ds_read_b128 v[182:185], v153 offset:3072
	s_add_u32 s48, s48, 0xb0000
	s_addc_u32 s49, s49, 0
	s_mov_b32 m0, s51
	v_lshl_add_u64 v[226:227], s[48:49], 0, v[128:129]
	ds_read_b128 v[186:189], v151 offset:32768
	ds_read_b128 v[190:193], v151 offset:33792
	ds_read_b128 v[196:199], v151 offset:34816
	ds_read_b128 v[200:203], v151 offset:35840
	ds_read_b128 v[204:207], v151 offset:36864
	ds_read_b128 v[208:211], v151 offset:37888
	ds_read_b128 v[212:215], v151 offset:38912
	ds_read_b128 v[216:219], v151 offset:39936
	global_load_lds_dwordx4 v[226:227], off
	v_lshl_add_u64 v[226:227], s[48:49], 0, v[132:133]
	s_mov_b32 m0, s52
	s_nop 0
	global_load_lds_dwordx4 v[226:227], off
	s_waitcnt vmcnt(8)
	s_waitcnt lgkmcnt(0)
	s_barrier
	s_waitcnt lgkmcnt(0)
	v_mfma_f32_16x16x32_bf16 v[124:127], v[154:157], v[186:189], v[124:127]
	v_mfma_f32_16x16x32_bf16 v[120:123], v[162:165], v[186:189], v[120:123]
	v_mfma_f32_16x16x32_bf16 v[108:111], v[154:157], v[196:199], v[108:111]
	v_mfma_f32_16x16x32_bf16 v[104:107], v[162:165], v[196:199], v[104:107]
	v_mfma_f32_16x16x32_bf16 v[92:95], v[154:157], v[204:207], v[92:95]
	v_mfma_f32_16x16x32_bf16 v[88:91], v[162:165], v[204:207], v[88:91]
	v_mfma_f32_16x16x32_bf16 v[76:79], v[154:157], v[212:215], v[76:79]
	v_mfma_f32_16x16x32_bf16 v[72:75], v[162:165], v[212:215], v[72:75]
	v_mfma_f32_16x16x32_bf16 v[124:127], v[158:161], v[190:193], v[124:127]
	v_mfma_f32_16x16x32_bf16 v[120:123], v[166:169], v[190:193], v[120:123]
	v_mfma_f32_16x16x32_bf16 v[108:111], v[158:161], v[200:203], v[108:111]
	v_mfma_f32_16x16x32_bf16 v[104:107], v[166:169], v[200:203], v[104:107]
	v_mfma_f32_16x16x32_bf16 v[92:95], v[158:161], v[208:211], v[92:95]
	v_mfma_f32_16x16x32_bf16 v[88:91], v[166:169], v[208:211], v[88:91]
	v_mfma_f32_16x16x32_bf16 v[76:79], v[158:161], v[216:219], v[76:79]
	v_mfma_f32_16x16x32_bf16 v[72:75], v[166:169], v[216:219], v[72:75]
	v_mfma_f32_16x16x32_bf16 v[116:119], v[170:173], v[186:189], v[116:119]
	v_mfma_f32_16x16x32_bf16 v[112:115], v[178:181], v[186:189], v[112:115]
	v_mfma_f32_16x16x32_bf16 v[100:103], v[170:173], v[196:199], v[100:103]
	v_mfma_f32_16x16x32_bf16 v[96:99], v[178:181], v[196:199], v[96:99]
	v_mfma_f32_16x16x32_bf16 v[84:87], v[170:173], v[204:207], v[84:87]
	v_mfma_f32_16x16x32_bf16 v[80:83], v[178:181], v[204:207], v[80:83]
	v_mfma_f32_16x16x32_bf16 v[68:71], v[170:173], v[212:215], v[68:71]
	v_mfma_f32_16x16x32_bf16 v[64:67], v[178:181], v[212:215], v[64:67]
	v_mfma_f32_16x16x32_bf16 v[116:119], v[174:177], v[190:193], v[116:119]
	v_mfma_f32_16x16x32_bf16 v[112:115], v[182:185], v[190:193], v[112:115]
	v_mfma_f32_16x16x32_bf16 v[100:103], v[174:177], v[200:203], v[100:103]
	v_mfma_f32_16x16x32_bf16 v[96:99], v[182:185], v[200:203], v[96:99]
	v_mfma_f32_16x16x32_bf16 v[84:87], v[174:177], v[208:211], v[84:87]
	v_mfma_f32_16x16x32_bf16 v[80:83], v[182:185], v[208:211], v[80:83]
	v_mfma_f32_16x16x32_bf16 v[68:71], v[174:177], v[216:219], v[68:71]
	s_setprio 2
	s_barrier
; #define PG8_STAGE_T(bufoff, gbase, voff, AUX) do { _Pragma("unroll") for (int _i = 0; _i < 2; ++_i) \
;         __builtin_amdgcn_global_load_lds((const unsigned*)((const char*)(gbase) + (voff)[_i]), (PG8_LAS unsigned*)(lds + (bufoff) + ldsw + _i * 8192), 16, 0, AUX); } while (0)
; #define PG8_LDA(dst, b, h) do { _Pragma("unroll") for (int m = 0; m < 4; ++m) _Pragma("unroll") for (int k = 0; k < 2; ++k) dst[m][k] = *(const PG8_LAS bf16x8*)(lds + PG8_SA(b, h) + aoff + m * 2048 + k * 1024); } while (0)
; #define PG8_MMA(ai, bj, At, Bt) do { __builtin_amdgcn_s_setprio(1); _Pragma("unroll") for (int m = 0; m < 4; ++m) _Pragma("unroll") for (int n = 0; n < 2; ++n) _Pragma("unroll") for (int k = 0; k < 2; ++k) \
;         acc[ai][bj][m][n] = __builtin_amdgcn_mfma_f32_16x16x32_bf16(Bt[n][k], At[m][k], acc[ai][bj][m][n], 0, 0, 0); __builtin_amdgcn_s_setprio(0); } while (0)
; #define PG8_WAIT_V(n) asm volatile("s_waitcnt vmcnt(" #n ")" ::: "memory")
; #define PG8_WAIT_L(n) asm volatile("s_waitcnt lgkmcnt(" #n ")" ::: "memory")
; #define PG8_BAR __builtin_amdgcn_s_barrier()
; #define PG8_SCHED __builtin_amdgcn_sched_barrier(0)
;     ...
;         for (int t = 0; t < nt; t += 2) {
;     ...
;             if (!pe) { PG8_WAIT_V(8); } PG8_WAIT_L(0); PG8_BAR; PG8_MMA(0, 0, At, B0); PG8_MMA(0, 1, At, B1); PG8_BAR; PG8_SCHED;
;             PG8_LDA(At, 1, 1); PG8_STAGE_T(PG8_SB(1, 0), b3, voffB, AUX_B); PG8_STAGE_T(PG8_SB(1, 1), b3 + hstep, voffB, AUX_B); PG8_STAGE_T(PG8_SA(1, 0), a3, voffA, AUX_A);
;             PG8_WAIT_V(8); PG8_WAIT_L(0); PG8_BAR; PG8_MMA(1, 0, At, B0); PG8_MMA(1, 1, At, B1); PG8_BAR; PG8_SCHED;
	v_mfma_f32_16x16x32_bf16 v[64:67], v[182:185], v[216:219], v[64:67]
	s_setprio 0
	s_add_i32 s48, s68, s8
	v_lshl_add_u64 v[144:145], v[144:145], 0, s[24:25]
	s_mov_b32 m0, s48
	ds_read_b128 v[186:189], v151 offset:49152
	ds_read_b128 v[190:193], v151 offset:50176
	ds_read_b128 v[196:199], v151 offset:51200
	ds_read_b128 v[200:203], v151 offset:52224
	ds_read_b128 v[204:207], v151 offset:53248
	ds_read_b128 v[208:211], v151 offset:54272
	ds_read_b128 v[212:215], v151 offset:55296
	ds_read_b128 v[216:219], v151 offset:56320
	global_load_lds_dwordx4 v[144:145], off
	s_add_i32 m0, s48, 0x2000
	s_add_u32 s44, s44, 0xb0080
	v_lshl_add_u64 v[144:145], v[220:221], 0, s[24:25]
	s_addc_u32 s45, s45, 0
	s_add_i32 s48, s69, s8
	global_load_lds_dwordx4 v[144:145], off
	v_lshl_add_u64 v[144:145], s[44:45], 0, v[130:131]
	s_mov_b32 m0, s48
	s_nop 0
	global_load_lds_dwordx4 v[144:145], off
	v_lshl_add_u64 v[144:145], s[44:45], 0, v[134:135]
	s_add_i32 m0, s48, 0x2000
	s_nop 0
	global_load_lds_dwordx4 v[144:145], off
	v_lshl_add_u64 v[144:145], v[222:223], 0, s[24:25]
	s_mov_b32 m0, s53
	s_nop 0
	global_load_lds_dwordx4 v[144:145], off
	v_lshl_add_u64 v[144:145], v[224:225], 0, s[24:25]
	s_mov_b32 m0, s54
	s_nop 0
	global_load_lds_dwordx4 v[144:145], off
	s_waitcnt vmcnt(8)
	s_waitcnt lgkmcnt(0)
	s_barrier
	s_waitcnt lgkmcnt(0)
	v_mfma_f32_16x16x32_bf16 v[60:63], v[154:157], v[186:189], v[60:63]
	v_mfma_f32_16x16x32_bf16 v[56:59], v[162:165], v[186:189], v[56:59]
	v_mfma_f32_16x16x32_bf16 v[44:47], v[154:157], v[196:199], v[44:47]
	v_mfma_f32_16x16x32_bf16 v[40:43], v[162:165], v[196:199], v[40:43]
	v_mfma_f32_16x16x32_bf16 v[28:31], v[154:157], v[204:207], v[28:31]
	v_mfma_f32_16x16x32_bf16 v[24:27], v[162:165], v[204:207], v[24:27]
	v_mfma_f32_16x16x32_bf16 v[12:15], v[154:157], v[212:215], v[12:15]
	v_mfma_f32_16x16x32_bf16 v[8:11], v[162:165], v[212:215], v[8:11]
	v_mfma_f32_16x16x32_bf16 v[60:63], v[158:161], v[190:193], v[60:63]
	v_mfma_f32_16x16x32_bf16 v[56:59], v[166:169], v[190:193], v[56:59]
	v_mfma_f32_16x16x32_bf16 v[44:47], v[158:161], v[200:203], v[44:47]
	v_mfma_f32_16x16x32_bf16 v[40:43], v[166:169], v[200:203], v[40:43]
	v_mfma_f32_16x16x32_bf16 v[28:31], v[158:161], v[208:211], v[28:31]
	v_mfma_f32_16x16x32_bf16 v[24:27], v[166:169], v[208:211], v[24:27]
	v_mfma_f32_16x16x32_bf16 v[12:15], v[158:161], v[216:219], v[12:15]
	v_mfma_f32_16x16x32_bf16 v[8:11], v[166:169], v[216:219], v[8:11]
	v_mfma_f32_16x16x32_bf16 v[52:55], v[170:173], v[186:189], v[52:55]
	v_mfma_f32_16x16x32_bf16 v[48:51], v[178:181], v[186:189], v[48:51]
	v_mfma_f32_16x16x32_bf16 v[36:39], v[170:173], v[196:199], v[36:39]
	v_mfma_f32_16x16x32_bf16 v[32:35], v[178:181], v[196:199], v[32:35]
	v_mfma_f32_16x16x32_bf16 v[20:23], v[170:173], v[204:207], v[20:23]
	v_mfma_f32_16x16x32_bf16 v[16:19], v[178:181], v[204:207], v[16:19]
	v_mfma_f32_16x16x32_bf16 v[4:7], v[170:173], v[212:215], v[4:7]
	v_mfma_f32_16x16x32_bf16 v[0:3], v[178:181], v[212:215], v[0:3]
	v_mfma_f32_16x16x32_bf16 v[52:55], v[174:177], v[190:193], v[52:55]
	v_mfma_f32_16x16x32_bf16 v[48:51], v[182:185], v[190:193], v[48:51]
	v_mfma_f32_16x16x32_bf16 v[36:39], v[174:177], v[200:203], v[36:39]
	v_mfma_f32_16x16x32_bf16 v[32:35], v[182:185], v[200:203], v[32:35]
	v_mfma_f32_16x16x32_bf16 v[20:23], v[174:177], v[208:211], v[20:23]
	v_mfma_f32_16x16x32_bf16 v[16:19], v[182:185], v[208:211], v[16:19]
	v_mfma_f32_16x16x32_bf16 v[4:7], v[174:177], v[216:219], v[4:7]
	s_setprio 2
	s_barrier
	v_mfma_f32_16x16x32_bf16 v[0:3], v[182:185], v[216:219], v[0:3]
	s_setprio 0
	s_add_i32 s67, s67, 2
	s_add_u32 s40, s40, 0x100
	s_addc_u32 s41, s41, 0
	s_add_u32 s63, s63, 0x100
	s_addc_u32 s66, s66, 0
	s_cmp_gt_u32 s67, 41
	s_cbranch_scc0 .LBB0_329
	s_and_b64 vcc, exec, s[26:27]
	s_cbranch_vccz .LBB0_332
	s_barrier

; #define PG8_STAGE_T(bufoff, gbase, voff, AUX) do { _Pragma("unroll") for (int _i = 0; _i < 2; ++_i) \
;         __builtin_amdgcn_global_load_lds((const unsigned*)((const char*)(gbase) + (voff)[_i]), (PG8_LAS unsigned*)(lds + (bufoff) + ldsw + _i * 8192), 16, 0, AUX); } while (0)
; #define PG8_LDA(dst, b, h) do { _Pragma("unroll") for (int m = 0; m < 4; ++m) _Pragma("unroll") for (int k = 0; k < 2; ++k) dst[m][k] = *(const PG8_LAS bf16x8*)(lds + PG8_SA(b, h) + aoff + m * 2048 + k * 1024); } while (0)
; #define PG8_LDB(dst, b, h) do { _Pragma("unroll") for (int n = 0; n < 2; ++n) _Pragma("unroll") for (int k = 0; k < 2; ++k) dst[n][k] = *(const PG8_LAS bf16x8*)(lds + PG8_SB(b, h) + boff + n * 2048 + k * 1024); } while (0)
; #define PG8_MMA(ai, bj, At, Bt) do { __builtin_amdgcn_s_setprio(1); _Pragma("unroll") for (int m = 0; m < 4; ++m) _Pragma("unroll") for (int n = 0; n < 2; ++n) _Pragma("unroll") for (int k = 0; k < 2; ++k) \
;         acc[ai][bj][m][n] = __builtin_amdgcn_mfma_f32_16x16x32_bf16(Bt[n][k], At[m][k], acc[ai][bj][m][n], 0, 0, 0); __builtin_amdgcn_s_setprio(0); } while (0)
; #define PG8_WAIT_V(n) asm volatile("s_waitcnt vmcnt(" #n ")" ::: "memory")
; #define PG8_WAIT_L(n) asm volatile("s_waitcnt lgkmcnt(" #n ")" ::: "memory")
; #define PG8_BAR __builtin_amdgcn_s_barrier()
;     ...
;             const bool last = (t == nt - 2);
;             const char* a1 = cA + (ptrdiff_t)(t + 1) * ck;
;             const char* a2 = last ? nA : cA + (ptrdiff_t)(t + 2) * ck; const char* b2 = last ? nB : cB + (ptrdiff_t)(t + 2) * ck;
;             const ptrdiff_t k3 = last ? nk : ck;
;             const char* a3 = a2 + k3; const char* b3 = b2 + k3;
;             if (last && has_next) S.a_ready(nxt);
;             if constexpr (SP2) {
;             int pei = 0; if constexpr (PEEL) { pei = __builtin_amdgcn_readfirstlane((t == 0 && ui > 0) ? 1 : 0); asm volatile("" : "+s"(pei)); }
;             const bool pe = pei != 0;
;             PG8_LDB(B0, 0, 0); PG8_LDB(B1, 0, 1); PG8_SCHED; PG8_LDA(At, 0, 0); if (!pe) { PG8_STAGE_T(PG8_SA(1, 1), a1 + hstep, voffA, AUX_A); }
;             if (!pe) { PG8_WAIT_V(8); } PG8_WAIT_L(0); PG8_BAR; PG8_MMA(0, 0, At, B0); PG8_MMA(0, 1, At, B1); PG8_BAR; PG8_SCHED;
;             PG8_LDA(At, 0, 1); PG8_STAGE_T(PG8_SB(0, 0), b2, voffB, AUX_B); PG8_STAGE_T(PG8_SB(0, 1), b2 + hstep, voffB, AUX_B); PG8_STAGE_T(PG8_SA(0, 0), a2, voffA, AUX_A);
.LBB0_516:
	ds_read_b128 v[146:149], v178
	ds_read_b128 v[150:153], v178 offset:1024
	ds_read_b128 v[154:157], v178 offset:2048
	ds_read_b128 v[158:161], v178 offset:3072
	ds_read_b128 v[162:165], v179
	ds_read_b128 v[166:169], v179 offset:1024
	ds_read_b128 v[170:173], v179 offset:2048
	ds_read_b128 v[182:185], v179 offset:3072
	s_add_u32 s50, s48, 0xfffc0080
	s_addc_u32 s51, s49, -1
	s_cmp_eq_u32 s68, 12
	s_cselect_b32 s53, s5, s51
	s_cselect_b32 s52, s7, s50
	s_cselect_b32 s51, s27, s67
	s_cselect_b32 s50, s37, s66
	v_lshl_add_u64 v[220:221], s[48:49], 0, v[138:139]
	s_add_i32 m0, s9, 0xc000
	ds_read_b128 v[186:189], v180
	ds_read_b128 v[190:193], v180 offset:1024
	ds_read_b128 v[196:199], v180 offset:2048
	ds_read_b128 v[200:203], v180 offset:3072
	ds_read_b128 v[204:207], v180 offset:4096
	ds_read_b128 v[208:211], v180 offset:5120
	ds_read_b128 v[212:215], v180 offset:6144
	ds_read_b128 v[216:219], v180 offset:7168
	global_load_lds_dwordx4 v[220:221], off
	v_lshl_add_u64 v[220:221], s[48:49], 0, v[140:141]
	s_add_i32 m0, s9, 0xe000
	s_nop 0
	global_load_lds_dwordx4 v[220:221], off
	s_waitcnt vmcnt(8)
	s_waitcnt lgkmcnt(0)
	s_barrier
	s_waitcnt lgkmcnt(0)
	v_mfma_f32_16x16x32_bf16 v[124:127], v[146:149], v[186:189], v[124:127]
	v_mfma_f32_16x16x32_bf16 v[120:123], v[154:157], v[186:189], v[120:123]
	v_mfma_f32_16x16x32_bf16 v[108:111], v[146:149], v[196:199], v[108:111]
	v_mfma_f32_16x16x32_bf16 v[104:107], v[154:157], v[196:199], v[104:107]
	v_mfma_f32_16x16x32_bf16 v[92:95], v[146:149], v[204:207], v[92:95]
	v_mfma_f32_16x16x32_bf16 v[88:91], v[154:157], v[204:207], v[88:91]
	v_mfma_f32_16x16x32_bf16 v[76:79], v[146:149], v[212:215], v[76:79]
	v_mfma_f32_16x16x32_bf16 v[72:75], v[154:157], v[212:215], v[72:75]
	v_mfma_f32_16x16x32_bf16 v[124:127], v[150:153], v[190:193], v[124:127]
	v_mfma_f32_16x16x32_bf16 v[120:123], v[158:161], v[190:193], v[120:123]
	v_mfma_f32_16x16x32_bf16 v[108:111], v[150:153], v[200:203], v[108:111]
	v_mfma_f32_16x16x32_bf16 v[104:107], v[158:161], v[200:203], v[104:107]
	v_mfma_f32_16x16x32_bf16 v[92:95], v[150:153], v[208:211], v[92:95]
	v_mfma_f32_16x16x32_bf16 v[88:91], v[158:161], v[208:211], v[88:91]
	v_mfma_f32_16x16x32_bf16 v[76:79], v[150:153], v[216:219], v[76:79]
	v_mfma_f32_16x16x32_bf16 v[72:75], v[158:161], v[216:219], v[72:75]
	v_mfma_f32_16x16x32_bf16 v[116:119], v[162:165], v[186:189], v[116:119]
	v_mfma_f32_16x16x32_bf16 v[112:115], v[170:173], v[186:189], v[112:115]
	v_mfma_f32_16x16x32_bf16 v[100:103], v[162:165], v[196:199], v[100:103]
	v_mfma_f32_16x16x32_bf16 v[96:99], v[170:173], v[196:199], v[96:99]
	v_mfma_f32_16x16x32_bf16 v[84:87], v[162:165], v[204:207], v[84:87]
	v_mfma_f32_16x16x32_bf16 v[80:83], v[170:173], v[204:207], v[80:83]
	v_mfma_f32_16x16x32_bf16 v[68:71], v[162:165], v[212:215], v[68:71]
	v_mfma_f32_16x16x32_bf16 v[64:67], v[170:173], v[212:215], v[64:67]
	v_mfma_f32_16x16x32_bf16 v[116:119], v[166:169], v[190:193], v[116:119]
	v_mfma_f32_16x16x32_bf16 v[112:115], v[182:185], v[190:193], v[112:115]
	v_mfma_f32_16x16x32_bf16 v[100:103], v[166:169], v[200:203], v[100:103]
	v_mfma_f32_16x16x32_bf16 v[96:99], v[182:185], v[200:203], v[96:99]
	v_mfma_f32_16x16x32_bf16 v[84:87], v[166:169], v[208:211], v[84:87]
	v_mfma_f32_16x16x32_bf16 v[80:83], v[182:185], v[208:211], v[80:83]
	v_mfma_f32_16x16x32_bf16 v[68:71], v[166:169], v[216:219], v[68:71]
	s_setprio 2
	s_barrier
	v_mfma_f32_16x16x32_bf16 v[64:67], v[182:185], v[216:219], v[64:67]
	s_setprio 0
	s_add_i32 s69, s61, s8
	v_lshl_add_u64 v[220:221], s[50:51], 0, v[130:131]
	s_mov_b32 m0, s69
	ds_read_b128 v[186:189], v180 offset:16384
	ds_read_b128 v[190:193], v180 offset:17408
	ds_read_b128 v[196:199], v180 offset:18432
	ds_read_b128 v[200:203], v180 offset:19456
	ds_read_b128 v[204:207], v180 offset:20480
	ds_read_b128 v[208:211], v180 offset:21504
	ds_read_b128 v[212:215], v180 offset:22528
	ds_read_b128 v[216:219], v180 offset:23552
	global_load_lds_dwordx4 v[220:221], off
	s_add_i32 m0, s69, 0x2000
	s_add_u32 s70, s50, 0x40000
	v_lshl_add_u64 v[222:223], s[50:51], 0, v[134:135]
	s_addc_u32 s71, s51, 0
	s_add_i32 s69, s62, s8
	global_load_lds_dwordx4 v[222:223], off
	v_lshl_add_u64 v[224:225], s[70:71], 0, v[130:131]
	s_mov_b32 m0, s69
	v_lshl_add_u64 v[226:227], s[52:53], 0, v[132:133]
	global_load_lds_dwordx4 v[224:225], off
	v_lshl_add_u64 v[224:225], s[70:71], 0, v[134:135]
	s_add_i32 m0, s69, 0x2000
	s_nop 0
	global_load_lds_dwordx4 v[224:225], off
	v_lshl_add_u64 v[224:225], s[52:53], 0, v[128:129]
	s_mov_b32 m0, s9
	s_nop 0
	global_load_lds_dwordx4 v[224:225], off
	s_mov_b32 m0, s55
	s_nop 0
	global_load_lds_dwordx4 v[226:227], off
	s_waitcnt vmcnt(8)
	s_waitcnt lgkmcnt(0)
	s_barrier
; #define PG8_STAGE_T(bufoff, gbase, voff, AUX) do { _Pragma("unroll") for (int _i = 0; _i < 2; ++_i) \
;         __builtin_amdgcn_global_load_lds((const unsigned*)((const char*)(gbase) + (voff)[_i]), (PG8_LAS unsigned*)(lds + (bufoff) + ldsw + _i * 8192), 16, 0, AUX); } while (0)
; #define PG8_LDA(dst, b, h) do { _Pragma("unroll") for (int m = 0; m < 4; ++m) _Pragma("unroll") for (int k = 0; k < 2; ++k) dst[m][k] = *(const PG8_LAS bf16x8*)(lds + PG8_SA(b, h) + aoff + m * 2048 + k * 1024); } while (0)
; #define PG8_LDB(dst, b, h) do { _Pragma("unroll") for (int n = 0; n < 2; ++n) _Pragma("unroll") for (int k = 0; k < 2; ++k) dst[n][k] = *(const PG8_LAS bf16x8*)(lds + PG8_SB(b, h) + boff + n * 2048 + k * 1024); } while (0)
; #define PG8_MMA(ai, bj, At, Bt) do { __builtin_amdgcn_s_setprio(1); _Pragma("unroll") for (int m = 0; m < 4; ++m) _Pragma("unroll") for (int n = 0; n < 2; ++n) _Pragma("unroll") for (int k = 0; k < 2; ++k) \
;         acc[ai][bj][m][n] = __builtin_amdgcn_mfma_f32_16x16x32_bf16(Bt[n][k], At[m][k], acc[ai][bj][m][n], 0, 0, 0); __builtin_amdgcn_s_setprio(0); } while (0)
; #define PG8_WAIT_V(n) asm volatile("s_waitcnt vmcnt(" #n ")" ::: "memory")
; #define PG8_WAIT_L(n) asm volatile("s_waitcnt lgkmcnt(" #n ")" ::: "memory")
; #define PG8_BAR __builtin_amdgcn_s_barrier()
; #define PG8_SCHED __builtin_amdgcn_sched_barrier(0)
;     ...
;             if (!pe) { PG8_WAIT_V(8); } PG8_WAIT_L(0); PG8_BAR; PG8_MMA(1, 0, At, B0); PG8_MMA(1, 1, At, B1); PG8_BAR; PG8_SCHED;
;             PG8_LDB(B0, 1, 0); PG8_LDB(B1, 1, 1); PG8_SCHED; PG8_LDA(At, 1, 0); PG8_STAGE_T(PG8_SA(0, 1), a2 + hstep, voffA, AUX_A);
;             if (!pe) { PG8_WAIT_V(8); } PG8_WAIT_L(0); PG8_BAR; PG8_MMA(0, 0, At, B0); PG8_MMA(0, 1, At, B1); PG8_BAR; PG8_SCHED;
	s_waitcnt lgkmcnt(0)
	v_mfma_f32_16x16x32_bf16 v[60:63], v[146:149], v[186:189], v[60:63]
	v_mfma_f32_16x16x32_bf16 v[56:59], v[154:157], v[186:189], v[56:59]
	v_mfma_f32_16x16x32_bf16 v[44:47], v[146:149], v[196:199], v[44:47]
	v_mfma_f32_16x16x32_bf16 v[40:43], v[154:157], v[196:199], v[40:43]
	v_mfma_f32_16x16x32_bf16 v[28:31], v[146:149], v[204:207], v[28:31]
	v_mfma_f32_16x16x32_bf16 v[24:27], v[154:157], v[204:207], v[24:27]
	v_mfma_f32_16x16x32_bf16 v[12:15], v[146:149], v[212:215], v[12:15]
	v_mfma_f32_16x16x32_bf16 v[8:11], v[154:157], v[212:215], v[8:11]
	v_mfma_f32_16x16x32_bf16 v[60:63], v[150:153], v[190:193], v[60:63]
	v_mfma_f32_16x16x32_bf16 v[56:59], v[158:161], v[190:193], v[56:59]
	v_mfma_f32_16x16x32_bf16 v[44:47], v[150:153], v[200:203], v[44:47]
	v_mfma_f32_16x16x32_bf16 v[40:43], v[158:161], v[200:203], v[40:43]
	v_mfma_f32_16x16x32_bf16 v[28:31], v[150:153], v[208:211], v[28:31]
	v_mfma_f32_16x16x32_bf16 v[24:27], v[158:161], v[208:211], v[24:27]
	v_mfma_f32_16x16x32_bf16 v[12:15], v[150:153], v[216:219], v[12:15]
	v_mfma_f32_16x16x32_bf16 v[8:11], v[158:161], v[216:219], v[8:11]
	v_mfma_f32_16x16x32_bf16 v[52:55], v[162:165], v[186:189], v[52:55]
	v_mfma_f32_16x16x32_bf16 v[48:51], v[170:173], v[186:189], v[48:51]
	v_mfma_f32_16x16x32_bf16 v[36:39], v[162:165], v[196:199], v[36:39]
	v_mfma_f32_16x16x32_bf16 v[32:35], v[170:173], v[196:199], v[32:35]
	v_mfma_f32_16x16x32_bf16 v[20:23], v[162:165], v[204:207], v[20:23]
	v_mfma_f32_16x16x32_bf16 v[16:19], v[170:173], v[204:207], v[16:19]
	v_mfma_f32_16x16x32_bf16 v[4:7], v[162:165], v[212:215], v[4:7]
	v_mfma_f32_16x16x32_bf16 v[0:3], v[170:173], v[212:215], v[0:3]
	v_mfma_f32_16x16x32_bf16 v[52:55], v[166:169], v[190:193], v[52:55]
	v_mfma_f32_16x16x32_bf16 v[48:51], v[182:185], v[190:193], v[48:51]
	v_mfma_f32_16x16x32_bf16 v[36:39], v[166:169], v[200:203], v[36:39]
	v_mfma_f32_16x16x32_bf16 v[32:35], v[182:185], v[200:203], v[32:35]
	v_mfma_f32_16x16x32_bf16 v[20:23], v[166:169], v[208:211], v[20:23]
	v_mfma_f32_16x16x32_bf16 v[16:19], v[182:185], v[208:211], v[16:19]
	v_mfma_f32_16x16x32_bf16 v[4:7], v[166:169], v[216:219], v[4:7]
	s_setprio 2
	s_barrier
	v_mfma_f32_16x16x32_bf16 v[0:3], v[182:185], v[216:219], v[0:3]
	s_setprio 0
	s_add_i32 s69, 0, 0x18000
	v_add_u32_e32 v136, s69, v175
	s_add_i32 s70, 0, 0x1c000
	ds_read_b128 v[146:149], v136
	ds_read_b128 v[150:153], v136 offset:1024
	ds_read_b128 v[154:157], v136 offset:2048
	ds_read_b128 v[158:161], v136 offset:3072
	v_add_u32_e32 v136, s70, v175
	ds_read_b128 v[162:165], v136
	ds_read_b128 v[166:169], v136 offset:1024
	ds_read_b128 v[170:173], v136 offset:2048
	ds_read_b128 v[182:185], v136 offset:3072
	s_add_u32 s52, s52, 0x40000
	s_addc_u32 s53, s53, 0
	s_mov_b32 m0, s56
	v_lshl_add_u64 v[228:229], s[52:53], 0, v[128:129]
	ds_read_b128 v[186:189], v180 offset:32768
	ds_read_b128 v[190:193], v180 offset:33792
	ds_read_b128 v[196:199], v180 offset:34816
	ds_read_b128 v[200:203], v180 offset:35840
	ds_read_b128 v[204:207], v180 offset:36864
	ds_read_b128 v[208:211], v180 offset:37888
	ds_read_b128 v[212:215], v180 offset:38912
	ds_read_b128 v[216:219], v180 offset:39936
	global_load_lds_dwordx4 v[228:229], off
	v_lshl_add_u64 v[228:229], s[52:53], 0, v[132:133]
	s_mov_b32 m0, s57
	s_nop 0
	global_load_lds_dwordx4 v[228:229], off
	s_waitcnt vmcnt(8)
	s_waitcnt lgkmcnt(0)
	s_barrier
	s_waitcnt lgkmcnt(0)
	v_mfma_f32_16x16x32_bf16 v[124:127], v[146:149], v[186:189], v[124:127]
	v_mfma_f32_16x16x32_bf16 v[120:123], v[154:157], v[186:189], v[120:123]
	v_mfma_f32_16x16x32_bf16 v[108:111], v[146:149], v[196:199], v[108:111]
	v_mfma_f32_16x16x32_bf16 v[104:107], v[154:157], v[196:199], v[104:107]
	v_mfma_f32_16x16x32_bf16 v[92:95], v[146:149], v[204:207], v[92:95]
	v_mfma_f32_16x16x32_bf16 v[88:91], v[154:157], v[204:207], v[88:91]
	v_mfma_f32_16x16x32_bf16 v[76:79], v[146:149], v[212:215], v[76:79]
	v_mfma_f32_16x16x32_bf16 v[72:75], v[154:157], v[212:215], v[72:75]
	v_mfma_f32_16x16x32_bf16 v[124:127], v[150:153], v[190:193], v[124:127]
	v_mfma_f32_16x16x32_bf16 v[120:123], v[158:161], v[190:193], v[120:123]
	v_mfma_f32_16x16x32_bf16 v[108:111], v[150:153], v[200:203], v[108:111]
	v_mfma_f32_16x16x32_bf16 v[104:107], v[158:161], v[200:203], v[104:107]
	v_mfma_f32_16x16x32_bf16 v[92:95], v[150:153], v[208:211], v[92:95]
	v_mfma_f32_16x16x32_bf16 v[88:91], v[158:161], v[208:211], v[88:91]
	v_mfma_f32_16x16x32_bf16 v[76:79], v[150:153], v[216:219], v[76:79]
	v_mfma_f32_16x16x32_bf16 v[72:75], v[158:161], v[216:219], v[72:75]
	v_mfma_f32_16x16x32_bf16 v[116:119], v[162:165], v[186:189], v[116:119]
	v_mfma_f32_16x16x32_bf16 v[112:115], v[170:173], v[186:189], v[112:115]
	v_mfma_f32_16x16x32_bf16 v[100:103], v[162:165], v[196:199], v[100:103]
	v_mfma_f32_16x16x32_bf16 v[96:99], v[170:173], v[196:199], v[96:99]
	v_mfma_f32_16x16x32_bf16 v[84:87], v[162:165], v[204:207], v[84:87]
	v_mfma_f32_16x16x32_bf16 v[80:83], v[170:173], v[204:207], v[80:83]
	v_mfma_f32_16x16x32_bf16 v[68:71], v[162:165], v[212:215], v[68:71]
	v_mfma_f32_16x16x32_bf16 v[64:67], v[170:173], v[212:215], v[64:67]
	v_mfma_f32_16x16x32_bf16 v[116:119], v[166:169], v[190:193], v[116:119]
	v_mfma_f32_16x16x32_bf16 v[112:115], v[182:185], v[190:193], v[112:115]
	v_mfma_f32_16x16x32_bf16 v[100:103], v[166:169], v[200:203], v[100:103]
	v_mfma_f32_16x16x32_bf16 v[96:99], v[182:185], v[200:203], v[96:99]
	v_mfma_f32_16x16x32_bf16 v[84:87], v[166:169], v[208:211], v[84:87]
	v_mfma_f32_16x16x32_bf16 v[80:83], v[182:185], v[208:211], v[80:83]
	v_mfma_f32_16x16x32_bf16 v[68:71], v[166:169], v[216:219], v[68:71]
	s_setprio 2
	s_barrier
; #define PG8_STAGE_T(bufoff, gbase, voff, AUX) do { _Pragma("unroll") for (int _i = 0; _i < 2; ++_i) \
;         __builtin_amdgcn_global_load_lds((const unsigned*)((const char*)(gbase) + (voff)[_i]), (PG8_LAS unsigned*)(lds + (bufoff) + ldsw + _i * 8192), 16, 0, AUX); } while (0)
; #define PG8_LDA(dst, b, h) do { _Pragma("unroll") for (int m = 0; m < 4; ++m) _Pragma("unroll") for (int k = 0; k < 2; ++k) dst[m][k] = *(const PG8_LAS bf16x8*)(lds + PG8_SA(b, h) + aoff + m * 2048 + k * 1024); } while (0)
; #define PG8_MMA(ai, bj, At, Bt) do { __builtin_amdgcn_s_setprio(1); _Pragma("unroll") for (int m = 0; m < 4; ++m) _Pragma("unroll") for (int n = 0; n < 2; ++n) _Pragma("unroll") for (int k = 0; k < 2; ++k) \
;         acc[ai][bj][m][n] = __builtin_amdgcn_mfma_f32_16x16x32_bf16(Bt[n][k], At[m][k], acc[ai][bj][m][n], 0, 0, 0); __builtin_amdgcn_s_setprio(0); } while (0)
; #define PG8_WAIT_V(n) asm volatile("s_waitcnt vmcnt(" #n ")" ::: "memory")
; #define PG8_WAIT_L(n) asm volatile("s_waitcnt lgkmcnt(" #n ")" ::: "memory")
; #define PG8_BAR __builtin_amdgcn_s_barrier()
; #define PG8_SCHED __builtin_amdgcn_sched_barrier(0)
;     ...
;             if (!pe) { PG8_WAIT_V(8); } PG8_WAIT_L(0); PG8_BAR; PG8_MMA(0, 0, At, B0); PG8_MMA(0, 1, At, B1); PG8_BAR; PG8_SCHED;
;             PG8_LDA(At, 1, 1); PG8_STAGE_T(PG8_SB(1, 0), b3, voffB, AUX_B); PG8_STAGE_T(PG8_SB(1, 1), b3 + hstep, voffB, AUX_B); PG8_STAGE_T(PG8_SA(1, 0), a3, voffA, AUX_A);
;             PG8_WAIT_V(8); PG8_WAIT_L(0); PG8_BAR; PG8_MMA(1, 0, At, B0); PG8_MMA(1, 1, At, B1); PG8_BAR; PG8_SCHED;
;     ...
;         if constexpr (ALIGN_EPI) { if (wr == 0) PG8_BAR; }
	v_mfma_f32_16x16x32_bf16 v[64:67], v[182:185], v[216:219], v[64:67]
	s_setprio 0
	s_add_i32 s52, s69, s8
	v_lshl_add_u64 v[220:221], v[220:221], 0, s[22:23]
	s_mov_b32 m0, s52
	ds_read_b128 v[186:189], v180 offset:49152
	ds_read_b128 v[190:193], v180 offset:50176
	ds_read_b128 v[196:199], v180 offset:51200
	ds_read_b128 v[200:203], v180 offset:52224
	ds_read_b128 v[204:207], v180 offset:53248
	ds_read_b128 v[208:211], v180 offset:54272
	ds_read_b128 v[212:215], v180 offset:55296
	ds_read_b128 v[216:219], v180 offset:56320
	global_load_lds_dwordx4 v[220:221], off
	s_add_i32 m0, s52, 0x2000
	s_add_u32 s50, s50, 0x40080
	v_lshl_add_u64 v[220:221], v[222:223], 0, s[22:23]
	s_addc_u32 s51, s51, 0
	s_add_i32 s52, s70, s8
	global_load_lds_dwordx4 v[220:221], off
	v_lshl_add_u64 v[220:221], s[50:51], 0, v[130:131]
	s_mov_b32 m0, s52
	s_nop 0
	global_load_lds_dwordx4 v[220:221], off
	v_lshl_add_u64 v[220:221], s[50:51], 0, v[134:135]
	s_add_i32 m0, s52, 0x2000
	s_nop 0
	global_load_lds_dwordx4 v[220:221], off
	v_lshl_add_u64 v[220:221], v[224:225], 0, s[22:23]
	s_mov_b32 m0, s59
	s_nop 0
	global_load_lds_dwordx4 v[220:221], off
	v_lshl_add_u64 v[220:221], v[226:227], 0, s[22:23]
	s_mov_b32 m0, s60
	s_nop 0
	global_load_lds_dwordx4 v[220:221], off
	s_waitcnt vmcnt(8)
	s_waitcnt lgkmcnt(0)
	s_barrier
	s_waitcnt lgkmcnt(0)
	v_mfma_f32_16x16x32_bf16 v[60:63], v[146:149], v[186:189], v[60:63]
	v_mfma_f32_16x16x32_bf16 v[56:59], v[154:157], v[186:189], v[56:59]
	v_mfma_f32_16x16x32_bf16 v[44:47], v[146:149], v[196:199], v[44:47]
	v_mfma_f32_16x16x32_bf16 v[40:43], v[154:157], v[196:199], v[40:43]
	v_mfma_f32_16x16x32_bf16 v[28:31], v[146:149], v[204:207], v[28:31]
	v_mfma_f32_16x16x32_bf16 v[24:27], v[154:157], v[204:207], v[24:27]
	v_mfma_f32_16x16x32_bf16 v[12:15], v[146:149], v[212:215], v[12:15]
	v_mfma_f32_16x16x32_bf16 v[8:11], v[154:157], v[212:215], v[8:11]
	v_mfma_f32_16x16x32_bf16 v[60:63], v[150:153], v[190:193], v[60:63]
	v_mfma_f32_16x16x32_bf16 v[56:59], v[158:161], v[190:193], v[56:59]
	v_mfma_f32_16x16x32_bf16 v[44:47], v[150:153], v[200:203], v[44:47]
	v_mfma_f32_16x16x32_bf16 v[40:43], v[158:161], v[200:203], v[40:43]
	v_mfma_f32_16x16x32_bf16 v[28:31], v[150:153], v[208:211], v[28:31]
	v_mfma_f32_16x16x32_bf16 v[24:27], v[158:161], v[208:211], v[24:27]
	v_mfma_f32_16x16x32_bf16 v[12:15], v[150:153], v[216:219], v[12:15]
	v_mfma_f32_16x16x32_bf16 v[8:11], v[158:161], v[216:219], v[8:11]
	v_mfma_f32_16x16x32_bf16 v[52:55], v[162:165], v[186:189], v[52:55]
	v_mfma_f32_16x16x32_bf16 v[48:51], v[170:173], v[186:189], v[48:51]
	v_mfma_f32_16x16x32_bf16 v[36:39], v[162:165], v[196:199], v[36:39]
	v_mfma_f32_16x16x32_bf16 v[32:35], v[170:173], v[196:199], v[32:35]
	v_mfma_f32_16x16x32_bf16 v[20:23], v[162:165], v[204:207], v[20:23]
	v_mfma_f32_16x16x32_bf16 v[16:19], v[170:173], v[204:207], v[16:19]
	v_mfma_f32_16x16x32_bf16 v[4:7], v[162:165], v[212:215], v[4:7]
	v_mfma_f32_16x16x32_bf16 v[0:3], v[170:173], v[212:215], v[0:3]
	v_mfma_f32_16x16x32_bf16 v[52:55], v[166:169], v[190:193], v[52:55]
	v_mfma_f32_16x16x32_bf16 v[48:51], v[182:185], v[190:193], v[48:51]
	v_mfma_f32_16x16x32_bf16 v[36:39], v[166:169], v[200:203], v[36:39]
	v_mfma_f32_16x16x32_bf16 v[32:35], v[182:185], v[200:203], v[32:35]
	v_mfma_f32_16x16x32_bf16 v[20:23], v[166:169], v[208:211], v[20:23]
	v_mfma_f32_16x16x32_bf16 v[16:19], v[182:185], v[208:211], v[16:19]
	v_mfma_f32_16x16x32_bf16 v[4:7], v[166:169], v[216:219], v[4:7]
	s_setprio 2
	s_barrier
	v_mfma_f32_16x16x32_bf16 v[0:3], v[182:185], v[216:219], v[0:3]
	s_setprio 0
	s_add_i32 s68, s68, 2
	s_add_u32 s48, s48, 0x100
	s_addc_u32 s49, s49, 0
	s_add_u32 s66, s66, 0x100
	s_addc_u32 s67, s67, 0
	s_cmp_gt_u32 s68, 13
	s_cbranch_scc0 .LBB0_516
	s_and_b64 vcc, exec, s[24:25]
	s_cbranch_vccz .LBB0_519
	s_barrier

; #define PG8_STAGE_T(bufoff, gbase, voff, AUX) do { _Pragma("unroll") for (int _i = 0; _i < 2; ++_i) \
;         __builtin_amdgcn_global_load_lds((const unsigned*)((const char*)(gbase) + (voff)[_i]), (PG8_LAS unsigned*)(lds + (bufoff) + ldsw + _i * 8192), 16, 0, AUX); } while (0)
; #define PG8_LDA(dst, b, h) do { _Pragma("unroll") for (int m = 0; m < 4; ++m) _Pragma("unroll") for (int k = 0; k < 2; ++k) dst[m][k] = *(const PG8_LAS bf16x8*)(lds + PG8_SA(b, h) + aoff + m * 2048 + k * 1024); } while (0)
; #define PG8_LDB(dst, b, h) do { _Pragma("unroll") for (int n = 0; n < 2; ++n) _Pragma("unroll") for (int k = 0; k < 2; ++k) dst[n][k] = *(const PG8_LAS bf16x8*)(lds + PG8_SB(b, h) + boff + n * 2048 + k * 1024); } while (0)
; #define PG8_MMA(ai, bj, At, Bt) do { __builtin_amdgcn_s_setprio(1); _Pragma("unroll") for (int m = 0; m < 4; ++m) _Pragma("unroll") for (int n = 0; n < 2; ++n) _Pragma("unroll") for (int k = 0; k < 2; ++k) \
;         acc[ai][bj][m][n] = __builtin_amdgcn_mfma_f32_16x16x32_bf16(Bt[n][k], At[m][k], acc[ai][bj][m][n], 0, 0, 0); __builtin_amdgcn_s_setprio(0); } while (0)
; #define PG8_WAIT_V(n) asm volatile("s_waitcnt vmcnt(" #n ")" ::: "memory")
;     ...
;             const bool last = (t == nt - 2);
;             const char* a1 = cA + (ptrdiff_t)(t + 1) * ck;
;             const char* a2 = last ? nA : cA + (ptrdiff_t)(t + 2) * ck; const char* b2 = last ? nB : cB + (ptrdiff_t)(t + 2) * ck;
;             const ptrdiff_t k3 = last ? nk : ck;
;             const char* a3 = a2 + k3; const char* b3 = b2 + k3;
;             if (last && has_next) S.a_ready(nxt);
;             if constexpr (SP2) {
;             int pei = 0; if constexpr (PEEL) { pei = __builtin_amdgcn_readfirstlane((t == 0 && ui > 0) ? 1 : 0); asm volatile("" : "+s"(pei)); }
;             const bool pe = pei != 0;
;             PG8_LDB(B0, 0, 0); PG8_LDB(B1, 0, 1); PG8_SCHED; PG8_LDA(At, 0, 0); if (!pe) { PG8_STAGE_T(PG8_SA(1, 1), a1 + hstep, voffA, AUX_A); }
;             if (!pe) { PG8_WAIT_V(8); } PG8_WAIT_L(0); PG8_BAR; PG8_MMA(0, 0, At, B0); PG8_MMA(0, 1, At, B1); PG8_BAR; PG8_SCHED;
;             PG8_LDA(At, 0, 1); PG8_STAGE_T(PG8_SB(0, 0), b2, voffB, AUX_B); PG8_STAGE_T(PG8_SB(0, 1), b2 + hstep, voffB, AUX_B); PG8_STAGE_T(PG8_SA(0, 0), a2, voffA, AUX_A);
;             if (!pe) { PG8_WAIT_V(8); } PG8_WAIT_L(0); PG8_BAR; PG8_MMA(1, 0, At, B0); PG8_MMA(1, 1, At, B1); PG8_BAR; PG8_SCHED;
.LBB0_787:
	ds_read_b128 v[136:139], v163
	ds_read_b128 v[140:143], v163 offset:1024
	ds_read_b128 v[166:169], v163 offset:2048
	ds_read_b128 v[170:173], v163 offset:3072
	ds_read_b128 v[174:177], v164
	ds_read_b128 v[178:181], v164 offset:1024
	ds_read_b128 v[182:185], v164 offset:2048
	ds_read_b128 v[186:189], v164 offset:3072
	s_add_u32 s46, s44, 0xfffc0080
	s_addc_u32 s47, s45, -1
	s_cmp_eq_u32 s65, 12
	s_cselect_b32 s49, s25, s47
	s_cselect_b32 s48, s61, s46
	s_cselect_b32 s47, s37, s64
	s_cselect_b32 s46, s62, s63
	v_lshl_add_u64 v[224:225], s[44:45], 0, v[128:129]
	s_add_i32 m0, s43, 0xc000
	ds_read_b128 v[190:193], v165
	ds_read_b128 v[196:199], v165 offset:1024
	ds_read_b128 v[200:203], v165 offset:2048
	ds_read_b128 v[204:207], v165 offset:3072
	ds_read_b128 v[208:211], v165 offset:4096
	ds_read_b128 v[212:215], v165 offset:5120
	ds_read_b128 v[216:219], v165 offset:6144
	ds_read_b128 v[220:223], v165 offset:7168
	global_load_lds_dwordx4 v[224:225], off
	v_lshl_add_u64 v[224:225], s[44:45], 0, v[130:131]
	s_add_i32 m0, s43, 0xe000
	s_nop 0
	global_load_lds_dwordx4 v[224:225], off
	s_waitcnt vmcnt(8)
	s_waitcnt lgkmcnt(0)
	s_barrier
	s_waitcnt lgkmcnt(0)
	v_mfma_f32_16x16x32_bf16 v[124:127], v[136:139], v[190:193], v[124:127]
	v_mfma_f32_16x16x32_bf16 v[120:123], v[166:169], v[190:193], v[120:123]
	v_mfma_f32_16x16x32_bf16 v[116:119], v[136:139], v[200:203], v[116:119]
	v_mfma_f32_16x16x32_bf16 v[112:115], v[166:169], v[200:203], v[112:115]
	v_mfma_f32_16x16x32_bf16 v[96:99], v[136:139], v[208:211], v[96:99]
	v_mfma_f32_16x16x32_bf16 v[88:91], v[166:169], v[208:211], v[88:91]
	v_mfma_f32_16x16x32_bf16 v[80:83], v[136:139], v[216:219], v[80:83]
	v_mfma_f32_16x16x32_bf16 v[72:75], v[166:169], v[216:219], v[72:75]
	v_mfma_f32_16x16x32_bf16 v[124:127], v[140:143], v[196:199], v[124:127]
	v_mfma_f32_16x16x32_bf16 v[120:123], v[170:173], v[196:199], v[120:123]
	v_mfma_f32_16x16x32_bf16 v[116:119], v[140:143], v[204:207], v[116:119]
	v_mfma_f32_16x16x32_bf16 v[112:115], v[170:173], v[204:207], v[112:115]
	v_mfma_f32_16x16x32_bf16 v[96:99], v[140:143], v[212:215], v[96:99]
	v_mfma_f32_16x16x32_bf16 v[88:91], v[170:173], v[212:215], v[88:91]
	v_mfma_f32_16x16x32_bf16 v[80:83], v[140:143], v[220:223], v[80:83]
	v_mfma_f32_16x16x32_bf16 v[72:75], v[170:173], v[220:223], v[72:75]
	v_mfma_f32_16x16x32_bf16 v[108:111], v[174:177], v[190:193], v[108:111]
	v_mfma_f32_16x16x32_bf16 v[104:107], v[182:185], v[190:193], v[104:107]
	v_mfma_f32_16x16x32_bf16 v[100:103], v[174:177], v[200:203], v[100:103]
	v_mfma_f32_16x16x32_bf16 v[92:95], v[182:185], v[200:203], v[92:95]
	v_mfma_f32_16x16x32_bf16 v[84:87], v[174:177], v[208:211], v[84:87]
	v_mfma_f32_16x16x32_bf16 v[76:79], v[182:185], v[208:211], v[76:79]
	v_mfma_f32_16x16x32_bf16 v[68:71], v[174:177], v[216:219], v[68:71]
	v_mfma_f32_16x16x32_bf16 v[64:67], v[182:185], v[216:219], v[64:67]
	v_mfma_f32_16x16x32_bf16 v[108:111], v[178:181], v[196:199], v[108:111]
	v_mfma_f32_16x16x32_bf16 v[104:107], v[186:189], v[196:199], v[104:107]
	v_mfma_f32_16x16x32_bf16 v[100:103], v[178:181], v[204:207], v[100:103]
	v_mfma_f32_16x16x32_bf16 v[92:95], v[186:189], v[204:207], v[92:95]
	v_mfma_f32_16x16x32_bf16 v[84:87], v[178:181], v[212:215], v[84:87]
	v_mfma_f32_16x16x32_bf16 v[76:79], v[186:189], v[212:215], v[76:79]
	v_mfma_f32_16x16x32_bf16 v[68:71], v[178:181], v[220:223], v[68:71]
	s_setprio 2
	s_barrier
	v_mfma_f32_16x16x32_bf16 v[64:67], v[186:189], v[220:223], v[64:67]
	s_setprio 0
	s_add_i32 s66, s58, s50
	v_lshl_add_u64 v[224:225], s[46:47], 0, v[154:155]
	s_mov_b32 m0, s66
	ds_read_b128 v[190:193], v165 offset:16384
	ds_read_b128 v[196:199], v165 offset:17408
	ds_read_b128 v[200:203], v165 offset:18432
	ds_read_b128 v[204:207], v165 offset:19456
	ds_read_b128 v[208:211], v165 offset:20480
	ds_read_b128 v[212:215], v165 offset:21504
	ds_read_b128 v[216:219], v165 offset:22528
	ds_read_b128 v[220:223], v165 offset:23552
	global_load_lds_dwordx4 v[224:225], off
	s_add_i32 m0, s66, 0x2000
	s_add_u32 s66, s46, 0x40000
	v_lshl_add_u64 v[226:227], s[46:47], 0, v[158:159]
	s_addc_u32 s67, s47, 0
	s_add_i32 s68, s59, s50
	global_load_lds_dwordx4 v[226:227], off
	v_lshl_add_u64 v[228:229], s[66:67], 0, v[154:155]
	s_mov_b32 m0, s68
	v_lshl_add_u64 v[230:231], s[48:49], 0, v[156:157]
	global_load_lds_dwordx4 v[228:229], off
	v_lshl_add_u64 v[228:229], s[66:67], 0, v[158:159]
	s_add_i32 m0, s68, 0x2000
	s_nop 0
	global_load_lds_dwordx4 v[228:229], off
	v_lshl_add_u64 v[228:229], s[48:49], 0, v[152:153]
	s_mov_b32 m0, s43
	s_nop 0
	global_load_lds_dwordx4 v[228:229], off
	s_mov_b32 m0, s51
	s_nop 0
	global_load_lds_dwordx4 v[230:231], off
	s_waitcnt vmcnt(8)
	s_waitcnt lgkmcnt(0)
	s_barrier
; #define PG8_STAGE_T(bufoff, gbase, voff, AUX) do { _Pragma("unroll") for (int _i = 0; _i < 2; ++_i) \
;         __builtin_amdgcn_global_load_lds((const unsigned*)((const char*)(gbase) + (voff)[_i]), (PG8_LAS unsigned*)(lds + (bufoff) + ldsw + _i * 8192), 16, 0, AUX); } while (0)
; #define PG8_LDA(dst, b, h) do { _Pragma("unroll") for (int m = 0; m < 4; ++m) _Pragma("unroll") for (int k = 0; k < 2; ++k) dst[m][k] = *(const PG8_LAS bf16x8*)(lds + PG8_SA(b, h) + aoff + m * 2048 + k * 1024); } while (0)
; #define PG8_LDB(dst, b, h) do { _Pragma("unroll") for (int n = 0; n < 2; ++n) _Pragma("unroll") for (int k = 0; k < 2; ++k) dst[n][k] = *(const PG8_LAS bf16x8*)(lds + PG8_SB(b, h) + boff + n * 2048 + k * 1024); } while (0)
; #define PG8_MMA(ai, bj, At, Bt) do { __builtin_amdgcn_s_setprio(1); _Pragma("unroll") for (int m = 0; m < 4; ++m) _Pragma("unroll") for (int n = 0; n < 2; ++n) _Pragma("unroll") for (int k = 0; k < 2; ++k) \
;         acc[ai][bj][m][n] = __builtin_amdgcn_mfma_f32_16x16x32_bf16(Bt[n][k], At[m][k], acc[ai][bj][m][n], 0, 0, 0); __builtin_amdgcn_s_setprio(0); } while (0)
; #define PG8_WAIT_V(n) asm volatile("s_waitcnt vmcnt(" #n ")" ::: "memory")
; #define PG8_WAIT_L(n) asm volatile("s_waitcnt lgkmcnt(" #n ")" ::: "memory")
; #define PG8_BAR __builtin_amdgcn_s_barrier()
; #define PG8_SCHED __builtin_amdgcn_sched_barrier(0)
;     ...
;             if (!pe) { PG8_WAIT_V(8); } PG8_WAIT_L(0); PG8_BAR; PG8_MMA(1, 0, At, B0); PG8_MMA(1, 1, At, B1); PG8_BAR; PG8_SCHED;
;             PG8_LDB(B0, 1, 0); PG8_LDB(B1, 1, 1); PG8_SCHED; PG8_LDA(At, 1, 0); PG8_STAGE_T(PG8_SA(0, 1), a2 + hstep, voffA, AUX_A);
;             if (!pe) { PG8_WAIT_V(8); } PG8_WAIT_L(0); PG8_BAR; PG8_MMA(0, 0, At, B0); PG8_MMA(0, 1, At, B1); PG8_BAR; PG8_SCHED;
	s_waitcnt lgkmcnt(0)
	v_mfma_f32_16x16x32_bf16 v[60:63], v[136:139], v[190:193], v[60:63]
	v_mfma_f32_16x16x32_bf16 v[56:59], v[166:169], v[190:193], v[56:59]
	v_mfma_f32_16x16x32_bf16 v[48:51], v[136:139], v[200:203], v[48:51]
	v_mfma_f32_16x16x32_bf16 v[40:43], v[166:169], v[200:203], v[40:43]
	v_mfma_f32_16x16x32_bf16 v[32:35], v[136:139], v[208:211], v[32:35]
	v_mfma_f32_16x16x32_bf16 v[24:27], v[166:169], v[208:211], v[24:27]
	v_mfma_f32_16x16x32_bf16 v[16:19], v[136:139], v[216:219], v[16:19]
	v_mfma_f32_16x16x32_bf16 v[8:11], v[166:169], v[216:219], v[8:11]
	v_mfma_f32_16x16x32_bf16 v[60:63], v[140:143], v[196:199], v[60:63]
	v_mfma_f32_16x16x32_bf16 v[56:59], v[170:173], v[196:199], v[56:59]
	v_mfma_f32_16x16x32_bf16 v[48:51], v[140:143], v[204:207], v[48:51]
	v_mfma_f32_16x16x32_bf16 v[40:43], v[170:173], v[204:207], v[40:43]
	v_mfma_f32_16x16x32_bf16 v[32:35], v[140:143], v[212:215], v[32:35]
	v_mfma_f32_16x16x32_bf16 v[24:27], v[170:173], v[212:215], v[24:27]
	v_mfma_f32_16x16x32_bf16 v[16:19], v[140:143], v[220:223], v[16:19]
	v_mfma_f32_16x16x32_bf16 v[8:11], v[170:173], v[220:223], v[8:11]
	v_mfma_f32_16x16x32_bf16 v[52:55], v[174:177], v[190:193], v[52:55]
	v_mfma_f32_16x16x32_bf16 v[44:47], v[182:185], v[190:193], v[44:47]
	v_mfma_f32_16x16x32_bf16 v[36:39], v[174:177], v[200:203], v[36:39]
	v_mfma_f32_16x16x32_bf16 v[28:31], v[182:185], v[200:203], v[28:31]
	v_mfma_f32_16x16x32_bf16 v[20:23], v[174:177], v[208:211], v[20:23]
	v_mfma_f32_16x16x32_bf16 v[12:15], v[182:185], v[208:211], v[12:15]
	v_mfma_f32_16x16x32_bf16 v[4:7], v[174:177], v[216:219], v[4:7]
	v_mfma_f32_16x16x32_bf16 v[0:3], v[182:185], v[216:219], v[0:3]
	v_mfma_f32_16x16x32_bf16 v[52:55], v[178:181], v[196:199], v[52:55]
	v_mfma_f32_16x16x32_bf16 v[44:47], v[186:189], v[196:199], v[44:47]
	v_mfma_f32_16x16x32_bf16 v[36:39], v[178:181], v[204:207], v[36:39]
	v_mfma_f32_16x16x32_bf16 v[28:31], v[186:189], v[204:207], v[28:31]
	v_mfma_f32_16x16x32_bf16 v[20:23], v[178:181], v[212:215], v[20:23]
	v_mfma_f32_16x16x32_bf16 v[12:15], v[186:189], v[212:215], v[12:15]
	v_mfma_f32_16x16x32_bf16 v[4:7], v[178:181], v[220:223], v[4:7]
	s_setprio 2
	s_barrier
	v_mfma_f32_16x16x32_bf16 v[0:3], v[186:189], v[220:223], v[0:3]
	s_setprio 0
	s_add_i32 s66, 0, 0x18000
	s_add_i32 s67, 0, 0x1c000
	v_add_u32_e32 v170, s66, v161
	v_add_u32_e32 v186, s67, v161
	ds_read_b128 v[136:139], v170
	ds_read_b128 v[140:143], v170 offset:1024
	ds_read_b128 v[166:169], v170 offset:2048
	ds_read_b128 v[170:173], v170 offset:3072
	ds_read_b128 v[174:177], v186
	ds_read_b128 v[178:181], v186 offset:1024
	ds_read_b128 v[182:185], v186 offset:2048
	ds_read_b128 v[186:189], v186 offset:3072
	s_add_u32 s48, s48, 0x40000
	s_addc_u32 s49, s49, 0
	s_mov_b32 m0, s52
	v_lshl_add_u64 v[232:233], s[48:49], 0, v[152:153]
	ds_read_b128 v[190:193], v165 offset:32768
	ds_read_b128 v[196:199], v165 offset:33792
	ds_read_b128 v[200:203], v165 offset:34816
	ds_read_b128 v[204:207], v165 offset:35840
	ds_read_b128 v[208:211], v165 offset:36864
	ds_read_b128 v[212:215], v165 offset:37888
	ds_read_b128 v[216:219], v165 offset:38912
	ds_read_b128 v[220:223], v165 offset:39936
	global_load_lds_dwordx4 v[232:233], off
	v_lshl_add_u64 v[232:233], s[48:49], 0, v[156:157]
	s_mov_b32 m0, s53
	s_nop 0
	global_load_lds_dwordx4 v[232:233], off
	s_waitcnt vmcnt(8)
	s_waitcnt lgkmcnt(0)
	s_barrier
	s_waitcnt lgkmcnt(0)
	v_mfma_f32_16x16x32_bf16 v[124:127], v[136:139], v[190:193], v[124:127]
	v_mfma_f32_16x16x32_bf16 v[120:123], v[166:169], v[190:193], v[120:123]
	v_mfma_f32_16x16x32_bf16 v[116:119], v[136:139], v[200:203], v[116:119]
	v_mfma_f32_16x16x32_bf16 v[112:115], v[166:169], v[200:203], v[112:115]
	v_mfma_f32_16x16x32_bf16 v[96:99], v[136:139], v[208:211], v[96:99]
	v_mfma_f32_16x16x32_bf16 v[88:91], v[166:169], v[208:211], v[88:91]
	v_mfma_f32_16x16x32_bf16 v[80:83], v[136:139], v[216:219], v[80:83]
	v_mfma_f32_16x16x32_bf16 v[72:75], v[166:169], v[216:219], v[72:75]
	v_mfma_f32_16x16x32_bf16 v[124:127], v[140:143], v[196:199], v[124:127]
	v_mfma_f32_16x16x32_bf16 v[120:123], v[170:173], v[196:199], v[120:123]
	v_mfma_f32_16x16x32_bf16 v[116:119], v[140:143], v[204:207], v[116:119]
	v_mfma_f32_16x16x32_bf16 v[112:115], v[170:173], v[204:207], v[112:115]
	v_mfma_f32_16x16x32_bf16 v[96:99], v[140:143], v[212:215], v[96:99]
	v_mfma_f32_16x16x32_bf16 v[88:91], v[170:173], v[212:215], v[88:91]
	v_mfma_f32_16x16x32_bf16 v[80:83], v[140:143], v[220:223], v[80:83]
	v_mfma_f32_16x16x32_bf16 v[72:75], v[170:173], v[220:223], v[72:75]
	v_mfma_f32_16x16x32_bf16 v[108:111], v[174:177], v[190:193], v[108:111]
	v_mfma_f32_16x16x32_bf16 v[104:107], v[182:185], v[190:193], v[104:107]
	v_mfma_f32_16x16x32_bf16 v[100:103], v[174:177], v[200:203], v[100:103]
	v_mfma_f32_16x16x32_bf16 v[92:95], v[182:185], v[200:203], v[92:95]
	v_mfma_f32_16x16x32_bf16 v[84:87], v[174:177], v[208:211], v[84:87]
	v_mfma_f32_16x16x32_bf16 v[76:79], v[182:185], v[208:211], v[76:79]
	v_mfma_f32_16x16x32_bf16 v[68:71], v[174:177], v[216:219], v[68:71]
	v_mfma_f32_16x16x32_bf16 v[64:67], v[182:185], v[216:219], v[64:67]
	v_mfma_f32_16x16x32_bf16 v[108:111], v[178:181], v[196:199], v[108:111]
	v_mfma_f32_16x16x32_bf16 v[104:107], v[186:189], v[196:199], v[104:107]
	v_mfma_f32_16x16x32_bf16 v[100:103], v[178:181], v[204:207], v[100:103]
	v_mfma_f32_16x16x32_bf16 v[92:95], v[186:189], v[204:207], v[92:95]
	v_mfma_f32_16x16x32_bf16 v[84:87], v[178:181], v[212:215], v[84:87]
	v_mfma_f32_16x16x32_bf16 v[76:79], v[186:189], v[212:215], v[76:79]
	v_mfma_f32_16x16x32_bf16 v[68:71], v[178:181], v[220:223], v[68:71]
	s_setprio 2
	s_barrier
; #define PG8_STAGE_T(bufoff, gbase, voff, AUX) do { _Pragma("unroll") for (int _i = 0; _i < 2; ++_i) \
;         __builtin_amdgcn_global_load_lds((const unsigned*)((const char*)(gbase) + (voff)[_i]), (PG8_LAS unsigned*)(lds + (bufoff) + ldsw + _i * 8192), 16, 0, AUX); } while (0)
; #define PG8_LDA(dst, b, h) do { _Pragma("unroll") for (int m = 0; m < 4; ++m) _Pragma("unroll") for (int k = 0; k < 2; ++k) dst[m][k] = *(const PG8_LAS bf16x8*)(lds + PG8_SA(b, h) + aoff + m * 2048 + k * 1024); } while (0)
; #define PG8_MMA(ai, bj, At, Bt) do { __builtin_amdgcn_s_setprio(1); _Pragma("unroll") for (int m = 0; m < 4; ++m) _Pragma("unroll") for (int n = 0; n < 2; ++n) _Pragma("unroll") for (int k = 0; k < 2; ++k) \
;         acc[ai][bj][m][n] = __builtin_amdgcn_mfma_f32_16x16x32_bf16(Bt[n][k], At[m][k], acc[ai][bj][m][n], 0, 0, 0); __builtin_amdgcn_s_setprio(0); } while (0)
; #define PG8_WAIT_V(n) asm volatile("s_waitcnt vmcnt(" #n ")" ::: "memory")
; #define PG8_WAIT_L(n) asm volatile("s_waitcnt lgkmcnt(" #n ")" ::: "memory")
; #define PG8_BAR __builtin_amdgcn_s_barrier()
; #define PG8_SCHED __builtin_amdgcn_sched_barrier(0)
;     ...
;             if (!pe) { PG8_WAIT_V(8); } PG8_WAIT_L(0); PG8_BAR; PG8_MMA(0, 0, At, B0); PG8_MMA(0, 1, At, B1); PG8_BAR; PG8_SCHED;
;             PG8_LDA(At, 1, 1); PG8_STAGE_T(PG8_SB(1, 0), b3, voffB, AUX_B); PG8_STAGE_T(PG8_SB(1, 1), b3 + hstep, voffB, AUX_B); PG8_STAGE_T(PG8_SA(1, 0), a3, voffA, AUX_A);
;             PG8_WAIT_V(8); PG8_WAIT_L(0); PG8_BAR; PG8_MMA(1, 0, At, B0); PG8_MMA(1, 1, At, B1); PG8_BAR; PG8_SCHED;
;     ...
;         if constexpr (ALIGN_EPI) { if (wr == 0) PG8_BAR; }
	v_mfma_f32_16x16x32_bf16 v[64:67], v[186:189], v[220:223], v[64:67]
	s_setprio 0
	s_add_i32 s48, s66, s50
	v_lshl_add_u64 v[224:225], v[224:225], 0, s[10:11]
	s_mov_b32 m0, s48
	ds_read_b128 v[190:193], v165 offset:49152
	ds_read_b128 v[196:199], v165 offset:50176
	ds_read_b128 v[200:203], v165 offset:51200
	ds_read_b128 v[204:207], v165 offset:52224
	ds_read_b128 v[208:211], v165 offset:53248
	ds_read_b128 v[212:215], v165 offset:54272
	ds_read_b128 v[216:219], v165 offset:55296
	ds_read_b128 v[220:223], v165 offset:56320
	global_load_lds_dwordx4 v[224:225], off
	s_add_i32 m0, s48, 0x2000
	s_add_u32 s46, s46, 0x40080
	v_lshl_add_u64 v[224:225], v[226:227], 0, s[10:11]
	s_addc_u32 s47, s47, 0
	s_add_i32 s48, s67, s50
	global_load_lds_dwordx4 v[224:225], off
	v_lshl_add_u64 v[224:225], s[46:47], 0, v[154:155]
	s_mov_b32 m0, s48
	s_nop 0
	global_load_lds_dwordx4 v[224:225], off
	v_lshl_add_u64 v[224:225], s[46:47], 0, v[158:159]
	s_add_i32 m0, s48, 0x2000
	s_nop 0
	global_load_lds_dwordx4 v[224:225], off
	v_lshl_add_u64 v[224:225], v[228:229], 0, s[10:11]
	s_mov_b32 m0, s55
	s_nop 0
	global_load_lds_dwordx4 v[224:225], off
	v_lshl_add_u64 v[224:225], v[230:231], 0, s[10:11]
	s_mov_b32 m0, s56
	s_nop 0
	global_load_lds_dwordx4 v[224:225], off
	s_waitcnt vmcnt(8)
	s_waitcnt lgkmcnt(0)
	s_barrier
	s_waitcnt lgkmcnt(0)
	v_mfma_f32_16x16x32_bf16 v[60:63], v[136:139], v[190:193], v[60:63]
	v_mfma_f32_16x16x32_bf16 v[56:59], v[166:169], v[190:193], v[56:59]
	v_mfma_f32_16x16x32_bf16 v[48:51], v[136:139], v[200:203], v[48:51]
	v_mfma_f32_16x16x32_bf16 v[40:43], v[166:169], v[200:203], v[40:43]
	v_mfma_f32_16x16x32_bf16 v[32:35], v[136:139], v[208:211], v[32:35]
	v_mfma_f32_16x16x32_bf16 v[24:27], v[166:169], v[208:211], v[24:27]
	v_mfma_f32_16x16x32_bf16 v[16:19], v[136:139], v[216:219], v[16:19]
	v_mfma_f32_16x16x32_bf16 v[8:11], v[166:169], v[216:219], v[8:11]
	v_mfma_f32_16x16x32_bf16 v[60:63], v[140:143], v[196:199], v[60:63]
	v_mfma_f32_16x16x32_bf16 v[56:59], v[170:173], v[196:199], v[56:59]
	v_mfma_f32_16x16x32_bf16 v[48:51], v[140:143], v[204:207], v[48:51]
	v_mfma_f32_16x16x32_bf16 v[40:43], v[170:173], v[204:207], v[40:43]
	v_mfma_f32_16x16x32_bf16 v[32:35], v[140:143], v[212:215], v[32:35]
	v_mfma_f32_16x16x32_bf16 v[24:27], v[170:173], v[212:215], v[24:27]
	v_mfma_f32_16x16x32_bf16 v[16:19], v[140:143], v[220:223], v[16:19]
	v_mfma_f32_16x16x32_bf16 v[8:11], v[170:173], v[220:223], v[8:11]
	v_mfma_f32_16x16x32_bf16 v[52:55], v[174:177], v[190:193], v[52:55]
	v_mfma_f32_16x16x32_bf16 v[44:47], v[182:185], v[190:193], v[44:47]
	v_mfma_f32_16x16x32_bf16 v[36:39], v[174:177], v[200:203], v[36:39]
	v_mfma_f32_16x16x32_bf16 v[28:31], v[182:185], v[200:203], v[28:31]
	v_mfma_f32_16x16x32_bf16 v[20:23], v[174:177], v[208:211], v[20:23]
	v_mfma_f32_16x16x32_bf16 v[12:15], v[182:185], v[208:211], v[12:15]
	v_mfma_f32_16x16x32_bf16 v[4:7], v[174:177], v[216:219], v[4:7]
	v_mfma_f32_16x16x32_bf16 v[0:3], v[182:185], v[216:219], v[0:3]
	v_mfma_f32_16x16x32_bf16 v[52:55], v[178:181], v[196:199], v[52:55]
	v_mfma_f32_16x16x32_bf16 v[44:47], v[186:189], v[196:199], v[44:47]
	v_mfma_f32_16x16x32_bf16 v[36:39], v[178:181], v[204:207], v[36:39]
	v_mfma_f32_16x16x32_bf16 v[28:31], v[186:189], v[204:207], v[28:31]
	v_mfma_f32_16x16x32_bf16 v[20:23], v[178:181], v[212:215], v[20:23]
	v_mfma_f32_16x16x32_bf16 v[12:15], v[186:189], v[212:215], v[12:15]
	v_mfma_f32_16x16x32_bf16 v[4:7], v[178:181], v[220:223], v[4:7]
	s_setprio 2
	s_barrier
	v_mfma_f32_16x16x32_bf16 v[0:3], v[186:189], v[220:223], v[0:3]
	s_setprio 0
	s_add_i32 s65, s65, 2
	s_add_u32 s44, s44, 0x100
	s_addc_u32 s45, s45, 0
	s_add_u32 s63, s63, 0x100
	s_addc_u32 s64, s64, 0
	s_cmp_gt_u32 s65, 13
	s_cbranch_scc0 .LBB0_787
	s_and_b64 vcc, exec, s[12:13]
	s_cbranch_vccz .LBB0_790
	s_barrier

; #define PG8_STAGE_T(bufoff, gbase, voff, AUX) do { _Pragma("unroll") for (int _i = 0; _i < 2; ++_i) \
;         __builtin_amdgcn_global_load_lds((const unsigned*)((const char*)(gbase) + (voff)[_i]), (PG8_LAS unsigned*)(lds + (bufoff) + ldsw + _i * 8192), 16, 0, AUX); } while (0)
; #define PG8_LDA(dst, b, h) do { _Pragma("unroll") for (int m = 0; m < 4; ++m) _Pragma("unroll") for (int k = 0; k < 2; ++k) dst[m][k] = *(const PG8_LAS bf16x8*)(lds + PG8_SA(b, h) + aoff + m * 2048 + k * 1024); } while (0)
; #define PG8_LDB(dst, b, h) do { _Pragma("unroll") for (int n = 0; n < 2; ++n) _Pragma("unroll") for (int k = 0; k < 2; ++k) dst[n][k] = *(const PG8_LAS bf16x8*)(lds + PG8_SB(b, h) + boff + n * 2048 + k * 1024); } while (0)
; #define PG8_MMA(ai, bj, At, Bt) do { __builtin_amdgcn_s_setprio(1); _Pragma("unroll") for (int m = 0; m < 4; ++m) _Pragma("unroll") for (int n = 0; n < 2; ++n) _Pragma("unroll") for (int k = 0; k < 2; ++k) \
;         acc[ai][bj][m][n] = __builtin_amdgcn_mfma_f32_16x16x32_bf16(Bt[n][k], At[m][k], acc[ai][bj][m][n], 0, 0, 0); __builtin_amdgcn_s_setprio(0); } while (0)
; #define PG8_WAIT_V(n) asm volatile("s_waitcnt vmcnt(" #n ")" ::: "memory")
;     ...
;             const bool last = (t == nt - 2);
;             const char* a1 = cA + (ptrdiff_t)(t + 1) * ck;
;             const char* a2 = last ? nA : cA + (ptrdiff_t)(t + 2) * ck; const char* b2 = last ? nB : cB + (ptrdiff_t)(t + 2) * ck;
;             const ptrdiff_t k3 = last ? nk : ck;
;             const char* a3 = a2 + k3; const char* b3 = b2 + k3;
;             if (last && has_next) S.a_ready(nxt);
;             if constexpr (SP2) {
;             int pei = 0; if constexpr (PEEL) { pei = __builtin_amdgcn_readfirstlane((t == 0 && ui > 0) ? 1 : 0); asm volatile("" : "+s"(pei)); }
;             const bool pe = pei != 0;
;             PG8_LDB(B0, 0, 0); PG8_LDB(B1, 0, 1); PG8_SCHED; PG8_LDA(At, 0, 0); if (!pe) { PG8_STAGE_T(PG8_SA(1, 1), a1 + hstep, voffA, AUX_A); }
;             if (!pe) { PG8_WAIT_V(8); } PG8_WAIT_L(0); PG8_BAR; PG8_MMA(0, 0, At, B0); PG8_MMA(0, 1, At, B1); PG8_BAR; PG8_SCHED;
;             PG8_LDA(At, 0, 1); PG8_STAGE_T(PG8_SB(0, 0), b2, voffB, AUX_B); PG8_STAGE_T(PG8_SB(0, 1), b2 + hstep, voffB, AUX_B); PG8_STAGE_T(PG8_SA(0, 0), a2, voffA, AUX_A);
;             if (!pe) { PG8_WAIT_V(8); } PG8_WAIT_L(0); PG8_BAR; PG8_MMA(1, 0, At, B0); PG8_MMA(1, 1, At, B1); PG8_BAR; PG8_SCHED;
.LBB0_811:
	ds_read_b128 v[128:131], v183
	ds_read_b128 v[132:135], v183 offset:1024
	ds_read_b128 v[136:139], v183 offset:2048
	ds_read_b128 v[140:143], v183 offset:3072
	ds_read_b128 v[144:147], v184
	ds_read_b128 v[148:151], v184 offset:1024
	ds_read_b128 v[168:171], v184 offset:2048
	ds_read_b128 v[172:175], v184 offset:3072
	s_add_u32 s48, s46, 0xfffc0080
	s_addc_u32 s49, s47, -1
	s_cmp_eq_u32 s67, 12
	s_cselect_b32 s51, s37, s49
	s_cselect_b32 s50, s63, s48
	s_cselect_b32 s49, s39, s66
	s_cselect_b32 s48, s64, s65
	v_lshl_add_u64 v[216:217], s[46:47], 0, v[160:161]
	s_add_i32 m0, s45, 0xc000
	ds_read_b128 v[176:179], v185
	ds_read_b128 v[186:189], v185 offset:1024
	ds_read_b128 v[190:193], v185 offset:2048
	ds_read_b128 v[196:199], v185 offset:3072
	ds_read_b128 v[200:203], v185 offset:4096
	ds_read_b128 v[204:207], v185 offset:5120
	ds_read_b128 v[208:211], v185 offset:6144
	ds_read_b128 v[212:215], v185 offset:7168
	global_load_lds_dwordx4 v[216:217], off
	v_lshl_add_u64 v[216:217], s[46:47], 0, v[162:163]
	s_add_i32 m0, s45, 0xe000
	s_nop 0
	global_load_lds_dwordx4 v[216:217], off
	s_waitcnt vmcnt(8)
	s_waitcnt lgkmcnt(0)
	s_barrier
	s_waitcnt lgkmcnt(0)
	v_mfma_f32_16x16x32_bf16 v[124:127], v[128:131], v[176:179], v[124:127]
	v_mfma_f32_16x16x32_bf16 v[120:123], v[136:139], v[176:179], v[120:123]
	v_mfma_f32_16x16x32_bf16 v[108:111], v[128:131], v[190:193], v[108:111]
	v_mfma_f32_16x16x32_bf16 v[104:107], v[136:139], v[190:193], v[104:107]
	v_mfma_f32_16x16x32_bf16 v[92:95], v[128:131], v[200:203], v[92:95]
	v_mfma_f32_16x16x32_bf16 v[88:91], v[136:139], v[200:203], v[88:91]
	v_mfma_f32_16x16x32_bf16 v[76:79], v[128:131], v[208:211], v[76:79]
	v_mfma_f32_16x16x32_bf16 v[72:75], v[136:139], v[208:211], v[72:75]
	v_mfma_f32_16x16x32_bf16 v[124:127], v[132:135], v[186:189], v[124:127]
	v_mfma_f32_16x16x32_bf16 v[120:123], v[140:143], v[186:189], v[120:123]
	v_mfma_f32_16x16x32_bf16 v[108:111], v[132:135], v[196:199], v[108:111]
	v_mfma_f32_16x16x32_bf16 v[104:107], v[140:143], v[196:199], v[104:107]
	v_mfma_f32_16x16x32_bf16 v[92:95], v[132:135], v[204:207], v[92:95]
	v_mfma_f32_16x16x32_bf16 v[88:91], v[140:143], v[204:207], v[88:91]
	v_mfma_f32_16x16x32_bf16 v[76:79], v[132:135], v[212:215], v[76:79]
	v_mfma_f32_16x16x32_bf16 v[72:75], v[140:143], v[212:215], v[72:75]
	v_mfma_f32_16x16x32_bf16 v[116:119], v[144:147], v[176:179], v[116:119]
	v_mfma_f32_16x16x32_bf16 v[112:115], v[168:171], v[176:179], v[112:115]
	v_mfma_f32_16x16x32_bf16 v[100:103], v[144:147], v[190:193], v[100:103]
	v_mfma_f32_16x16x32_bf16 v[96:99], v[168:171], v[190:193], v[96:99]
	v_mfma_f32_16x16x32_bf16 v[84:87], v[144:147], v[200:203], v[84:87]
	v_mfma_f32_16x16x32_bf16 v[80:83], v[168:171], v[200:203], v[80:83]
	v_mfma_f32_16x16x32_bf16 v[68:71], v[144:147], v[208:211], v[68:71]
	v_mfma_f32_16x16x32_bf16 v[64:67], v[168:171], v[208:211], v[64:67]
	v_mfma_f32_16x16x32_bf16 v[116:119], v[148:151], v[186:189], v[116:119]
	v_mfma_f32_16x16x32_bf16 v[112:115], v[172:175], v[186:189], v[112:115]
	v_mfma_f32_16x16x32_bf16 v[100:103], v[148:151], v[196:199], v[100:103]
	v_mfma_f32_16x16x32_bf16 v[96:99], v[172:175], v[196:199], v[96:99]
	v_mfma_f32_16x16x32_bf16 v[84:87], v[148:151], v[204:207], v[84:87]
	v_mfma_f32_16x16x32_bf16 v[80:83], v[172:175], v[204:207], v[80:83]
	v_mfma_f32_16x16x32_bf16 v[68:71], v[148:151], v[212:215], v[68:71]
	s_setprio 2
	s_barrier
	v_mfma_f32_16x16x32_bf16 v[64:67], v[172:175], v[212:215], v[64:67]
	s_setprio 0
	s_add_i32 s68, s60, s52
	v_lshl_add_u64 v[216:217], s[48:49], 0, v[154:155]
	s_mov_b32 m0, s68
	ds_read_b128 v[176:179], v185 offset:16384
	ds_read_b128 v[186:189], v185 offset:17408
	ds_read_b128 v[190:193], v185 offset:18432
	ds_read_b128 v[196:199], v185 offset:19456
	ds_read_b128 v[200:203], v185 offset:20480
	ds_read_b128 v[204:207], v185 offset:21504
	ds_read_b128 v[208:211], v185 offset:22528
	ds_read_b128 v[212:215], v185 offset:23552
	global_load_lds_dwordx4 v[216:217], off
	s_add_i32 m0, s68, 0x2000
	s_add_u32 s68, s48, 0x40000
	v_lshl_add_u64 v[218:219], s[48:49], 0, v[158:159]
	s_addc_u32 s69, s49, 0
	s_add_i32 s70, s61, s52
	global_load_lds_dwordx4 v[218:219], off
	v_lshl_add_u64 v[220:221], s[68:69], 0, v[154:155]
	s_mov_b32 m0, s70
	v_lshl_add_u64 v[222:223], s[50:51], 0, v[156:157]
	global_load_lds_dwordx4 v[220:221], off
	v_lshl_add_u64 v[220:221], s[68:69], 0, v[158:159]
	s_add_i32 m0, s70, 0x2000
	s_nop 0
	global_load_lds_dwordx4 v[220:221], off
	v_lshl_add_u64 v[220:221], s[50:51], 0, v[152:153]
	s_mov_b32 m0, s45
	s_nop 0
	global_load_lds_dwordx4 v[220:221], off
	s_mov_b32 m0, s53
	s_nop 0
	global_load_lds_dwordx4 v[222:223], off
	s_waitcnt vmcnt(8)
	s_waitcnt lgkmcnt(0)
	s_barrier
; #define PG8_STAGE_T(bufoff, gbase, voff, AUX) do { _Pragma("unroll") for (int _i = 0; _i < 2; ++_i) \
;         __builtin_amdgcn_global_load_lds((const unsigned*)((const char*)(gbase) + (voff)[_i]), (PG8_LAS unsigned*)(lds + (bufoff) + ldsw + _i * 8192), 16, 0, AUX); } while (0)
; #define PG8_LDA(dst, b, h) do { _Pragma("unroll") for (int m = 0; m < 4; ++m) _Pragma("unroll") for (int k = 0; k < 2; ++k) dst[m][k] = *(const PG8_LAS bf16x8*)(lds + PG8_SA(b, h) + aoff + m * 2048 + k * 1024); } while (0)
; #define PG8_LDB(dst, b, h) do { _Pragma("unroll") for (int n = 0; n < 2; ++n) _Pragma("unroll") for (int k = 0; k < 2; ++k) dst[n][k] = *(const PG8_LAS bf16x8*)(lds + PG8_SB(b, h) + boff + n * 2048 + k * 1024); } while (0)
; #define PG8_MMA(ai, bj, At, Bt) do { __builtin_amdgcn_s_setprio(1); _Pragma("unroll") for (int m = 0; m < 4; ++m) _Pragma("unroll") for (int n = 0; n < 2; ++n) _Pragma("unroll") for (int k = 0; k < 2; ++k) \
;         acc[ai][bj][m][n] = __builtin_amdgcn_mfma_f32_16x16x32_bf16(Bt[n][k], At[m][k], acc[ai][bj][m][n], 0, 0, 0); __builtin_amdgcn_s_setprio(0); } while (0)
; #define PG8_WAIT_V(n) asm volatile("s_waitcnt vmcnt(" #n ")" ::: "memory")
; #define PG8_WAIT_L(n) asm volatile("s_waitcnt lgkmcnt(" #n ")" ::: "memory")
; #define PG8_BAR __builtin_amdgcn_s_barrier()
; #define PG8_SCHED __builtin_amdgcn_sched_barrier(0)
;     ...
;             if (!pe) { PG8_WAIT_V(8); } PG8_WAIT_L(0); PG8_BAR; PG8_MMA(1, 0, At, B0); PG8_MMA(1, 1, At, B1); PG8_BAR; PG8_SCHED;
;             PG8_LDB(B0, 1, 0); PG8_LDB(B1, 1, 1); PG8_SCHED; PG8_LDA(At, 1, 0); PG8_STAGE_T(PG8_SA(0, 1), a2 + hstep, voffA, AUX_A);
;             if (!pe) { PG8_WAIT_V(8); } PG8_WAIT_L(0); PG8_BAR; PG8_MMA(0, 0, At, B0); PG8_MMA(0, 1, At, B1); PG8_BAR; PG8_SCHED;
	s_waitcnt lgkmcnt(0)
	v_mfma_f32_16x16x32_bf16 v[60:63], v[128:131], v[176:179], v[60:63]
	v_mfma_f32_16x16x32_bf16 v[56:59], v[136:139], v[176:179], v[56:59]
	v_mfma_f32_16x16x32_bf16 v[44:47], v[128:131], v[190:193], v[44:47]
	v_mfma_f32_16x16x32_bf16 v[40:43], v[136:139], v[190:193], v[40:43]
	v_mfma_f32_16x16x32_bf16 v[28:31], v[128:131], v[200:203], v[28:31]
	v_mfma_f32_16x16x32_bf16 v[24:27], v[136:139], v[200:203], v[24:27]
	v_mfma_f32_16x16x32_bf16 v[12:15], v[128:131], v[208:211], v[12:15]
	v_mfma_f32_16x16x32_bf16 v[8:11], v[136:139], v[208:211], v[8:11]
	v_mfma_f32_16x16x32_bf16 v[60:63], v[132:135], v[186:189], v[60:63]
	v_mfma_f32_16x16x32_bf16 v[56:59], v[140:143], v[186:189], v[56:59]
	v_mfma_f32_16x16x32_bf16 v[44:47], v[132:135], v[196:199], v[44:47]
	v_mfma_f32_16x16x32_bf16 v[40:43], v[140:143], v[196:199], v[40:43]
	v_mfma_f32_16x16x32_bf16 v[28:31], v[132:135], v[204:207], v[28:31]
	v_mfma_f32_16x16x32_bf16 v[24:27], v[140:143], v[204:207], v[24:27]
	v_mfma_f32_16x16x32_bf16 v[12:15], v[132:135], v[212:215], v[12:15]
	v_mfma_f32_16x16x32_bf16 v[8:11], v[140:143], v[212:215], v[8:11]
	v_mfma_f32_16x16x32_bf16 v[52:55], v[144:147], v[176:179], v[52:55]
	v_mfma_f32_16x16x32_bf16 v[48:51], v[168:171], v[176:179], v[48:51]
	v_mfma_f32_16x16x32_bf16 v[36:39], v[144:147], v[190:193], v[36:39]
	v_mfma_f32_16x16x32_bf16 v[32:35], v[168:171], v[190:193], v[32:35]
	v_mfma_f32_16x16x32_bf16 v[20:23], v[144:147], v[200:203], v[20:23]
	v_mfma_f32_16x16x32_bf16 v[16:19], v[168:171], v[200:203], v[16:19]
	v_mfma_f32_16x16x32_bf16 v[4:7], v[144:147], v[208:211], v[4:7]
	v_mfma_f32_16x16x32_bf16 v[0:3], v[168:171], v[208:211], v[0:3]
	v_mfma_f32_16x16x32_bf16 v[52:55], v[148:151], v[186:189], v[52:55]
	v_mfma_f32_16x16x32_bf16 v[48:51], v[172:175], v[186:189], v[48:51]
	v_mfma_f32_16x16x32_bf16 v[36:39], v[148:151], v[196:199], v[36:39]
	v_mfma_f32_16x16x32_bf16 v[32:35], v[172:175], v[196:199], v[32:35]
	v_mfma_f32_16x16x32_bf16 v[20:23], v[148:151], v[204:207], v[20:23]
	v_mfma_f32_16x16x32_bf16 v[16:19], v[172:175], v[204:207], v[16:19]
	v_mfma_f32_16x16x32_bf16 v[4:7], v[148:151], v[212:215], v[4:7]
	s_setprio 2
	s_barrier
	v_mfma_f32_16x16x32_bf16 v[0:3], v[172:175], v[212:215], v[0:3]
	s_setprio 0
	s_add_i32 s68, 0, 0x18000
	s_add_i32 s69, 0, 0x1c000
	v_add_u32_e32 v140, s68, v181
	v_add_u32_e32 v172, s69, v181
	ds_read_b128 v[128:131], v140
	ds_read_b128 v[132:135], v140 offset:1024
	ds_read_b128 v[136:139], v140 offset:2048
	ds_read_b128 v[140:143], v140 offset:3072
	ds_read_b128 v[144:147], v172
	ds_read_b128 v[148:151], v172 offset:1024
	ds_read_b128 v[168:171], v172 offset:2048
	ds_read_b128 v[172:175], v172 offset:3072
	s_add_u32 s50, s50, 0x40000
	s_addc_u32 s51, s51, 0
	s_mov_b32 m0, s54
	v_lshl_add_u64 v[224:225], s[50:51], 0, v[152:153]
	ds_read_b128 v[176:179], v185 offset:32768
	ds_read_b128 v[186:189], v185 offset:33792
	ds_read_b128 v[190:193], v185 offset:34816
	ds_read_b128 v[196:199], v185 offset:35840
	ds_read_b128 v[200:203], v185 offset:36864
	ds_read_b128 v[204:207], v185 offset:37888
	ds_read_b128 v[208:211], v185 offset:38912
	ds_read_b128 v[212:215], v185 offset:39936
	global_load_lds_dwordx4 v[224:225], off
	v_lshl_add_u64 v[224:225], s[50:51], 0, v[156:157]
	s_mov_b32 m0, s55
	s_nop 0
	global_load_lds_dwordx4 v[224:225], off
	s_waitcnt vmcnt(8)
	s_waitcnt lgkmcnt(0)
	s_barrier
	s_waitcnt lgkmcnt(0)
	v_mfma_f32_16x16x32_bf16 v[124:127], v[128:131], v[176:179], v[124:127]
	v_mfma_f32_16x16x32_bf16 v[120:123], v[136:139], v[176:179], v[120:123]
	v_mfma_f32_16x16x32_bf16 v[108:111], v[128:131], v[190:193], v[108:111]
	v_mfma_f32_16x16x32_bf16 v[104:107], v[136:139], v[190:193], v[104:107]
	v_mfma_f32_16x16x32_bf16 v[92:95], v[128:131], v[200:203], v[92:95]
	v_mfma_f32_16x16x32_bf16 v[88:91], v[136:139], v[200:203], v[88:91]
	v_mfma_f32_16x16x32_bf16 v[76:79], v[128:131], v[208:211], v[76:79]
	v_mfma_f32_16x16x32_bf16 v[72:75], v[136:139], v[208:211], v[72:75]
	v_mfma_f32_16x16x32_bf16 v[124:127], v[132:135], v[186:189], v[124:127]
	v_mfma_f32_16x16x32_bf16 v[120:123], v[140:143], v[186:189], v[120:123]
	v_mfma_f32_16x16x32_bf16 v[108:111], v[132:135], v[196:199], v[108:111]
	v_mfma_f32_16x16x32_bf16 v[104:107], v[140:143], v[196:199], v[104:107]
	v_mfma_f32_16x16x32_bf16 v[92:95], v[132:135], v[204:207], v[92:95]
	v_mfma_f32_16x16x32_bf16 v[88:91], v[140:143], v[204:207], v[88:91]
	v_mfma_f32_16x16x32_bf16 v[76:79], v[132:135], v[212:215], v[76:79]
	v_mfma_f32_16x16x32_bf16 v[72:75], v[140:143], v[212:215], v[72:75]
	v_mfma_f32_16x16x32_bf16 v[116:119], v[144:147], v[176:179], v[116:119]
	v_mfma_f32_16x16x32_bf16 v[112:115], v[168:171], v[176:179], v[112:115]
	v_mfma_f32_16x16x32_bf16 v[100:103], v[144:147], v[190:193], v[100:103]
	v_mfma_f32_16x16x32_bf16 v[96:99], v[168:171], v[190:193], v[96:99]
	v_mfma_f32_16x16x32_bf16 v[84:87], v[144:147], v[200:203], v[84:87]
	v_mfma_f32_16x16x32_bf16 v[80:83], v[168:171], v[200:203], v[80:83]
	v_mfma_f32_16x16x32_bf16 v[68:71], v[144:147], v[208:211], v[68:71]
	v_mfma_f32_16x16x32_bf16 v[64:67], v[168:171], v[208:211], v[64:67]
	v_mfma_f32_16x16x32_bf16 v[116:119], v[148:151], v[186:189], v[116:119]
	v_mfma_f32_16x16x32_bf16 v[112:115], v[172:175], v[186:189], v[112:115]
	v_mfma_f32_16x16x32_bf16 v[100:103], v[148:151], v[196:199], v[100:103]
	v_mfma_f32_16x16x32_bf16 v[96:99], v[172:175], v[196:199], v[96:99]
	v_mfma_f32_16x16x32_bf16 v[84:87], v[148:151], v[204:207], v[84:87]
	v_mfma_f32_16x16x32_bf16 v[80:83], v[172:175], v[204:207], v[80:83]
	v_mfma_f32_16x16x32_bf16 v[68:71], v[148:151], v[212:215], v[68:71]
	s_setprio 2
	s_barrier
; #define PG8_STAGE_T(bufoff, gbase, voff, AUX) do { _Pragma("unroll") for (int _i = 0; _i < 2; ++_i) \
;         __builtin_amdgcn_global_load_lds((const unsigned*)((const char*)(gbase) + (voff)[_i]), (PG8_LAS unsigned*)(lds + (bufoff) + ldsw + _i * 8192), 16, 0, AUX); } while (0)
; #define PG8_LDA(dst, b, h) do { _Pragma("unroll") for (int m = 0; m < 4; ++m) _Pragma("unroll") for (int k = 0; k < 2; ++k) dst[m][k] = *(const PG8_LAS bf16x8*)(lds + PG8_SA(b, h) + aoff + m * 2048 + k * 1024); } while (0)
; #define PG8_MMA(ai, bj, At, Bt) do { __builtin_amdgcn_s_setprio(1); _Pragma("unroll") for (int m = 0; m < 4; ++m) _Pragma("unroll") for (int n = 0; n < 2; ++n) _Pragma("unroll") for (int k = 0; k < 2; ++k) \
;         acc[ai][bj][m][n] = __builtin_amdgcn_mfma_f32_16x16x32_bf16(Bt[n][k], At[m][k], acc[ai][bj][m][n], 0, 0, 0); __builtin_amdgcn_s_setprio(0); } while (0)
; #define PG8_WAIT_V(n) asm volatile("s_waitcnt vmcnt(" #n ")" ::: "memory")
; #define PG8_WAIT_L(n) asm volatile("s_waitcnt lgkmcnt(" #n ")" ::: "memory")
; #define PG8_BAR __builtin_amdgcn_s_barrier()
; #define PG8_SCHED __builtin_amdgcn_sched_barrier(0)
;     ...
;             if (!pe) { PG8_WAIT_V(8); } PG8_WAIT_L(0); PG8_BAR; PG8_MMA(0, 0, At, B0); PG8_MMA(0, 1, At, B1); PG8_BAR; PG8_SCHED;
;             PG8_LDA(At, 1, 1); PG8_STAGE_T(PG8_SB(1, 0), b3, voffB, AUX_B); PG8_STAGE_T(PG8_SB(1, 1), b3 + hstep, voffB, AUX_B); PG8_STAGE_T(PG8_SA(1, 0), a3, voffA, AUX_A);
;             PG8_WAIT_V(8); PG8_WAIT_L(0); PG8_BAR; PG8_MMA(1, 0, At, B0); PG8_MMA(1, 1, At, B1); PG8_BAR; PG8_SCHED;
;     ...
;         if constexpr (ALIGN_EPI) { if (wr == 0) PG8_BAR; }
	v_mfma_f32_16x16x32_bf16 v[64:67], v[172:175], v[212:215], v[64:67]
	s_setprio 0
	s_add_i32 s50, s68, s52
	v_lshl_add_u64 v[216:217], v[216:217], 0, s[10:11]
	s_mov_b32 m0, s50
	ds_read_b128 v[176:179], v185 offset:49152
	ds_read_b128 v[186:189], v185 offset:50176
	ds_read_b128 v[190:193], v185 offset:51200
	ds_read_b128 v[196:199], v185 offset:52224
	ds_read_b128 v[200:203], v185 offset:53248
	ds_read_b128 v[204:207], v185 offset:54272
	ds_read_b128 v[208:211], v185 offset:55296
	ds_read_b128 v[212:215], v185 offset:56320
	global_load_lds_dwordx4 v[216:217], off
	s_add_i32 m0, s50, 0x2000
	s_add_u32 s48, s48, 0x40080
	v_lshl_add_u64 v[216:217], v[218:219], 0, s[10:11]
	s_addc_u32 s49, s49, 0
	s_add_i32 s50, s69, s52
	global_load_lds_dwordx4 v[216:217], off
	v_lshl_add_u64 v[216:217], s[48:49], 0, v[154:155]
	s_mov_b32 m0, s50
	s_nop 0
	global_load_lds_dwordx4 v[216:217], off
	v_lshl_add_u64 v[216:217], s[48:49], 0, v[158:159]
	s_add_i32 m0, s50, 0x2000
	s_nop 0
	global_load_lds_dwordx4 v[216:217], off
	v_lshl_add_u64 v[216:217], v[220:221], 0, s[10:11]
	s_mov_b32 m0, s57
	s_nop 0
	global_load_lds_dwordx4 v[216:217], off
	v_lshl_add_u64 v[216:217], v[222:223], 0, s[10:11]
	s_mov_b32 m0, s58
	s_nop 0
	global_load_lds_dwordx4 v[216:217], off
	s_waitcnt vmcnt(8)
	s_waitcnt lgkmcnt(0)
	s_barrier
	s_waitcnt lgkmcnt(0)
	v_mfma_f32_16x16x32_bf16 v[60:63], v[128:131], v[176:179], v[60:63]
	v_mfma_f32_16x16x32_bf16 v[56:59], v[136:139], v[176:179], v[56:59]
	v_mfma_f32_16x16x32_bf16 v[44:47], v[128:131], v[190:193], v[44:47]
	v_mfma_f32_16x16x32_bf16 v[40:43], v[136:139], v[190:193], v[40:43]
	v_mfma_f32_16x16x32_bf16 v[28:31], v[128:131], v[200:203], v[28:31]
	v_mfma_f32_16x16x32_bf16 v[24:27], v[136:139], v[200:203], v[24:27]
	v_mfma_f32_16x16x32_bf16 v[12:15], v[128:131], v[208:211], v[12:15]
	v_mfma_f32_16x16x32_bf16 v[8:11], v[136:139], v[208:211], v[8:11]
	v_mfma_f32_16x16x32_bf16 v[60:63], v[132:135], v[186:189], v[60:63]
	v_mfma_f32_16x16x32_bf16 v[56:59], v[140:143], v[186:189], v[56:59]
	v_mfma_f32_16x16x32_bf16 v[44:47], v[132:135], v[196:199], v[44:47]
	v_mfma_f32_16x16x32_bf16 v[40:43], v[140:143], v[196:199], v[40:43]
	v_mfma_f32_16x16x32_bf16 v[28:31], v[132:135], v[204:207], v[28:31]
	v_mfma_f32_16x16x32_bf16 v[24:27], v[140:143], v[204:207], v[24:27]
	v_mfma_f32_16x16x32_bf16 v[12:15], v[132:135], v[212:215], v[12:15]
	v_mfma_f32_16x16x32_bf16 v[8:11], v[140:143], v[212:215], v[8:11]
	v_mfma_f32_16x16x32_bf16 v[52:55], v[144:147], v[176:179], v[52:55]
	v_mfma_f32_16x16x32_bf16 v[48:51], v[168:171], v[176:179], v[48:51]
	v_mfma_f32_16x16x32_bf16 v[36:39], v[144:147], v[190:193], v[36:39]
	v_mfma_f32_16x16x32_bf16 v[32:35], v[168:171], v[190:193], v[32:35]
	v_mfma_f32_16x16x32_bf16 v[20:23], v[144:147], v[200:203], v[20:23]
	v_mfma_f32_16x16x32_bf16 v[16:19], v[168:171], v[200:203], v[16:19]
	v_mfma_f32_16x16x32_bf16 v[4:7], v[144:147], v[208:211], v[4:7]
	v_mfma_f32_16x16x32_bf16 v[0:3], v[168:171], v[208:211], v[0:3]
	v_mfma_f32_16x16x32_bf16 v[52:55], v[148:151], v[186:189], v[52:55]
	v_mfma_f32_16x16x32_bf16 v[48:51], v[172:175], v[186:189], v[48:51]
	v_mfma_f32_16x16x32_bf16 v[36:39], v[148:151], v[196:199], v[36:39]
	v_mfma_f32_16x16x32_bf16 v[32:35], v[172:175], v[196:199], v[32:35]
	v_mfma_f32_16x16x32_bf16 v[20:23], v[148:151], v[204:207], v[20:23]
	v_mfma_f32_16x16x32_bf16 v[16:19], v[172:175], v[204:207], v[16:19]
	v_mfma_f32_16x16x32_bf16 v[4:7], v[148:151], v[212:215], v[4:7]
	s_setprio 2
	s_barrier
	v_mfma_f32_16x16x32_bf16 v[0:3], v[172:175], v[212:215], v[0:3]
	s_setprio 0
	s_add_i32 s67, s67, 2
	s_add_u32 s46, s46, 0x100
	s_addc_u32 s47, s47, 0
	s_add_u32 s65, s65, 0x100
	s_addc_u32 s66, s66, 0
	s_cmp_gt_u32 s67, 13
	s_cbranch_scc0 .LBB0_811
	s_and_b64 vcc, exec, s[12:13]
	s_cbranch_vccz .LBB0_814
	s_barrier

; #define PG8_STAGE_T(bufoff, gbase, voff, AUX) do { _Pragma("unroll") for (int _i = 0; _i < 2; ++_i) \
;         __builtin_amdgcn_global_load_lds((const unsigned*)((const char*)(gbase) + (voff)[_i]), (PG8_LAS unsigned*)(lds + (bufoff) + ldsw + _i * 8192), 16, 0, AUX); } while (0)
; #define PG8_LDA(dst, b, h) do { _Pragma("unroll") for (int m = 0; m < 4; ++m) _Pragma("unroll") for (int k = 0; k < 2; ++k) dst[m][k] = *(const PG8_LAS bf16x8*)(lds + PG8_SA(b, h) + aoff + m * 2048 + k * 1024); } while (0)
; #define PG8_LDB(dst, b, h) do { _Pragma("unroll") for (int n = 0; n < 2; ++n) _Pragma("unroll") for (int k = 0; k < 2; ++k) dst[n][k] = *(const PG8_LAS bf16x8*)(lds + PG8_SB(b, h) + boff + n * 2048 + k * 1024); } while (0)
; #define PG8_MMA(ai, bj, At, Bt) do { __builtin_amdgcn_s_setprio(1); _Pragma("unroll") for (int m = 0; m < 4; ++m) _Pragma("unroll") for (int n = 0; n < 2; ++n) _Pragma("unroll") for (int k = 0; k < 2; ++k) \
;         acc[ai][bj][m][n] = __builtin_amdgcn_mfma_f32_16x16x32_bf16(Bt[n][k], At[m][k], acc[ai][bj][m][n], 0, 0, 0); __builtin_amdgcn_s_setprio(0); } while (0)
; #define PG8_WAIT_V(n) asm volatile("s_waitcnt vmcnt(" #n ")" ::: "memory")
;     ...
;             const bool last = (t == nt - 2);
;             const char* a1 = cA + (ptrdiff_t)(t + 1) * ck;
;             const char* a2 = last ? nA : cA + (ptrdiff_t)(t + 2) * ck; const char* b2 = last ? nB : cB + (ptrdiff_t)(t + 2) * ck;
;             const ptrdiff_t k3 = last ? nk : ck;
;             const char* a3 = a2 + k3; const char* b3 = b2 + k3;
;             if (last && has_next) S.a_ready(nxt);
;             if constexpr (SP2) {
;             int pei = 0; if constexpr (PEEL) { pei = __builtin_amdgcn_readfirstlane((t == 0 && ui > 0) ? 1 : 0); asm volatile("" : "+s"(pei)); }
;             const bool pe = pei != 0;
;             PG8_LDB(B0, 0, 0); PG8_LDB(B1, 0, 1); PG8_SCHED; PG8_LDA(At, 0, 0); if (!pe) { PG8_STAGE_T(PG8_SA(1, 1), a1 + hstep, voffA, AUX_A); }
;             if (!pe) { PG8_WAIT_V(8); } PG8_WAIT_L(0); PG8_BAR; PG8_MMA(0, 0, At, B0); PG8_MMA(0, 1, At, B1); PG8_BAR; PG8_SCHED;
;             PG8_LDA(At, 0, 1); PG8_STAGE_T(PG8_SB(0, 0), b2, voffB, AUX_B); PG8_STAGE_T(PG8_SB(0, 1), b2 + hstep, voffB, AUX_B); PG8_STAGE_T(PG8_SA(0, 0), a2, voffA, AUX_A);
;             if (!pe) { PG8_WAIT_V(8); } PG8_WAIT_L(0); PG8_BAR; PG8_MMA(1, 0, At, B0); PG8_MMA(1, 1, At, B1); PG8_BAR; PG8_SCHED;
.LBB0_886:
	ds_read_b128 v[154:157], v149
	s_waitcnt lgkmcnt(0)
	ds_read_b128 v[158:161], v149 offset:1024
	ds_read_b128 v[162:165], v149 offset:2048
	ds_read_b128 v[166:169], v149 offset:3072
	ds_read_b128 v[170:173], v150
	ds_read_b128 v[174:177], v150 offset:1024
	ds_read_b128 v[178:181], v150 offset:2048
	ds_read_b128 v[182:185], v150 offset:3072
	s_add_u32 s44, s42, 0xfffc0080
	s_addc_u32 s45, s43, -1
	s_cmp_eq_u32 s63, 12
	s_cselect_b32 s47, s15, s45
	s_cselect_b32 s46, s59, s44
	s_cselect_b32 s45, s25, s62
	s_cselect_b32 s44, s60, s61
	v_lshl_add_u64 v[144:145], s[42:43], 0, v[136:137]
	s_add_i32 m0, s49, 0xc000
	ds_read_b128 v[186:189], v151
	ds_read_b128 v[190:193], v151 offset:1024
	ds_read_b128 v[196:199], v151 offset:2048
	ds_read_b128 v[200:203], v151 offset:3072
	ds_read_b128 v[204:207], v151 offset:4096
	ds_read_b128 v[208:211], v151 offset:5120
	ds_read_b128 v[212:215], v151 offset:6144
	ds_read_b128 v[216:219], v151 offset:7168
	global_load_lds_dwordx4 v[144:145], off
	v_lshl_add_u64 v[144:145], s[42:43], 0, v[138:139]
	s_add_i32 m0, s49, 0xe000
	s_nop 0
	global_load_lds_dwordx4 v[144:145], off
	s_waitcnt vmcnt(8)
	s_waitcnt lgkmcnt(0)
	s_barrier
	s_waitcnt lgkmcnt(0)
	v_mfma_f32_16x16x32_bf16 v[124:127], v[154:157], v[186:189], v[124:127]
	v_mfma_f32_16x16x32_bf16 v[120:123], v[162:165], v[186:189], v[120:123]
	v_mfma_f32_16x16x32_bf16 v[108:111], v[154:157], v[196:199], v[108:111]
	v_mfma_f32_16x16x32_bf16 v[104:107], v[162:165], v[196:199], v[104:107]
	v_mfma_f32_16x16x32_bf16 v[92:95], v[154:157], v[204:207], v[92:95]
	v_mfma_f32_16x16x32_bf16 v[88:91], v[162:165], v[204:207], v[88:91]
	v_mfma_f32_16x16x32_bf16 v[76:79], v[154:157], v[212:215], v[76:79]
	v_mfma_f32_16x16x32_bf16 v[72:75], v[162:165], v[212:215], v[72:75]
	v_mfma_f32_16x16x32_bf16 v[124:127], v[158:161], v[190:193], v[124:127]
	v_mfma_f32_16x16x32_bf16 v[120:123], v[166:169], v[190:193], v[120:123]
	v_mfma_f32_16x16x32_bf16 v[108:111], v[158:161], v[200:203], v[108:111]
	v_mfma_f32_16x16x32_bf16 v[104:107], v[166:169], v[200:203], v[104:107]
	v_mfma_f32_16x16x32_bf16 v[92:95], v[158:161], v[208:211], v[92:95]
	v_mfma_f32_16x16x32_bf16 v[88:91], v[166:169], v[208:211], v[88:91]
	v_mfma_f32_16x16x32_bf16 v[76:79], v[158:161], v[216:219], v[76:79]
	v_mfma_f32_16x16x32_bf16 v[72:75], v[166:169], v[216:219], v[72:75]
	v_mfma_f32_16x16x32_bf16 v[116:119], v[170:173], v[186:189], v[116:119]
	v_mfma_f32_16x16x32_bf16 v[112:115], v[178:181], v[186:189], v[112:115]
	v_mfma_f32_16x16x32_bf16 v[100:103], v[170:173], v[196:199], v[100:103]
	v_mfma_f32_16x16x32_bf16 v[96:99], v[178:181], v[196:199], v[96:99]
	v_mfma_f32_16x16x32_bf16 v[84:87], v[170:173], v[204:207], v[84:87]
	v_mfma_f32_16x16x32_bf16 v[80:83], v[178:181], v[204:207], v[80:83]
	v_mfma_f32_16x16x32_bf16 v[68:71], v[170:173], v[212:215], v[68:71]
	v_mfma_f32_16x16x32_bf16 v[64:67], v[178:181], v[212:215], v[64:67]
	v_mfma_f32_16x16x32_bf16 v[116:119], v[174:177], v[190:193], v[116:119]
	v_mfma_f32_16x16x32_bf16 v[112:115], v[182:185], v[190:193], v[112:115]
	v_mfma_f32_16x16x32_bf16 v[100:103], v[174:177], v[200:203], v[100:103]
	v_mfma_f32_16x16x32_bf16 v[96:99], v[182:185], v[200:203], v[96:99]
	v_mfma_f32_16x16x32_bf16 v[84:87], v[174:177], v[208:211], v[84:87]
	v_mfma_f32_16x16x32_bf16 v[80:83], v[182:185], v[208:211], v[80:83]
	v_mfma_f32_16x16x32_bf16 v[68:71], v[174:177], v[216:219], v[68:71]
	s_setprio 2
	s_barrier
	v_mfma_f32_16x16x32_bf16 v[64:67], v[182:185], v[216:219], v[64:67]
	s_setprio 0
	s_add_i32 s64, s56, s48
	v_lshl_add_u64 v[144:145], s[44:45], 0, v[130:131]
	s_mov_b32 m0, s64
	ds_read_b128 v[186:189], v151 offset:16384
	ds_read_b128 v[190:193], v151 offset:17408
	ds_read_b128 v[196:199], v151 offset:18432
	ds_read_b128 v[200:203], v151 offset:19456
	ds_read_b128 v[204:207], v151 offset:20480
	ds_read_b128 v[208:211], v151 offset:21504
	ds_read_b128 v[212:215], v151 offset:22528
	ds_read_b128 v[216:219], v151 offset:23552
	global_load_lds_dwordx4 v[144:145], off
	s_add_i32 m0, s64, 0x2000
	s_add_u32 s64, s44, 0x40000
	v_lshl_add_u64 v[220:221], s[44:45], 0, v[134:135]
	s_addc_u32 s65, s45, 0
	s_add_i32 s66, s57, s48
	global_load_lds_dwordx4 v[220:221], off
	v_lshl_add_u64 v[222:223], s[64:65], 0, v[130:131]
	s_mov_b32 m0, s66
	v_lshl_add_u64 v[224:225], s[46:47], 0, v[132:133]
	global_load_lds_dwordx4 v[222:223], off
	v_lshl_add_u64 v[222:223], s[64:65], 0, v[134:135]
	s_add_i32 m0, s66, 0x2000
	s_nop 0
	global_load_lds_dwordx4 v[222:223], off
	v_lshl_add_u64 v[222:223], s[46:47], 0, v[128:129]
	s_mov_b32 m0, s49
	s_nop 0
	global_load_lds_dwordx4 v[222:223], off
	s_mov_b32 m0, s50
	s_nop 0
	global_load_lds_dwordx4 v[224:225], off
	s_waitcnt vmcnt(8)
	s_waitcnt lgkmcnt(0)
	s_barrier
; #define PG8_STAGE_T(bufoff, gbase, voff, AUX) do { _Pragma("unroll") for (int _i = 0; _i < 2; ++_i) \
;         __builtin_amdgcn_global_load_lds((const unsigned*)((const char*)(gbase) + (voff)[_i]), (PG8_LAS unsigned*)(lds + (bufoff) + ldsw + _i * 8192), 16, 0, AUX); } while (0)
; #define PG8_LDA(dst, b, h) do { _Pragma("unroll") for (int m = 0; m < 4; ++m) _Pragma("unroll") for (int k = 0; k < 2; ++k) dst[m][k] = *(const PG8_LAS bf16x8*)(lds + PG8_SA(b, h) + aoff + m * 2048 + k * 1024); } while (0)
; #define PG8_LDB(dst, b, h) do { _Pragma("unroll") for (int n = 0; n < 2; ++n) _Pragma("unroll") for (int k = 0; k < 2; ++k) dst[n][k] = *(const PG8_LAS bf16x8*)(lds + PG8_SB(b, h) + boff + n * 2048 + k * 1024); } while (0)
; #define PG8_MMA(ai, bj, At, Bt) do { __builtin_amdgcn_s_setprio(1); _Pragma("unroll") for (int m = 0; m < 4; ++m) _Pragma("unroll") for (int n = 0; n < 2; ++n) _Pragma("unroll") for (int k = 0; k < 2; ++k) \
;         acc[ai][bj][m][n] = __builtin_amdgcn_mfma_f32_16x16x32_bf16(Bt[n][k], At[m][k], acc[ai][bj][m][n], 0, 0, 0); __builtin_amdgcn_s_setprio(0); } while (0)
; #define PG8_WAIT_V(n) asm volatile("s_waitcnt vmcnt(" #n ")" ::: "memory")
; #define PG8_WAIT_L(n) asm volatile("s_waitcnt lgkmcnt(" #n ")" ::: "memory")
; #define PG8_BAR __builtin_amdgcn_s_barrier()
; #define PG8_SCHED __builtin_amdgcn_sched_barrier(0)
;     ...
;             if (!pe) { PG8_WAIT_V(8); } PG8_WAIT_L(0); PG8_BAR; PG8_MMA(1, 0, At, B0); PG8_MMA(1, 1, At, B1); PG8_BAR; PG8_SCHED;
;             PG8_LDB(B0, 1, 0); PG8_LDB(B1, 1, 1); PG8_SCHED; PG8_LDA(At, 1, 0); PG8_STAGE_T(PG8_SA(0, 1), a2 + hstep, voffA, AUX_A);
;             if (!pe) { PG8_WAIT_V(8); } PG8_WAIT_L(0); PG8_BAR; PG8_MMA(0, 0, At, B0); PG8_MMA(0, 1, At, B1); PG8_BAR; PG8_SCHED;
	s_waitcnt lgkmcnt(0)
	v_mfma_f32_16x16x32_bf16 v[60:63], v[154:157], v[186:189], v[60:63]
	v_mfma_f32_16x16x32_bf16 v[56:59], v[162:165], v[186:189], v[56:59]
	v_mfma_f32_16x16x32_bf16 v[44:47], v[154:157], v[196:199], v[44:47]
	v_mfma_f32_16x16x32_bf16 v[40:43], v[162:165], v[196:199], v[40:43]
	v_mfma_f32_16x16x32_bf16 v[28:31], v[154:157], v[204:207], v[28:31]
	v_mfma_f32_16x16x32_bf16 v[24:27], v[162:165], v[204:207], v[24:27]
	v_mfma_f32_16x16x32_bf16 v[12:15], v[154:157], v[212:215], v[12:15]
	v_mfma_f32_16x16x32_bf16 v[8:11], v[162:165], v[212:215], v[8:11]
	v_mfma_f32_16x16x32_bf16 v[60:63], v[158:161], v[190:193], v[60:63]
	v_mfma_f32_16x16x32_bf16 v[56:59], v[166:169], v[190:193], v[56:59]
	v_mfma_f32_16x16x32_bf16 v[44:47], v[158:161], v[200:203], v[44:47]
	v_mfma_f32_16x16x32_bf16 v[40:43], v[166:169], v[200:203], v[40:43]
	v_mfma_f32_16x16x32_bf16 v[28:31], v[158:161], v[208:211], v[28:31]
	v_mfma_f32_16x16x32_bf16 v[24:27], v[166:169], v[208:211], v[24:27]
	v_mfma_f32_16x16x32_bf16 v[12:15], v[158:161], v[216:219], v[12:15]
	v_mfma_f32_16x16x32_bf16 v[8:11], v[166:169], v[216:219], v[8:11]
	v_mfma_f32_16x16x32_bf16 v[52:55], v[170:173], v[186:189], v[52:55]
	v_mfma_f32_16x16x32_bf16 v[48:51], v[178:181], v[186:189], v[48:51]
	v_mfma_f32_16x16x32_bf16 v[36:39], v[170:173], v[196:199], v[36:39]
	v_mfma_f32_16x16x32_bf16 v[32:35], v[178:181], v[196:199], v[32:35]
	v_mfma_f32_16x16x32_bf16 v[20:23], v[170:173], v[204:207], v[20:23]
	v_mfma_f32_16x16x32_bf16 v[16:19], v[178:181], v[204:207], v[16:19]
	v_mfma_f32_16x16x32_bf16 v[4:7], v[170:173], v[212:215], v[4:7]
	v_mfma_f32_16x16x32_bf16 v[0:3], v[178:181], v[212:215], v[0:3]
	v_mfma_f32_16x16x32_bf16 v[52:55], v[174:177], v[190:193], v[52:55]
	v_mfma_f32_16x16x32_bf16 v[48:51], v[182:185], v[190:193], v[48:51]
	v_mfma_f32_16x16x32_bf16 v[36:39], v[174:177], v[200:203], v[36:39]
	v_mfma_f32_16x16x32_bf16 v[32:35], v[182:185], v[200:203], v[32:35]
	v_mfma_f32_16x16x32_bf16 v[20:23], v[174:177], v[208:211], v[20:23]
	v_mfma_f32_16x16x32_bf16 v[16:19], v[182:185], v[208:211], v[16:19]
	v_mfma_f32_16x16x32_bf16 v[4:7], v[174:177], v[216:219], v[4:7]
	s_setprio 2
	s_barrier
	v_mfma_f32_16x16x32_bf16 v[0:3], v[182:185], v[216:219], v[0:3]
	s_setprio 0
	s_add_i32 s64, 0, 0x18000
	v_add_u32_e32 v153, s64, v147
	s_add_i32 s65, 0, 0x1c000
	ds_read_b128 v[154:157], v153
	ds_read_b128 v[158:161], v153 offset:1024
	ds_read_b128 v[162:165], v153 offset:2048
	ds_read_b128 v[166:169], v153 offset:3072
	v_add_u32_e32 v153, s65, v147
	ds_read_b128 v[170:173], v153
	ds_read_b128 v[174:177], v153 offset:1024
	ds_read_b128 v[178:181], v153 offset:2048
	ds_read_b128 v[182:185], v153 offset:3072
	s_add_u32 s46, s46, 0x40000
	s_addc_u32 s47, s47, 0
	s_mov_b32 m0, s51
	v_lshl_add_u64 v[226:227], s[46:47], 0, v[128:129]
	ds_read_b128 v[186:189], v151 offset:32768
	ds_read_b128 v[190:193], v151 offset:33792
	ds_read_b128 v[196:199], v151 offset:34816
	ds_read_b128 v[200:203], v151 offset:35840
	ds_read_b128 v[204:207], v151 offset:36864
	ds_read_b128 v[208:211], v151 offset:37888
	ds_read_b128 v[212:215], v151 offset:38912
	ds_read_b128 v[216:219], v151 offset:39936
	global_load_lds_dwordx4 v[226:227], off
	v_lshl_add_u64 v[226:227], s[46:47], 0, v[132:133]
	s_mov_b32 m0, s52
	s_nop 0
	global_load_lds_dwordx4 v[226:227], off
	s_waitcnt vmcnt(8)
	s_waitcnt lgkmcnt(0)
	s_barrier
	s_waitcnt lgkmcnt(0)
	v_mfma_f32_16x16x32_bf16 v[124:127], v[154:157], v[186:189], v[124:127]
	v_mfma_f32_16x16x32_bf16 v[120:123], v[162:165], v[186:189], v[120:123]
	v_mfma_f32_16x16x32_bf16 v[108:111], v[154:157], v[196:199], v[108:111]
	v_mfma_f32_16x16x32_bf16 v[104:107], v[162:165], v[196:199], v[104:107]
	v_mfma_f32_16x16x32_bf16 v[92:95], v[154:157], v[204:207], v[92:95]
	v_mfma_f32_16x16x32_bf16 v[88:91], v[162:165], v[204:207], v[88:91]
	v_mfma_f32_16x16x32_bf16 v[76:79], v[154:157], v[212:215], v[76:79]
	v_mfma_f32_16x16x32_bf16 v[72:75], v[162:165], v[212:215], v[72:75]
	v_mfma_f32_16x16x32_bf16 v[124:127], v[158:161], v[190:193], v[124:127]
	v_mfma_f32_16x16x32_bf16 v[120:123], v[166:169], v[190:193], v[120:123]
	v_mfma_f32_16x16x32_bf16 v[108:111], v[158:161], v[200:203], v[108:111]
	v_mfma_f32_16x16x32_bf16 v[104:107], v[166:169], v[200:203], v[104:107]
	v_mfma_f32_16x16x32_bf16 v[92:95], v[158:161], v[208:211], v[92:95]
	v_mfma_f32_16x16x32_bf16 v[88:91], v[166:169], v[208:211], v[88:91]
	v_mfma_f32_16x16x32_bf16 v[76:79], v[158:161], v[216:219], v[76:79]
	v_mfma_f32_16x16x32_bf16 v[72:75], v[166:169], v[216:219], v[72:75]
	v_mfma_f32_16x16x32_bf16 v[116:119], v[170:173], v[186:189], v[116:119]
	v_mfma_f32_16x16x32_bf16 v[112:115], v[178:181], v[186:189], v[112:115]
	v_mfma_f32_16x16x32_bf16 v[100:103], v[170:173], v[196:199], v[100:103]
	v_mfma_f32_16x16x32_bf16 v[96:99], v[178:181], v[196:199], v[96:99]
	v_mfma_f32_16x16x32_bf16 v[84:87], v[170:173], v[204:207], v[84:87]
	v_mfma_f32_16x16x32_bf16 v[80:83], v[178:181], v[204:207], v[80:83]
	v_mfma_f32_16x16x32_bf16 v[68:71], v[170:173], v[212:215], v[68:71]
	v_mfma_f32_16x16x32_bf16 v[64:67], v[178:181], v[212:215], v[64:67]
	v_mfma_f32_16x16x32_bf16 v[116:119], v[174:177], v[190:193], v[116:119]
	v_mfma_f32_16x16x32_bf16 v[112:115], v[182:185], v[190:193], v[112:115]
	v_mfma_f32_16x16x32_bf16 v[100:103], v[174:177], v[200:203], v[100:103]
	v_mfma_f32_16x16x32_bf16 v[96:99], v[182:185], v[200:203], v[96:99]
	v_mfma_f32_16x16x32_bf16 v[84:87], v[174:177], v[208:211], v[84:87]
	v_mfma_f32_16x16x32_bf16 v[80:83], v[182:185], v[208:211], v[80:83]
	v_mfma_f32_16x16x32_bf16 v[68:71], v[174:177], v[216:219], v[68:71]
	s_setprio 2
	s_barrier
; #define PG8_STAGE_T(bufoff, gbase, voff, AUX) do { _Pragma("unroll") for (int _i = 0; _i < 2; ++_i) \
;         __builtin_amdgcn_global_load_lds((const unsigned*)((const char*)(gbase) + (voff)[_i]), (PG8_LAS unsigned*)(lds + (bufoff) + ldsw + _i * 8192), 16, 0, AUX); } while (0)
; #define PG8_LDA(dst, b, h) do { _Pragma("unroll") for (int m = 0; m < 4; ++m) _Pragma("unroll") for (int k = 0; k < 2; ++k) dst[m][k] = *(const PG8_LAS bf16x8*)(lds + PG8_SA(b, h) + aoff + m * 2048 + k * 1024); } while (0)
; #define PG8_MMA(ai, bj, At, Bt) do { __builtin_amdgcn_s_setprio(1); _Pragma("unroll") for (int m = 0; m < 4; ++m) _Pragma("unroll") for (int n = 0; n < 2; ++n) _Pragma("unroll") for (int k = 0; k < 2; ++k) \
;         acc[ai][bj][m][n] = __builtin_amdgcn_mfma_f32_16x16x32_bf16(Bt[n][k], At[m][k], acc[ai][bj][m][n], 0, 0, 0); __builtin_amdgcn_s_setprio(0); } while (0)
; #define PG8_WAIT_V(n) asm volatile("s_waitcnt vmcnt(" #n ")" ::: "memory")
; #define PG8_WAIT_L(n) asm volatile("s_waitcnt lgkmcnt(" #n ")" ::: "memory")
; #define PG8_BAR __builtin_amdgcn_s_barrier()
; #define PG8_SCHED __builtin_amdgcn_sched_barrier(0)
;     ...
;             if (!pe) { PG8_WAIT_V(8); } PG8_WAIT_L(0); PG8_BAR; PG8_MMA(0, 0, At, B0); PG8_MMA(0, 1, At, B1); PG8_BAR; PG8_SCHED;
;             PG8_LDA(At, 1, 1); PG8_STAGE_T(PG8_SB(1, 0), b3, voffB, AUX_B); PG8_STAGE_T(PG8_SB(1, 1), b3 + hstep, voffB, AUX_B); PG8_STAGE_T(PG8_SA(1, 0), a3, voffA, AUX_A);
;             PG8_WAIT_V(8); PG8_WAIT_L(0); PG8_BAR; PG8_MMA(1, 0, At, B0); PG8_MMA(1, 1, At, B1); PG8_BAR; PG8_SCHED;
;     ...
;         if constexpr (ALIGN_EPI) { if (wr == 0) PG8_BAR; }
	v_mfma_f32_16x16x32_bf16 v[64:67], v[182:185], v[216:219], v[64:67]
	s_setprio 0
	s_add_i32 s46, s64, s48
	v_lshl_add_u64 v[144:145], v[144:145], 0, s[10:11]
	s_mov_b32 m0, s46
	ds_read_b128 v[186:189], v151 offset:49152
	ds_read_b128 v[190:193], v151 offset:50176
	ds_read_b128 v[196:199], v151 offset:51200
	ds_read_b128 v[200:203], v151 offset:52224
	ds_read_b128 v[204:207], v151 offset:53248
	ds_read_b128 v[208:211], v151 offset:54272
	ds_read_b128 v[212:215], v151 offset:55296
	ds_read_b128 v[216:219], v151 offset:56320
	global_load_lds_dwordx4 v[144:145], off
	s_add_i32 m0, s46, 0x2000
	s_add_u32 s44, s44, 0x40080
	v_lshl_add_u64 v[144:145], v[220:221], 0, s[10:11]
	s_addc_u32 s45, s45, 0
	s_add_i32 s46, s65, s48
	global_load_lds_dwordx4 v[144:145], off
	v_lshl_add_u64 v[144:145], s[44:45], 0, v[130:131]
	s_mov_b32 m0, s46
	s_nop 0
	global_load_lds_dwordx4 v[144:145], off
	v_lshl_add_u64 v[144:145], s[44:45], 0, v[134:135]
	s_add_i32 m0, s46, 0x2000
	s_nop 0
	global_load_lds_dwordx4 v[144:145], off
	v_lshl_add_u64 v[144:145], v[222:223], 0, s[10:11]
	s_mov_b32 m0, s53
	s_nop 0
	global_load_lds_dwordx4 v[144:145], off
	v_lshl_add_u64 v[144:145], v[224:225], 0, s[10:11]
	s_mov_b32 m0, s54
	s_nop 0
	global_load_lds_dwordx4 v[144:145], off
	s_waitcnt vmcnt(8)
	s_waitcnt lgkmcnt(0)
	s_barrier
	s_waitcnt lgkmcnt(0)
	v_mfma_f32_16x16x32_bf16 v[60:63], v[154:157], v[186:189], v[60:63]
	v_mfma_f32_16x16x32_bf16 v[56:59], v[162:165], v[186:189], v[56:59]
	v_mfma_f32_16x16x32_bf16 v[44:47], v[154:157], v[196:199], v[44:47]
	v_mfma_f32_16x16x32_bf16 v[40:43], v[162:165], v[196:199], v[40:43]
	v_mfma_f32_16x16x32_bf16 v[28:31], v[154:157], v[204:207], v[28:31]
	v_mfma_f32_16x16x32_bf16 v[24:27], v[162:165], v[204:207], v[24:27]
	v_mfma_f32_16x16x32_bf16 v[12:15], v[154:157], v[212:215], v[12:15]
	v_mfma_f32_16x16x32_bf16 v[8:11], v[162:165], v[212:215], v[8:11]
	v_mfma_f32_16x16x32_bf16 v[60:63], v[158:161], v[190:193], v[60:63]
	v_mfma_f32_16x16x32_bf16 v[56:59], v[166:169], v[190:193], v[56:59]
	v_mfma_f32_16x16x32_bf16 v[44:47], v[158:161], v[200:203], v[44:47]
	v_mfma_f32_16x16x32_bf16 v[40:43], v[166:169], v[200:203], v[40:43]
	v_mfma_f32_16x16x32_bf16 v[28:31], v[158:161], v[208:211], v[28:31]
	v_mfma_f32_16x16x32_bf16 v[24:27], v[166:169], v[208:211], v[24:27]
	v_mfma_f32_16x16x32_bf16 v[12:15], v[158:161], v[216:219], v[12:15]
	v_mfma_f32_16x16x32_bf16 v[8:11], v[166:169], v[216:219], v[8:11]
	v_mfma_f32_16x16x32_bf16 v[52:55], v[170:173], v[186:189], v[52:55]
	v_mfma_f32_16x16x32_bf16 v[48:51], v[178:181], v[186:189], v[48:51]
	v_mfma_f32_16x16x32_bf16 v[36:39], v[170:173], v[196:199], v[36:39]
	v_mfma_f32_16x16x32_bf16 v[32:35], v[178:181], v[196:199], v[32:35]
	v_mfma_f32_16x16x32_bf16 v[20:23], v[170:173], v[204:207], v[20:23]
	v_mfma_f32_16x16x32_bf16 v[16:19], v[178:181], v[204:207], v[16:19]
	v_mfma_f32_16x16x32_bf16 v[4:7], v[170:173], v[212:215], v[4:7]
	v_mfma_f32_16x16x32_bf16 v[0:3], v[178:181], v[212:215], v[0:3]
	v_mfma_f32_16x16x32_bf16 v[52:55], v[174:177], v[190:193], v[52:55]
	v_mfma_f32_16x16x32_bf16 v[48:51], v[182:185], v[190:193], v[48:51]
	v_mfma_f32_16x16x32_bf16 v[36:39], v[174:177], v[200:203], v[36:39]
	v_mfma_f32_16x16x32_bf16 v[32:35], v[182:185], v[200:203], v[32:35]
	v_mfma_f32_16x16x32_bf16 v[20:23], v[174:177], v[208:211], v[20:23]
	v_mfma_f32_16x16x32_bf16 v[16:19], v[182:185], v[208:211], v[16:19]
	v_mfma_f32_16x16x32_bf16 v[4:7], v[174:177], v[216:219], v[4:7]
	s_setprio 2
	s_barrier
	v_mfma_f32_16x16x32_bf16 v[0:3], v[182:185], v[216:219], v[0:3]
	s_setprio 0
	s_add_i32 s63, s63, 2
	s_add_u32 s42, s42, 0x100
	s_addc_u32 s43, s43, 0
	s_add_u32 s61, s61, 0x100
	s_addc_u32 s62, s62, 0
	s_cmp_gt_u32 s63, 13
	s_cbranch_scc0 .LBB0_886
	s_and_b64 vcc, exec, s[12:13]
	s_cbranch_vccz .LBB0_889
	s_barrier

; #define PG8_STAGE_T(bufoff, gbase, voff, AUX) do { _Pragma("unroll") for (int _i = 0; _i < 2; ++_i) \
;         __builtin_amdgcn_global_load_lds((const unsigned*)((const char*)(gbase) + (voff)[_i]), (PG8_LAS unsigned*)(lds + (bufoff) + ldsw + _i * 8192), 16, 0, AUX); } while (0)
; #define PG8_LDA(dst, b, h) do { _Pragma("unroll") for (int m = 0; m < 4; ++m) _Pragma("unroll") for (int k = 0; k < 2; ++k) dst[m][k] = *(const PG8_LAS bf16x8*)(lds + PG8_SA(b, h) + aoff + m * 2048 + k * 1024); } while (0)
; #define PG8_LDB(dst, b, h) do { _Pragma("unroll") for (int n = 0; n < 2; ++n) _Pragma("unroll") for (int k = 0; k < 2; ++k) dst[n][k] = *(const PG8_LAS bf16x8*)(lds + PG8_SB(b, h) + boff + n * 2048 + k * 1024); } while (0)
; #define PG8_MMA(ai, bj, At, Bt) do { __builtin_amdgcn_s_setprio(1); _Pragma("unroll") for (int m = 0; m < 4; ++m) _Pragma("unroll") for (int n = 0; n < 2; ++n) _Pragma("unroll") for (int k = 0; k < 2; ++k) \
;         acc[ai][bj][m][n] = __builtin_amdgcn_mfma_f32_16x16x32_bf16(Bt[n][k], At[m][k], acc[ai][bj][m][n], 0, 0, 0); __builtin_amdgcn_s_setprio(0); } while (0)
; #define PG8_WAIT_V(n) asm volatile("s_waitcnt vmcnt(" #n ")" ::: "memory")
;     ...
;             const bool last = (t == nt - 2);
;             const char* a1 = cA + (ptrdiff_t)(t + 1) * ck;
;             const char* a2 = last ? nA : cA + (ptrdiff_t)(t + 2) * ck; const char* b2 = last ? nB : cB + (ptrdiff_t)(t + 2) * ck;
;             const ptrdiff_t k3 = last ? nk : ck;
;             const char* a3 = a2 + k3; const char* b3 = b2 + k3;
;             if (last && has_next) S.a_ready(nxt);
;             if constexpr (SP2) {
;             int pei = 0; if constexpr (PEEL) { pei = __builtin_amdgcn_readfirstlane((t == 0 && ui > 0) ? 1 : 0); asm volatile("" : "+s"(pei)); }
;             const bool pe = pei != 0;
;             PG8_LDB(B0, 0, 0); PG8_LDB(B1, 0, 1); PG8_SCHED; PG8_LDA(At, 0, 0); if (!pe) { PG8_STAGE_T(PG8_SA(1, 1), a1 + hstep, voffA, AUX_A); }
;             if (!pe) { PG8_WAIT_V(8); } PG8_WAIT_L(0); PG8_BAR; PG8_MMA(0, 0, At, B0); PG8_MMA(0, 1, At, B1); PG8_BAR; PG8_SCHED;
;             PG8_LDA(At, 0, 1); PG8_STAGE_T(PG8_SB(0, 0), b2, voffB, AUX_B); PG8_STAGE_T(PG8_SB(0, 1), b2 + hstep, voffB, AUX_B); PG8_STAGE_T(PG8_SA(0, 0), a2, voffA, AUX_A);
;             if (!pe) { PG8_WAIT_V(8); } PG8_WAIT_L(0); PG8_BAR; PG8_MMA(1, 0, At, B0); PG8_MMA(1, 1, At, B1); PG8_BAR; PG8_SCHED;
.LBB0_1071:
	ds_read_b128 v[146:149], v166
	ds_read_b128 v[162:165], v166 offset:1024
	ds_read_b128 v[170:173], v166 offset:2048
	ds_read_b128 v[174:177], v166 offset:3072
	ds_read_b128 v[178:181], v167
	ds_read_b128 v[182:185], v167 offset:1024
	ds_read_b128 v[186:189], v167 offset:2048
	ds_read_b128 v[190:193], v167 offset:3072
	s_add_u32 s38, s36, 0xfffc0080
	s_addc_u32 s39, s37, -1
	s_cmp_eq_u32 s62, 12
	s_cselect_b32 s41, s13, s39
	s_cselect_b32 s40, s27, s38
	s_cselect_b32 s39, s15, s61
	s_cselect_b32 s38, s59, s60
	v_lshl_add_u64 v[150:151], s[36:37], 0, v[136:137]
	s_add_i32 m0, s45, 0xc000
	ds_read_b128 v[196:199], v168
	ds_read_b128 v[200:203], v168 offset:1024
	ds_read_b128 v[204:207], v168 offset:2048
	ds_read_b128 v[208:211], v168 offset:3072
	ds_read_b128 v[212:215], v168 offset:4096
	ds_read_b128 v[216:219], v168 offset:5120
	ds_read_b128 v[220:223], v168 offset:6144
	ds_read_b128 v[224:227], v168 offset:7168
	global_load_lds_dwordx4 v[150:151], off
	v_lshl_add_u64 v[150:151], s[36:37], 0, v[138:139]
	s_add_i32 m0, s45, 0xe000
	s_nop 0
	global_load_lds_dwordx4 v[150:151], off
	s_waitcnt vmcnt(8)
	s_waitcnt lgkmcnt(0)
	s_barrier
	s_waitcnt lgkmcnt(0)
	v_mfma_f32_16x16x32_bf16 v[124:127], v[146:149], v[196:199], v[124:127]
	v_mfma_f32_16x16x32_bf16 v[120:123], v[170:173], v[196:199], v[120:123]
	v_mfma_f32_16x16x32_bf16 v[108:111], v[146:149], v[204:207], v[108:111]
	v_mfma_f32_16x16x32_bf16 v[104:107], v[170:173], v[204:207], v[104:107]
	v_mfma_f32_16x16x32_bf16 v[92:95], v[146:149], v[212:215], v[92:95]
	v_mfma_f32_16x16x32_bf16 v[88:91], v[170:173], v[212:215], v[88:91]
	v_mfma_f32_16x16x32_bf16 v[76:79], v[146:149], v[220:223], v[76:79]
	v_mfma_f32_16x16x32_bf16 v[72:75], v[170:173], v[220:223], v[72:75]
	v_mfma_f32_16x16x32_bf16 v[124:127], v[162:165], v[200:203], v[124:127]
	v_mfma_f32_16x16x32_bf16 v[120:123], v[174:177], v[200:203], v[120:123]
	v_mfma_f32_16x16x32_bf16 v[108:111], v[162:165], v[208:211], v[108:111]
	v_mfma_f32_16x16x32_bf16 v[104:107], v[174:177], v[208:211], v[104:107]
	v_mfma_f32_16x16x32_bf16 v[92:95], v[162:165], v[216:219], v[92:95]
	v_mfma_f32_16x16x32_bf16 v[88:91], v[174:177], v[216:219], v[88:91]
	v_mfma_f32_16x16x32_bf16 v[76:79], v[162:165], v[224:227], v[76:79]
	v_mfma_f32_16x16x32_bf16 v[72:75], v[174:177], v[224:227], v[72:75]
	v_mfma_f32_16x16x32_bf16 v[116:119], v[178:181], v[196:199], v[116:119]
	v_mfma_f32_16x16x32_bf16 v[112:115], v[186:189], v[196:199], v[112:115]
	v_mfma_f32_16x16x32_bf16 v[100:103], v[178:181], v[204:207], v[100:103]
	v_mfma_f32_16x16x32_bf16 v[96:99], v[186:189], v[204:207], v[96:99]
	v_mfma_f32_16x16x32_bf16 v[84:87], v[178:181], v[212:215], v[84:87]
	v_mfma_f32_16x16x32_bf16 v[80:83], v[186:189], v[212:215], v[80:83]
	v_mfma_f32_16x16x32_bf16 v[68:71], v[178:181], v[220:223], v[68:71]
	v_mfma_f32_16x16x32_bf16 v[64:67], v[186:189], v[220:223], v[64:67]
	v_mfma_f32_16x16x32_bf16 v[116:119], v[182:185], v[200:203], v[116:119]
	v_mfma_f32_16x16x32_bf16 v[112:115], v[190:193], v[200:203], v[112:115]
	v_mfma_f32_16x16x32_bf16 v[100:103], v[182:185], v[208:211], v[100:103]
	v_mfma_f32_16x16x32_bf16 v[96:99], v[190:193], v[208:211], v[96:99]
	v_mfma_f32_16x16x32_bf16 v[84:87], v[182:185], v[216:219], v[84:87]
	v_mfma_f32_16x16x32_bf16 v[80:83], v[190:193], v[216:219], v[80:83]
	v_mfma_f32_16x16x32_bf16 v[68:71], v[182:185], v[224:227], v[68:71]
	s_setprio 2
	s_barrier
	v_mfma_f32_16x16x32_bf16 v[64:67], v[190:193], v[224:227], v[64:67]
	s_setprio 0
	s_add_i32 s63, s52, s43
	v_lshl_add_u64 v[150:151], s[38:39], 0, v[132:133]
	s_mov_b32 m0, s63
	ds_read_b128 v[196:199], v168 offset:16384
	ds_read_b128 v[200:203], v168 offset:17408
	ds_read_b128 v[204:207], v168 offset:18432
	ds_read_b128 v[208:211], v168 offset:19456
	ds_read_b128 v[212:215], v168 offset:20480
	ds_read_b128 v[216:219], v168 offset:21504
	ds_read_b128 v[220:223], v168 offset:22528
	ds_read_b128 v[224:227], v168 offset:23552
	global_load_lds_dwordx4 v[150:151], off
	s_add_i32 m0, s63, 0x2000
	s_add_u32 s64, s38, 0x40000
	v_lshl_add_u64 v[154:155], s[38:39], 0, v[128:129]
	s_addc_u32 s65, s39, 0
	s_add_i32 s63, s53, s43
	global_load_lds_dwordx4 v[154:155], off
	v_lshl_add_u64 v[158:159], s[64:65], 0, v[132:133]
	s_mov_b32 m0, s63
	v_lshl_add_u64 v[228:229], s[40:41], 0, v[130:131]
	global_load_lds_dwordx4 v[158:159], off
	v_lshl_add_u64 v[158:159], s[64:65], 0, v[128:129]
	s_add_i32 m0, s63, 0x2000
	s_nop 0
	global_load_lds_dwordx4 v[158:159], off
	v_lshl_add_u64 v[158:159], s[40:41], 0, v[134:135]
	s_mov_b32 m0, s45
	s_nop 0
	global_load_lds_dwordx4 v[158:159], off
	s_mov_b32 m0, s46
	s_nop 0
	global_load_lds_dwordx4 v[228:229], off
	s_waitcnt vmcnt(8)
	s_waitcnt lgkmcnt(0)
	s_barrier
; #define PG8_STAGE_T(bufoff, gbase, voff, AUX) do { _Pragma("unroll") for (int _i = 0; _i < 2; ++_i) \
;         __builtin_amdgcn_global_load_lds((const unsigned*)((const char*)(gbase) + (voff)[_i]), (PG8_LAS unsigned*)(lds + (bufoff) + ldsw + _i * 8192), 16, 0, AUX); } while (0)
; #define PG8_LDA(dst, b, h) do { _Pragma("unroll") for (int m = 0; m < 4; ++m) _Pragma("unroll") for (int k = 0; k < 2; ++k) dst[m][k] = *(const PG8_LAS bf16x8*)(lds + PG8_SA(b, h) + aoff + m * 2048 + k * 1024); } while (0)
; #define PG8_LDB(dst, b, h) do { _Pragma("unroll") for (int n = 0; n < 2; ++n) _Pragma("unroll") for (int k = 0; k < 2; ++k) dst[n][k] = *(const PG8_LAS bf16x8*)(lds + PG8_SB(b, h) + boff + n * 2048 + k * 1024); } while (0)
; #define PG8_MMA(ai, bj, At, Bt) do { __builtin_amdgcn_s_setprio(1); _Pragma("unroll") for (int m = 0; m < 4; ++m) _Pragma("unroll") for (int n = 0; n < 2; ++n) _Pragma("unroll") for (int k = 0; k < 2; ++k) \
;         acc[ai][bj][m][n] = __builtin_amdgcn_mfma_f32_16x16x32_bf16(Bt[n][k], At[m][k], acc[ai][bj][m][n], 0, 0, 0); __builtin_amdgcn_s_setprio(0); } while (0)
; #define PG8_WAIT_V(n) asm volatile("s_waitcnt vmcnt(" #n ")" ::: "memory")
; #define PG8_WAIT_L(n) asm volatile("s_waitcnt lgkmcnt(" #n ")" ::: "memory")
; #define PG8_BAR __builtin_amdgcn_s_barrier()
; #define PG8_SCHED __builtin_amdgcn_sched_barrier(0)
;     ...
;             if (!pe) { PG8_WAIT_V(8); } PG8_WAIT_L(0); PG8_BAR; PG8_MMA(1, 0, At, B0); PG8_MMA(1, 1, At, B1); PG8_BAR; PG8_SCHED;
;             PG8_LDB(B0, 1, 0); PG8_LDB(B1, 1, 1); PG8_SCHED; PG8_LDA(At, 1, 0); PG8_STAGE_T(PG8_SA(0, 1), a2 + hstep, voffA, AUX_A);
;             if (!pe) { PG8_WAIT_V(8); } PG8_WAIT_L(0); PG8_BAR; PG8_MMA(0, 0, At, B0); PG8_MMA(0, 1, At, B1); PG8_BAR; PG8_SCHED;
	s_waitcnt lgkmcnt(0)
	v_mfma_f32_16x16x32_bf16 v[60:63], v[146:149], v[196:199], v[60:63]
	v_mfma_f32_16x16x32_bf16 v[56:59], v[170:173], v[196:199], v[56:59]
	v_mfma_f32_16x16x32_bf16 v[44:47], v[146:149], v[204:207], v[44:47]
	v_mfma_f32_16x16x32_bf16 v[40:43], v[170:173], v[204:207], v[40:43]
	v_mfma_f32_16x16x32_bf16 v[28:31], v[146:149], v[212:215], v[28:31]
	v_mfma_f32_16x16x32_bf16 v[24:27], v[170:173], v[212:215], v[24:27]
	v_mfma_f32_16x16x32_bf16 v[12:15], v[146:149], v[220:223], v[12:15]
	v_mfma_f32_16x16x32_bf16 v[8:11], v[170:173], v[220:223], v[8:11]
	v_mfma_f32_16x16x32_bf16 v[60:63], v[162:165], v[200:203], v[60:63]
	v_mfma_f32_16x16x32_bf16 v[56:59], v[174:177], v[200:203], v[56:59]
	v_mfma_f32_16x16x32_bf16 v[44:47], v[162:165], v[208:211], v[44:47]
	v_mfma_f32_16x16x32_bf16 v[40:43], v[174:177], v[208:211], v[40:43]
	v_mfma_f32_16x16x32_bf16 v[28:31], v[162:165], v[216:219], v[28:31]
	v_mfma_f32_16x16x32_bf16 v[24:27], v[174:177], v[216:219], v[24:27]
	v_mfma_f32_16x16x32_bf16 v[12:15], v[162:165], v[224:227], v[12:15]
	v_mfma_f32_16x16x32_bf16 v[8:11], v[174:177], v[224:227], v[8:11]
	v_mfma_f32_16x16x32_bf16 v[52:55], v[178:181], v[196:199], v[52:55]
	v_mfma_f32_16x16x32_bf16 v[48:51], v[186:189], v[196:199], v[48:51]
	v_mfma_f32_16x16x32_bf16 v[36:39], v[178:181], v[204:207], v[36:39]
	v_mfma_f32_16x16x32_bf16 v[32:35], v[186:189], v[204:207], v[32:35]
	v_mfma_f32_16x16x32_bf16 v[20:23], v[178:181], v[212:215], v[20:23]
	v_mfma_f32_16x16x32_bf16 v[16:19], v[186:189], v[212:215], v[16:19]
	v_mfma_f32_16x16x32_bf16 v[4:7], v[178:181], v[220:223], v[4:7]
	v_mfma_f32_16x16x32_bf16 v[0:3], v[186:189], v[220:223], v[0:3]
	v_mfma_f32_16x16x32_bf16 v[52:55], v[182:185], v[200:203], v[52:55]
	v_mfma_f32_16x16x32_bf16 v[48:51], v[190:193], v[200:203], v[48:51]
	v_mfma_f32_16x16x32_bf16 v[36:39], v[182:185], v[208:211], v[36:39]
	v_mfma_f32_16x16x32_bf16 v[32:35], v[190:193], v[208:211], v[32:35]
	v_mfma_f32_16x16x32_bf16 v[20:23], v[182:185], v[216:219], v[20:23]
	v_mfma_f32_16x16x32_bf16 v[16:19], v[190:193], v[216:219], v[16:19]
	v_mfma_f32_16x16x32_bf16 v[4:7], v[182:185], v[224:227], v[4:7]
	s_setprio 2
	s_barrier
	v_mfma_f32_16x16x32_bf16 v[0:3], v[190:193], v[224:227], v[0:3]
	s_setprio 0
	s_add_i32 s63, 0, 0x18000
	v_add_u32_e32 v144, s63, v153
	s_add_i32 s64, 0, 0x1c000
	ds_read_b128 v[146:149], v144
	ds_read_b128 v[162:165], v144 offset:1024
	ds_read_b128 v[170:173], v144 offset:2048
	ds_read_b128 v[174:177], v144 offset:3072
	v_add_u32_e32 v144, s64, v153
	ds_read_b128 v[178:181], v144
	ds_read_b128 v[182:185], v144 offset:1024
	ds_read_b128 v[186:189], v144 offset:2048
	ds_read_b128 v[190:193], v144 offset:3072
	s_add_u32 s40, s40, 0x40000
	s_addc_u32 s41, s41, 0
	s_mov_b32 m0, s47
	v_lshl_add_u64 v[230:231], s[40:41], 0, v[134:135]
	ds_read_b128 v[196:199], v168 offset:32768
	ds_read_b128 v[200:203], v168 offset:33792
	ds_read_b128 v[204:207], v168 offset:34816
	ds_read_b128 v[208:211], v168 offset:35840
	ds_read_b128 v[212:215], v168 offset:36864
	ds_read_b128 v[216:219], v168 offset:37888
	ds_read_b128 v[220:223], v168 offset:38912
	ds_read_b128 v[224:227], v168 offset:39936
	global_load_lds_dwordx4 v[230:231], off
	v_lshl_add_u64 v[230:231], s[40:41], 0, v[130:131]
	s_mov_b32 m0, s48
	s_nop 0
	global_load_lds_dwordx4 v[230:231], off
	s_waitcnt vmcnt(8)
	s_waitcnt lgkmcnt(0)
	s_barrier
	s_waitcnt lgkmcnt(0)
	v_mfma_f32_16x16x32_bf16 v[124:127], v[146:149], v[196:199], v[124:127]
	v_mfma_f32_16x16x32_bf16 v[120:123], v[170:173], v[196:199], v[120:123]
	v_mfma_f32_16x16x32_bf16 v[108:111], v[146:149], v[204:207], v[108:111]
	v_mfma_f32_16x16x32_bf16 v[104:107], v[170:173], v[204:207], v[104:107]
	v_mfma_f32_16x16x32_bf16 v[92:95], v[146:149], v[212:215], v[92:95]
	v_mfma_f32_16x16x32_bf16 v[88:91], v[170:173], v[212:215], v[88:91]
	v_mfma_f32_16x16x32_bf16 v[76:79], v[146:149], v[220:223], v[76:79]
	v_mfma_f32_16x16x32_bf16 v[72:75], v[170:173], v[220:223], v[72:75]
	v_mfma_f32_16x16x32_bf16 v[124:127], v[162:165], v[200:203], v[124:127]
	v_mfma_f32_16x16x32_bf16 v[120:123], v[174:177], v[200:203], v[120:123]
	v_mfma_f32_16x16x32_bf16 v[108:111], v[162:165], v[208:211], v[108:111]
	v_mfma_f32_16x16x32_bf16 v[104:107], v[174:177], v[208:211], v[104:107]
	v_mfma_f32_16x16x32_bf16 v[92:95], v[162:165], v[216:219], v[92:95]
	v_mfma_f32_16x16x32_bf16 v[88:91], v[174:177], v[216:219], v[88:91]
	v_mfma_f32_16x16x32_bf16 v[76:79], v[162:165], v[224:227], v[76:79]
	v_mfma_f32_16x16x32_bf16 v[72:75], v[174:177], v[224:227], v[72:75]
	v_mfma_f32_16x16x32_bf16 v[116:119], v[178:181], v[196:199], v[116:119]
	v_mfma_f32_16x16x32_bf16 v[112:115], v[186:189], v[196:199], v[112:115]
	v_mfma_f32_16x16x32_bf16 v[100:103], v[178:181], v[204:207], v[100:103]
	v_mfma_f32_16x16x32_bf16 v[96:99], v[186:189], v[204:207], v[96:99]
	v_mfma_f32_16x16x32_bf16 v[84:87], v[178:181], v[212:215], v[84:87]
	v_mfma_f32_16x16x32_bf16 v[80:83], v[186:189], v[212:215], v[80:83]
	v_mfma_f32_16x16x32_bf16 v[68:71], v[178:181], v[220:223], v[68:71]
	v_mfma_f32_16x16x32_bf16 v[64:67], v[186:189], v[220:223], v[64:67]
	v_mfma_f32_16x16x32_bf16 v[116:119], v[182:185], v[200:203], v[116:119]
	v_mfma_f32_16x16x32_bf16 v[112:115], v[190:193], v[200:203], v[112:115]
	v_mfma_f32_16x16x32_bf16 v[100:103], v[182:185], v[208:211], v[100:103]
	v_mfma_f32_16x16x32_bf16 v[96:99], v[190:193], v[208:211], v[96:99]
	v_mfma_f32_16x16x32_bf16 v[84:87], v[182:185], v[216:219], v[84:87]
	v_mfma_f32_16x16x32_bf16 v[80:83], v[190:193], v[216:219], v[80:83]
	v_mfma_f32_16x16x32_bf16 v[68:71], v[182:185], v[224:227], v[68:71]
	s_setprio 2
	s_barrier
; #define PG8_STAGE_T(bufoff, gbase, voff, AUX) do { _Pragma("unroll") for (int _i = 0; _i < 2; ++_i) \
;         __builtin_amdgcn_global_load_lds((const unsigned*)((const char*)(gbase) + (voff)[_i]), (PG8_LAS unsigned*)(lds + (bufoff) + ldsw + _i * 8192), 16, 0, AUX); } while (0)
; #define PG8_LDA(dst, b, h) do { _Pragma("unroll") for (int m = 0; m < 4; ++m) _Pragma("unroll") for (int k = 0; k < 2; ++k) dst[m][k] = *(const PG8_LAS bf16x8*)(lds + PG8_SA(b, h) + aoff + m * 2048 + k * 1024); } while (0)
; #define PG8_MMA(ai, bj, At, Bt) do { __builtin_amdgcn_s_setprio(1); _Pragma("unroll") for (int m = 0; m < 4; ++m) _Pragma("unroll") for (int n = 0; n < 2; ++n) _Pragma("unroll") for (int k = 0; k < 2; ++k) \
;         acc[ai][bj][m][n] = __builtin_amdgcn_mfma_f32_16x16x32_bf16(Bt[n][k], At[m][k], acc[ai][bj][m][n], 0, 0, 0); __builtin_amdgcn_s_setprio(0); } while (0)
; #define PG8_WAIT_V(n) asm volatile("s_waitcnt vmcnt(" #n ")" ::: "memory")
; #define PG8_WAIT_L(n) asm volatile("s_waitcnt lgkmcnt(" #n ")" ::: "memory")
; #define PG8_BAR __builtin_amdgcn_s_barrier()
; #define PG8_SCHED __builtin_amdgcn_sched_barrier(0)
;     ...
;             if (!pe) { PG8_WAIT_V(8); } PG8_WAIT_L(0); PG8_BAR; PG8_MMA(0, 0, At, B0); PG8_MMA(0, 1, At, B1); PG8_BAR; PG8_SCHED;
;             PG8_LDA(At, 1, 1); PG8_STAGE_T(PG8_SB(1, 0), b3, voffB, AUX_B); PG8_STAGE_T(PG8_SB(1, 1), b3 + hstep, voffB, AUX_B); PG8_STAGE_T(PG8_SA(1, 0), a3, voffA, AUX_A);
;             PG8_WAIT_V(8); PG8_WAIT_L(0); PG8_BAR; PG8_MMA(1, 0, At, B0); PG8_MMA(1, 1, At, B1); PG8_BAR; PG8_SCHED;
;     ...
;         if constexpr (ALIGN_EPI) { if (wr == 0) PG8_BAR; }
	v_mfma_f32_16x16x32_bf16 v[64:67], v[190:193], v[224:227], v[64:67]
	s_setprio 0
	s_add_i32 s40, s63, s43
	v_lshl_add_u64 v[150:151], v[150:151], 0, s[8:9]
	s_mov_b32 m0, s40
	ds_read_b128 v[196:199], v168 offset:49152
	ds_read_b128 v[200:203], v168 offset:50176
	ds_read_b128 v[204:207], v168 offset:51200
	ds_read_b128 v[208:211], v168 offset:52224
	ds_read_b128 v[212:215], v168 offset:53248
	ds_read_b128 v[216:219], v168 offset:54272
	ds_read_b128 v[220:223], v168 offset:55296
	ds_read_b128 v[224:227], v168 offset:56320
	global_load_lds_dwordx4 v[150:151], off
	s_add_i32 m0, s40, 0x2000
	s_add_u32 s38, s38, 0x40080
	v_lshl_add_u64 v[150:151], v[154:155], 0, s[8:9]
	s_addc_u32 s39, s39, 0
	s_add_i32 s40, s64, s43
	global_load_lds_dwordx4 v[150:151], off
	v_lshl_add_u64 v[150:151], s[38:39], 0, v[132:133]
	s_mov_b32 m0, s40
	s_nop 0
	global_load_lds_dwordx4 v[150:151], off
	v_lshl_add_u64 v[150:151], s[38:39], 0, v[128:129]
	s_add_i32 m0, s40, 0x2000
	s_nop 0
	global_load_lds_dwordx4 v[150:151], off
	v_lshl_add_u64 v[150:151], v[158:159], 0, s[8:9]
	s_mov_b32 m0, s50
	s_nop 0
	global_load_lds_dwordx4 v[150:151], off
	v_lshl_add_u64 v[150:151], v[228:229], 0, s[8:9]
	s_mov_b32 m0, s51
	s_nop 0
	global_load_lds_dwordx4 v[150:151], off
	s_waitcnt vmcnt(8)
	s_waitcnt lgkmcnt(0)
	s_barrier
	s_waitcnt lgkmcnt(0)
	v_mfma_f32_16x16x32_bf16 v[60:63], v[146:149], v[196:199], v[60:63]
	v_mfma_f32_16x16x32_bf16 v[56:59], v[170:173], v[196:199], v[56:59]
	v_mfma_f32_16x16x32_bf16 v[44:47], v[146:149], v[204:207], v[44:47]
	v_mfma_f32_16x16x32_bf16 v[40:43], v[170:173], v[204:207], v[40:43]
	v_mfma_f32_16x16x32_bf16 v[28:31], v[146:149], v[212:215], v[28:31]
	v_mfma_f32_16x16x32_bf16 v[24:27], v[170:173], v[212:215], v[24:27]
	v_mfma_f32_16x16x32_bf16 v[12:15], v[146:149], v[220:223], v[12:15]
	v_mfma_f32_16x16x32_bf16 v[8:11], v[170:173], v[220:223], v[8:11]
	v_mfma_f32_16x16x32_bf16 v[60:63], v[162:165], v[200:203], v[60:63]
	v_mfma_f32_16x16x32_bf16 v[56:59], v[174:177], v[200:203], v[56:59]
	v_mfma_f32_16x16x32_bf16 v[44:47], v[162:165], v[208:211], v[44:47]
	v_mfma_f32_16x16x32_bf16 v[40:43], v[174:177], v[208:211], v[40:43]
	v_mfma_f32_16x16x32_bf16 v[28:31], v[162:165], v[216:219], v[28:31]
	v_mfma_f32_16x16x32_bf16 v[24:27], v[174:177], v[216:219], v[24:27]
	v_mfma_f32_16x16x32_bf16 v[12:15], v[162:165], v[224:227], v[12:15]
	v_mfma_f32_16x16x32_bf16 v[8:11], v[174:177], v[224:227], v[8:11]
	v_mfma_f32_16x16x32_bf16 v[52:55], v[178:181], v[196:199], v[52:55]
	v_mfma_f32_16x16x32_bf16 v[48:51], v[186:189], v[196:199], v[48:51]
	v_mfma_f32_16x16x32_bf16 v[36:39], v[178:181], v[204:207], v[36:39]
	v_mfma_f32_16x16x32_bf16 v[32:35], v[186:189], v[204:207], v[32:35]
	v_mfma_f32_16x16x32_bf16 v[20:23], v[178:181], v[212:215], v[20:23]
	v_mfma_f32_16x16x32_bf16 v[16:19], v[186:189], v[212:215], v[16:19]
	v_mfma_f32_16x16x32_bf16 v[4:7], v[178:181], v[220:223], v[4:7]
	v_mfma_f32_16x16x32_bf16 v[0:3], v[186:189], v[220:223], v[0:3]
	v_mfma_f32_16x16x32_bf16 v[52:55], v[182:185], v[200:203], v[52:55]
	v_mfma_f32_16x16x32_bf16 v[48:51], v[190:193], v[200:203], v[48:51]
	v_mfma_f32_16x16x32_bf16 v[36:39], v[182:185], v[208:211], v[36:39]
	v_mfma_f32_16x16x32_bf16 v[32:35], v[190:193], v[208:211], v[32:35]
	v_mfma_f32_16x16x32_bf16 v[20:23], v[182:185], v[216:219], v[20:23]
	v_mfma_f32_16x16x32_bf16 v[16:19], v[190:193], v[216:219], v[16:19]
	v_mfma_f32_16x16x32_bf16 v[4:7], v[182:185], v[224:227], v[4:7]
	s_setprio 2
	s_barrier
	v_mfma_f32_16x16x32_bf16 v[0:3], v[190:193], v[224:227], v[0:3]
	s_setprio 0
	s_add_i32 s62, s62, 2
	s_add_u32 s36, s36, 0x100
	s_addc_u32 s37, s37, 0
	s_add_u32 s60, s60, 0x100
	s_addc_u32 s61, s61, 0
	s_cmp_gt_u32 s62, 13
	s_cbranch_scc0 .LBB0_1071
	s_and_b64 vcc, exec, s[10:11]
	s_cbranch_vccz .LBB0_1074
	s_barrier

; #define PG8_STAGE_T(bufoff, gbase, voff, AUX) do { _Pragma("unroll") for (int _i = 0; _i < 2; ++_i) \
;         __builtin_amdgcn_global_load_lds((const unsigned*)((const char*)(gbase) + (voff)[_i]), (PG8_LAS unsigned*)(lds + (bufoff) + ldsw + _i * 8192), 16, 0, AUX); } while (0)
; #define PG8_LDA(dst, b, h) do { _Pragma("unroll") for (int m = 0; m < 4; ++m) _Pragma("unroll") for (int k = 0; k < 2; ++k) dst[m][k] = *(const PG8_LAS bf16x8*)(lds + PG8_SA(b, h) + aoff + m * 2048 + k * 1024); } while (0)
; #define PG8_LDB(dst, b, h) do { _Pragma("unroll") for (int n = 0; n < 2; ++n) _Pragma("unroll") for (int k = 0; k < 2; ++k) dst[n][k] = *(const PG8_LAS bf16x8*)(lds + PG8_SB(b, h) + boff + n * 2048 + k * 1024); } while (0)
; #define PG8_MMA(ai, bj, At, Bt) do { __builtin_amdgcn_s_setprio(1); _Pragma("unroll") for (int m = 0; m < 4; ++m) _Pragma("unroll") for (int n = 0; n < 2; ++n) _Pragma("unroll") for (int k = 0; k < 2; ++k) \
;         acc[ai][bj][m][n] = __builtin_amdgcn_mfma_f32_16x16x32_bf16(Bt[n][k], At[m][k], acc[ai][bj][m][n], 0, 0, 0); __builtin_amdgcn_s_setprio(0); } while (0)
; #define PG8_WAIT_V(n) asm volatile("s_waitcnt vmcnt(" #n ")" ::: "memory")
;     ...
;             const bool last = (t == nt - 2);
;             const char* a1 = cA + (ptrdiff_t)(t + 1) * ck;
;             const char* a2 = last ? nA : cA + (ptrdiff_t)(t + 2) * ck; const char* b2 = last ? nB : cB + (ptrdiff_t)(t + 2) * ck;
;             const ptrdiff_t k3 = last ? nk : ck;
;             const char* a3 = a2 + k3; const char* b3 = b2 + k3;
;             if (last && has_next) S.a_ready(nxt);
;             if constexpr (SP2) {
;             int pei = 0; if constexpr (PEEL) { pei = __builtin_amdgcn_readfirstlane((t == 0 && ui > 0) ? 1 : 0); asm volatile("" : "+s"(pei)); }
;             const bool pe = pei != 0;
;             PG8_LDB(B0, 0, 0); PG8_LDB(B1, 0, 1); PG8_SCHED; PG8_LDA(At, 0, 0); if (!pe) { PG8_STAGE_T(PG8_SA(1, 1), a1 + hstep, voffA, AUX_A); }
;             if (!pe) { PG8_WAIT_V(8); } PG8_WAIT_L(0); PG8_BAR; PG8_MMA(0, 0, At, B0); PG8_MMA(0, 1, At, B1); PG8_BAR; PG8_SCHED;
;             PG8_LDA(At, 0, 1); PG8_STAGE_T(PG8_SB(0, 0), b2, voffB, AUX_B); PG8_STAGE_T(PG8_SB(0, 1), b2 + hstep, voffB, AUX_B); PG8_STAGE_T(PG8_SA(0, 0), a2, voffA, AUX_A);
;             if (!pe) { PG8_WAIT_V(8); } PG8_WAIT_L(0); PG8_BAR; PG8_MMA(1, 0, At, B0); PG8_MMA(1, 1, At, B1); PG8_BAR; PG8_SCHED;
.LBB0_1156:
	ds_read_b128 v[154:157], v149
	s_waitcnt lgkmcnt(0)
	ds_read_b128 v[158:161], v149 offset:1024
	ds_read_b128 v[162:165], v149 offset:2048
	ds_read_b128 v[166:169], v149 offset:3072
	ds_read_b128 v[170:173], v150
	ds_read_b128 v[174:177], v150 offset:1024
	ds_read_b128 v[178:181], v150 offset:2048
	ds_read_b128 v[182:185], v150 offset:3072
	s_add_u32 s26, s24, 0xfff50080
	s_addc_u32 s27, s25, -1
	s_cmp_eq_u32 s55, 40
	s_cselect_b32 s37, s5, s27
	s_cselect_b32 s36, s4, s26
	s_cselect_b32 s27, s23, s54
	s_cselect_b32 s26, s22, s53
	v_lshl_add_u64 v[144:145], s[24:25], 0, v[136:137]
	s_add_i32 m0, s39, 0xc000
	ds_read_b128 v[186:189], v151
	ds_read_b128 v[190:193], v151 offset:1024
	ds_read_b128 v[196:199], v151 offset:2048
	ds_read_b128 v[200:203], v151 offset:3072
	ds_read_b128 v[204:207], v151 offset:4096
	ds_read_b128 v[208:211], v151 offset:5120
	ds_read_b128 v[212:215], v151 offset:6144
	ds_read_b128 v[216:219], v151 offset:7168
	global_load_lds_dwordx4 v[144:145], off
	v_lshl_add_u64 v[144:145], s[24:25], 0, v[138:139]
	s_add_i32 m0, s39, 0xe000
	s_nop 0
	global_load_lds_dwordx4 v[144:145], off
	s_waitcnt vmcnt(8)
	s_waitcnt lgkmcnt(0)
	s_barrier
	s_waitcnt lgkmcnt(0)
	v_mfma_f32_16x16x32_bf16 v[124:127], v[154:157], v[186:189], v[124:127]
	v_mfma_f32_16x16x32_bf16 v[120:123], v[162:165], v[186:189], v[120:123]
	v_mfma_f32_16x16x32_bf16 v[108:111], v[154:157], v[196:199], v[108:111]
	v_mfma_f32_16x16x32_bf16 v[104:107], v[162:165], v[196:199], v[104:107]
	v_mfma_f32_16x16x32_bf16 v[92:95], v[154:157], v[204:207], v[92:95]
	v_mfma_f32_16x16x32_bf16 v[88:91], v[162:165], v[204:207], v[88:91]
	v_mfma_f32_16x16x32_bf16 v[76:79], v[154:157], v[212:215], v[76:79]
	v_mfma_f32_16x16x32_bf16 v[72:75], v[162:165], v[212:215], v[72:75]
	v_mfma_f32_16x16x32_bf16 v[124:127], v[158:161], v[190:193], v[124:127]
	v_mfma_f32_16x16x32_bf16 v[120:123], v[166:169], v[190:193], v[120:123]
	v_mfma_f32_16x16x32_bf16 v[108:111], v[158:161], v[200:203], v[108:111]
	v_mfma_f32_16x16x32_bf16 v[104:107], v[166:169], v[200:203], v[104:107]
	v_mfma_f32_16x16x32_bf16 v[92:95], v[158:161], v[208:211], v[92:95]
	v_mfma_f32_16x16x32_bf16 v[88:91], v[166:169], v[208:211], v[88:91]
	v_mfma_f32_16x16x32_bf16 v[76:79], v[158:161], v[216:219], v[76:79]
	v_mfma_f32_16x16x32_bf16 v[72:75], v[166:169], v[216:219], v[72:75]
	v_mfma_f32_16x16x32_bf16 v[116:119], v[170:173], v[186:189], v[116:119]
	v_mfma_f32_16x16x32_bf16 v[112:115], v[178:181], v[186:189], v[112:115]
	v_mfma_f32_16x16x32_bf16 v[100:103], v[170:173], v[196:199], v[100:103]
	v_mfma_f32_16x16x32_bf16 v[96:99], v[178:181], v[196:199], v[96:99]
	v_mfma_f32_16x16x32_bf16 v[84:87], v[170:173], v[204:207], v[84:87]
	v_mfma_f32_16x16x32_bf16 v[80:83], v[178:181], v[204:207], v[80:83]
	v_mfma_f32_16x16x32_bf16 v[68:71], v[170:173], v[212:215], v[68:71]
	v_mfma_f32_16x16x32_bf16 v[64:67], v[178:181], v[212:215], v[64:67]
	v_mfma_f32_16x16x32_bf16 v[116:119], v[174:177], v[190:193], v[116:119]
	v_mfma_f32_16x16x32_bf16 v[112:115], v[182:185], v[190:193], v[112:115]
	v_mfma_f32_16x16x32_bf16 v[100:103], v[174:177], v[200:203], v[100:103]
	v_mfma_f32_16x16x32_bf16 v[96:99], v[182:185], v[200:203], v[96:99]
	v_mfma_f32_16x16x32_bf16 v[84:87], v[174:177], v[208:211], v[84:87]
	v_mfma_f32_16x16x32_bf16 v[80:83], v[182:185], v[208:211], v[80:83]
	v_mfma_f32_16x16x32_bf16 v[68:71], v[174:177], v[216:219], v[68:71]
	s_setprio 2
	s_barrier
	v_mfma_f32_16x16x32_bf16 v[64:67], v[182:185], v[216:219], v[64:67]
	s_setprio 0
	s_add_i32 s56, s46, s38
	v_lshl_add_u64 v[144:145], s[26:27], 0, v[130:131]
	s_mov_b32 m0, s56
	ds_read_b128 v[186:189], v151 offset:16384
	ds_read_b128 v[190:193], v151 offset:17408
	ds_read_b128 v[196:199], v151 offset:18432
	ds_read_b128 v[200:203], v151 offset:19456
	ds_read_b128 v[204:207], v151 offset:20480
	ds_read_b128 v[208:211], v151 offset:21504
	ds_read_b128 v[212:215], v151 offset:22528
	ds_read_b128 v[216:219], v151 offset:23552
	global_load_lds_dwordx4 v[144:145], off
	s_add_i32 m0, s56, 0x2000
	s_add_u32 s56, s26, 0xb0000
	v_lshl_add_u64 v[220:221], s[26:27], 0, v[134:135]
	s_addc_u32 s57, s27, 0
	s_add_i32 s58, s47, s38
	global_load_lds_dwordx4 v[220:221], off
	v_lshl_add_u64 v[222:223], s[56:57], 0, v[130:131]
	s_mov_b32 m0, s58
	v_lshl_add_u64 v[224:225], s[36:37], 0, v[132:133]
	global_load_lds_dwordx4 v[222:223], off
	v_lshl_add_u64 v[222:223], s[56:57], 0, v[134:135]
	s_add_i32 m0, s58, 0x2000
	s_nop 0
	global_load_lds_dwordx4 v[222:223], off
	v_lshl_add_u64 v[222:223], s[36:37], 0, v[128:129]
	s_mov_b32 m0, s39
	s_nop 0
	global_load_lds_dwordx4 v[222:223], off
	s_mov_b32 m0, s40
	s_nop 0
	global_load_lds_dwordx4 v[224:225], off
	s_waitcnt vmcnt(8)
	s_waitcnt lgkmcnt(0)
	s_barrier
; #define PG8_STAGE_T(bufoff, gbase, voff, AUX) do { _Pragma("unroll") for (int _i = 0; _i < 2; ++_i) \
;         __builtin_amdgcn_global_load_lds((const unsigned*)((const char*)(gbase) + (voff)[_i]), (PG8_LAS unsigned*)(lds + (bufoff) + ldsw + _i * 8192), 16, 0, AUX); } while (0)
; #define PG8_LDA(dst, b, h) do { _Pragma("unroll") for (int m = 0; m < 4; ++m) _Pragma("unroll") for (int k = 0; k < 2; ++k) dst[m][k] = *(const PG8_LAS bf16x8*)(lds + PG8_SA(b, h) + aoff + m * 2048 + k * 1024); } while (0)
; #define PG8_LDB(dst, b, h) do { _Pragma("unroll") for (int n = 0; n < 2; ++n) _Pragma("unroll") for (int k = 0; k < 2; ++k) dst[n][k] = *(const PG8_LAS bf16x8*)(lds + PG8_SB(b, h) + boff + n * 2048 + k * 1024); } while (0)
; #define PG8_MMA(ai, bj, At, Bt) do { __builtin_amdgcn_s_setprio(1); _Pragma("unroll") for (int m = 0; m < 4; ++m) _Pragma("unroll") for (int n = 0; n < 2; ++n) _Pragma("unroll") for (int k = 0; k < 2; ++k) \
;         acc[ai][bj][m][n] = __builtin_amdgcn_mfma_f32_16x16x32_bf16(Bt[n][k], At[m][k], acc[ai][bj][m][n], 0, 0, 0); __builtin_amdgcn_s_setprio(0); } while (0)
; #define PG8_WAIT_V(n) asm volatile("s_waitcnt vmcnt(" #n ")" ::: "memory")
; #define PG8_WAIT_L(n) asm volatile("s_waitcnt lgkmcnt(" #n ")" ::: "memory")
; #define PG8_BAR __builtin_amdgcn_s_barrier()
; #define PG8_SCHED __builtin_amdgcn_sched_barrier(0)
;     ...
;             if (!pe) { PG8_WAIT_V(8); } PG8_WAIT_L(0); PG8_BAR; PG8_MMA(1, 0, At, B0); PG8_MMA(1, 1, At, B1); PG8_BAR; PG8_SCHED;
;             PG8_LDB(B0, 1, 0); PG8_LDB(B1, 1, 1); PG8_SCHED; PG8_LDA(At, 1, 0); PG8_STAGE_T(PG8_SA(0, 1), a2 + hstep, voffA, AUX_A);
;             if (!pe) { PG8_WAIT_V(8); } PG8_WAIT_L(0); PG8_BAR; PG8_MMA(0, 0, At, B0); PG8_MMA(0, 1, At, B1); PG8_BAR; PG8_SCHED;
	s_waitcnt lgkmcnt(0)
	v_mfma_f32_16x16x32_bf16 v[60:63], v[154:157], v[186:189], v[60:63]
	v_mfma_f32_16x16x32_bf16 v[56:59], v[162:165], v[186:189], v[56:59]
	v_mfma_f32_16x16x32_bf16 v[44:47], v[154:157], v[196:199], v[44:47]
	v_mfma_f32_16x16x32_bf16 v[40:43], v[162:165], v[196:199], v[40:43]
	v_mfma_f32_16x16x32_bf16 v[28:31], v[154:157], v[204:207], v[28:31]
	v_mfma_f32_16x16x32_bf16 v[24:27], v[162:165], v[204:207], v[24:27]
	v_mfma_f32_16x16x32_bf16 v[12:15], v[154:157], v[212:215], v[12:15]
	v_mfma_f32_16x16x32_bf16 v[8:11], v[162:165], v[212:215], v[8:11]
	v_mfma_f32_16x16x32_bf16 v[60:63], v[158:161], v[190:193], v[60:63]
	v_mfma_f32_16x16x32_bf16 v[56:59], v[166:169], v[190:193], v[56:59]
	v_mfma_f32_16x16x32_bf16 v[44:47], v[158:161], v[200:203], v[44:47]
	v_mfma_f32_16x16x32_bf16 v[40:43], v[166:169], v[200:203], v[40:43]
	v_mfma_f32_16x16x32_bf16 v[28:31], v[158:161], v[208:211], v[28:31]
	v_mfma_f32_16x16x32_bf16 v[24:27], v[166:169], v[208:211], v[24:27]
	v_mfma_f32_16x16x32_bf16 v[12:15], v[158:161], v[216:219], v[12:15]
	v_mfma_f32_16x16x32_bf16 v[8:11], v[166:169], v[216:219], v[8:11]
	v_mfma_f32_16x16x32_bf16 v[52:55], v[170:173], v[186:189], v[52:55]
	v_mfma_f32_16x16x32_bf16 v[48:51], v[178:181], v[186:189], v[48:51]
	v_mfma_f32_16x16x32_bf16 v[36:39], v[170:173], v[196:199], v[36:39]
	v_mfma_f32_16x16x32_bf16 v[32:35], v[178:181], v[196:199], v[32:35]
	v_mfma_f32_16x16x32_bf16 v[20:23], v[170:173], v[204:207], v[20:23]
	v_mfma_f32_16x16x32_bf16 v[16:19], v[178:181], v[204:207], v[16:19]
	v_mfma_f32_16x16x32_bf16 v[4:7], v[170:173], v[212:215], v[4:7]
	v_mfma_f32_16x16x32_bf16 v[0:3], v[178:181], v[212:215], v[0:3]
	v_mfma_f32_16x16x32_bf16 v[52:55], v[174:177], v[190:193], v[52:55]
	v_mfma_f32_16x16x32_bf16 v[48:51], v[182:185], v[190:193], v[48:51]
	v_mfma_f32_16x16x32_bf16 v[36:39], v[174:177], v[200:203], v[36:39]
	v_mfma_f32_16x16x32_bf16 v[32:35], v[182:185], v[200:203], v[32:35]
	v_mfma_f32_16x16x32_bf16 v[20:23], v[174:177], v[208:211], v[20:23]
	v_mfma_f32_16x16x32_bf16 v[16:19], v[182:185], v[208:211], v[16:19]
	v_mfma_f32_16x16x32_bf16 v[4:7], v[174:177], v[216:219], v[4:7]
	s_setprio 2
	s_barrier
	v_mfma_f32_16x16x32_bf16 v[0:3], v[182:185], v[216:219], v[0:3]
	s_setprio 0
	s_add_i32 s56, 0, 0x18000
	v_add_u32_e32 v153, s56, v147
	s_add_i32 s57, 0, 0x1c000
	ds_read_b128 v[154:157], v153
	ds_read_b128 v[158:161], v153 offset:1024
	ds_read_b128 v[162:165], v153 offset:2048
	ds_read_b128 v[166:169], v153 offset:3072
	v_add_u32_e32 v153, s57, v147
	ds_read_b128 v[170:173], v153
	ds_read_b128 v[174:177], v153 offset:1024
	ds_read_b128 v[178:181], v153 offset:2048
	ds_read_b128 v[182:185], v153 offset:3072
	s_add_u32 s36, s36, 0xb0000
	s_addc_u32 s37, s37, 0
	s_mov_b32 m0, s41
	v_lshl_add_u64 v[226:227], s[36:37], 0, v[128:129]
	ds_read_b128 v[186:189], v151 offset:32768
	ds_read_b128 v[190:193], v151 offset:33792
	ds_read_b128 v[196:199], v151 offset:34816
	ds_read_b128 v[200:203], v151 offset:35840
	ds_read_b128 v[204:207], v151 offset:36864
	ds_read_b128 v[208:211], v151 offset:37888
	ds_read_b128 v[212:215], v151 offset:38912
	ds_read_b128 v[216:219], v151 offset:39936
	global_load_lds_dwordx4 v[226:227], off
	v_lshl_add_u64 v[226:227], s[36:37], 0, v[132:133]
	s_mov_b32 m0, s42
	s_nop 0
	global_load_lds_dwordx4 v[226:227], off
	s_waitcnt vmcnt(8)
	s_waitcnt lgkmcnt(0)
	s_barrier
	s_waitcnt lgkmcnt(0)
	v_mfma_f32_16x16x32_bf16 v[124:127], v[154:157], v[186:189], v[124:127]
	v_mfma_f32_16x16x32_bf16 v[120:123], v[162:165], v[186:189], v[120:123]
	v_mfma_f32_16x16x32_bf16 v[108:111], v[154:157], v[196:199], v[108:111]
	v_mfma_f32_16x16x32_bf16 v[104:107], v[162:165], v[196:199], v[104:107]
	v_mfma_f32_16x16x32_bf16 v[92:95], v[154:157], v[204:207], v[92:95]
	v_mfma_f32_16x16x32_bf16 v[88:91], v[162:165], v[204:207], v[88:91]
	v_mfma_f32_16x16x32_bf16 v[76:79], v[154:157], v[212:215], v[76:79]
	v_mfma_f32_16x16x32_bf16 v[72:75], v[162:165], v[212:215], v[72:75]
	v_mfma_f32_16x16x32_bf16 v[124:127], v[158:161], v[190:193], v[124:127]
	v_mfma_f32_16x16x32_bf16 v[120:123], v[166:169], v[190:193], v[120:123]
	v_mfma_f32_16x16x32_bf16 v[108:111], v[158:161], v[200:203], v[108:111]
	v_mfma_f32_16x16x32_bf16 v[104:107], v[166:169], v[200:203], v[104:107]
	v_mfma_f32_16x16x32_bf16 v[92:95], v[158:161], v[208:211], v[92:95]
	v_mfma_f32_16x16x32_bf16 v[88:91], v[166:169], v[208:211], v[88:91]
	v_mfma_f32_16x16x32_bf16 v[76:79], v[158:161], v[216:219], v[76:79]
	v_mfma_f32_16x16x32_bf16 v[72:75], v[166:169], v[216:219], v[72:75]
	v_mfma_f32_16x16x32_bf16 v[116:119], v[170:173], v[186:189], v[116:119]
	v_mfma_f32_16x16x32_bf16 v[112:115], v[178:181], v[186:189], v[112:115]
	v_mfma_f32_16x16x32_bf16 v[100:103], v[170:173], v[196:199], v[100:103]
	v_mfma_f32_16x16x32_bf16 v[96:99], v[178:181], v[196:199], v[96:99]
	v_mfma_f32_16x16x32_bf16 v[84:87], v[170:173], v[204:207], v[84:87]
	v_mfma_f32_16x16x32_bf16 v[80:83], v[178:181], v[204:207], v[80:83]
	v_mfma_f32_16x16x32_bf16 v[68:71], v[170:173], v[212:215], v[68:71]
	v_mfma_f32_16x16x32_bf16 v[64:67], v[178:181], v[212:215], v[64:67]
	v_mfma_f32_16x16x32_bf16 v[116:119], v[174:177], v[190:193], v[116:119]
	v_mfma_f32_16x16x32_bf16 v[112:115], v[182:185], v[190:193], v[112:115]
	v_mfma_f32_16x16x32_bf16 v[100:103], v[174:177], v[200:203], v[100:103]
	v_mfma_f32_16x16x32_bf16 v[96:99], v[182:185], v[200:203], v[96:99]
	v_mfma_f32_16x16x32_bf16 v[84:87], v[174:177], v[208:211], v[84:87]
	v_mfma_f32_16x16x32_bf16 v[80:83], v[182:185], v[208:211], v[80:83]
	v_mfma_f32_16x16x32_bf16 v[68:71], v[174:177], v[216:219], v[68:71]
	s_setprio 2
	s_barrier
; #define PG8_STAGE_T(bufoff, gbase, voff, AUX) do { _Pragma("unroll") for (int _i = 0; _i < 2; ++_i) \
;         __builtin_amdgcn_global_load_lds((const unsigned*)((const char*)(gbase) + (voff)[_i]), (PG8_LAS unsigned*)(lds + (bufoff) + ldsw + _i * 8192), 16, 0, AUX); } while (0)
; #define PG8_LDA(dst, b, h) do { _Pragma("unroll") for (int m = 0; m < 4; ++m) _Pragma("unroll") for (int k = 0; k < 2; ++k) dst[m][k] = *(const PG8_LAS bf16x8*)(lds + PG8_SA(b, h) + aoff + m * 2048 + k * 1024); } while (0)
; #define PG8_MMA(ai, bj, At, Bt) do { __builtin_amdgcn_s_setprio(1); _Pragma("unroll") for (int m = 0; m < 4; ++m) _Pragma("unroll") for (int n = 0; n < 2; ++n) _Pragma("unroll") for (int k = 0; k < 2; ++k) \
;         acc[ai][bj][m][n] = __builtin_amdgcn_mfma_f32_16x16x32_bf16(Bt[n][k], At[m][k], acc[ai][bj][m][n], 0, 0, 0); __builtin_amdgcn_s_setprio(0); } while (0)
; #define PG8_WAIT_V(n) asm volatile("s_waitcnt vmcnt(" #n ")" ::: "memory")
; #define PG8_WAIT_L(n) asm volatile("s_waitcnt lgkmcnt(" #n ")" ::: "memory")
; #define PG8_BAR __builtin_amdgcn_s_barrier()
; #define PG8_SCHED __builtin_amdgcn_sched_barrier(0)
;     ...
;             if (!pe) { PG8_WAIT_V(8); } PG8_WAIT_L(0); PG8_BAR; PG8_MMA(0, 0, At, B0); PG8_MMA(0, 1, At, B1); PG8_BAR; PG8_SCHED;
;             PG8_LDA(At, 1, 1); PG8_STAGE_T(PG8_SB(1, 0), b3, voffB, AUX_B); PG8_STAGE_T(PG8_SB(1, 1), b3 + hstep, voffB, AUX_B); PG8_STAGE_T(PG8_SA(1, 0), a3, voffA, AUX_A);
;             PG8_WAIT_V(8); PG8_WAIT_L(0); PG8_BAR; PG8_MMA(1, 0, At, B0); PG8_MMA(1, 1, At, B1); PG8_BAR; PG8_SCHED;
;     ...
;         if constexpr (ALIGN_EPI) { if (wr == 0) PG8_BAR; }
	v_mfma_f32_16x16x32_bf16 v[64:67], v[182:185], v[216:219], v[64:67]
	s_setprio 0
	s_add_i32 s36, s56, s38
	v_lshl_add_u64 v[144:145], v[144:145], 0, s[12:13]
	s_mov_b32 m0, s36
	ds_read_b128 v[186:189], v151 offset:49152
	ds_read_b128 v[190:193], v151 offset:50176
	ds_read_b128 v[196:199], v151 offset:51200
	ds_read_b128 v[200:203], v151 offset:52224
	ds_read_b128 v[204:207], v151 offset:53248
	ds_read_b128 v[208:211], v151 offset:54272
	ds_read_b128 v[212:215], v151 offset:55296
	ds_read_b128 v[216:219], v151 offset:56320
	global_load_lds_dwordx4 v[144:145], off
	s_add_i32 m0, s36, 0x2000
	s_add_u32 s26, s26, 0xb0080
	v_lshl_add_u64 v[144:145], v[220:221], 0, s[12:13]
	s_addc_u32 s27, s27, 0
	s_add_i32 s36, s57, s38
	global_load_lds_dwordx4 v[144:145], off
	v_lshl_add_u64 v[144:145], s[26:27], 0, v[130:131]
	s_mov_b32 m0, s36
	s_nop 0
	global_load_lds_dwordx4 v[144:145], off
	v_lshl_add_u64 v[144:145], s[26:27], 0, v[134:135]
	s_add_i32 m0, s36, 0x2000
	s_nop 0
	global_load_lds_dwordx4 v[144:145], off
	v_lshl_add_u64 v[144:145], v[222:223], 0, s[12:13]
	s_mov_b32 m0, s43
	s_nop 0
	global_load_lds_dwordx4 v[144:145], off
	v_lshl_add_u64 v[144:145], v[224:225], 0, s[12:13]
	s_mov_b32 m0, s44
	s_nop 0
	global_load_lds_dwordx4 v[144:145], off
	s_waitcnt vmcnt(8)
	s_waitcnt lgkmcnt(0)
	s_barrier
	s_waitcnt lgkmcnt(0)
	v_mfma_f32_16x16x32_bf16 v[60:63], v[154:157], v[186:189], v[60:63]
	v_mfma_f32_16x16x32_bf16 v[56:59], v[162:165], v[186:189], v[56:59]
	v_mfma_f32_16x16x32_bf16 v[44:47], v[154:157], v[196:199], v[44:47]
	v_mfma_f32_16x16x32_bf16 v[40:43], v[162:165], v[196:199], v[40:43]
	v_mfma_f32_16x16x32_bf16 v[28:31], v[154:157], v[204:207], v[28:31]
	v_mfma_f32_16x16x32_bf16 v[24:27], v[162:165], v[204:207], v[24:27]
	v_mfma_f32_16x16x32_bf16 v[12:15], v[154:157], v[212:215], v[12:15]
	v_mfma_f32_16x16x32_bf16 v[8:11], v[162:165], v[212:215], v[8:11]
	v_mfma_f32_16x16x32_bf16 v[60:63], v[158:161], v[190:193], v[60:63]
	v_mfma_f32_16x16x32_bf16 v[56:59], v[166:169], v[190:193], v[56:59]
	v_mfma_f32_16x16x32_bf16 v[44:47], v[158:161], v[200:203], v[44:47]
	v_mfma_f32_16x16x32_bf16 v[40:43], v[166:169], v[200:203], v[40:43]
	v_mfma_f32_16x16x32_bf16 v[28:31], v[158:161], v[208:211], v[28:31]
	v_mfma_f32_16x16x32_bf16 v[24:27], v[166:169], v[208:211], v[24:27]
	v_mfma_f32_16x16x32_bf16 v[12:15], v[158:161], v[216:219], v[12:15]
	v_mfma_f32_16x16x32_bf16 v[8:11], v[166:169], v[216:219], v[8:11]
	v_mfma_f32_16x16x32_bf16 v[52:55], v[170:173], v[186:189], v[52:55]
	v_mfma_f32_16x16x32_bf16 v[48:51], v[178:181], v[186:189], v[48:51]
	v_mfma_f32_16x16x32_bf16 v[36:39], v[170:173], v[196:199], v[36:39]
	v_mfma_f32_16x16x32_bf16 v[32:35], v[178:181], v[196:199], v[32:35]
	v_mfma_f32_16x16x32_bf16 v[20:23], v[170:173], v[204:207], v[20:23]
	v_mfma_f32_16x16x32_bf16 v[16:19], v[178:181], v[204:207], v[16:19]
	v_mfma_f32_16x16x32_bf16 v[4:7], v[170:173], v[212:215], v[4:7]
	v_mfma_f32_16x16x32_bf16 v[0:3], v[178:181], v[212:215], v[0:3]
	v_mfma_f32_16x16x32_bf16 v[52:55], v[174:177], v[190:193], v[52:55]
	v_mfma_f32_16x16x32_bf16 v[48:51], v[182:185], v[190:193], v[48:51]
	v_mfma_f32_16x16x32_bf16 v[36:39], v[174:177], v[200:203], v[36:39]
	v_mfma_f32_16x16x32_bf16 v[32:35], v[182:185], v[200:203], v[32:35]
	v_mfma_f32_16x16x32_bf16 v[20:23], v[174:177], v[208:211], v[20:23]
	v_mfma_f32_16x16x32_bf16 v[16:19], v[182:185], v[208:211], v[16:19]
	v_mfma_f32_16x16x32_bf16 v[4:7], v[174:177], v[216:219], v[4:7]
	s_setprio 2
	s_barrier
	v_mfma_f32_16x16x32_bf16 v[0:3], v[182:185], v[216:219], v[0:3]
	s_setprio 0
	s_add_i32 s55, s55, 2
	s_add_u32 s24, s24, 0x100
	s_addc_u32 s25, s25, 0
	s_add_u32 s53, s53, 0x100
	s_addc_u32 s54, s54, 0
	s_cmp_gt_u32 s55, 41
	s_cbranch_scc0 .LBB0_1156
	s_and_b64 vcc, exec, s[14:15]
	s_cbranch_vccz .LBB0_1159
	s_barrier

; #define PG8_STAGE_T(bufoff, gbase, voff, AUX) do { _Pragma("unroll") for (int _i = 0; _i < 2; ++_i) \
;         __builtin_amdgcn_global_load_lds((const unsigned*)((const char*)(gbase) + (voff)[_i]), (PG8_LAS unsigned*)(lds + (bufoff) + ldsw + _i * 8192), 16, 0, AUX); } while (0)
; #define PG8_LDA(dst, b, h) do { _Pragma("unroll") for (int m = 0; m < 4; ++m) _Pragma("unroll") for (int k = 0; k < 2; ++k) dst[m][k] = *(const PG8_LAS bf16x8*)(lds + PG8_SA(b, h) + aoff + m * 2048 + k * 1024); } while (0)
; #define PG8_LDB(dst, b, h) do { _Pragma("unroll") for (int n = 0; n < 2; ++n) _Pragma("unroll") for (int k = 0; k < 2; ++k) dst[n][k] = *(const PG8_LAS bf16x8*)(lds + PG8_SB(b, h) + boff + n * 2048 + k * 1024); } while (0)
; #define PG8_MMA(ai, bj, At, Bt) do { __builtin_amdgcn_s_setprio(1); _Pragma("unroll") for (int m = 0; m < 4; ++m) _Pragma("unroll") for (int n = 0; n < 2; ++n) _Pragma("unroll") for (int k = 0; k < 2; ++k) \
;         acc[ai][bj][m][n] = __builtin_amdgcn_mfma_f32_16x16x32_bf16(Bt[n][k], At[m][k], acc[ai][bj][m][n], 0, 0, 0); __builtin_amdgcn_s_setprio(0); } while (0)
; #define PG8_WAIT_V(n) asm volatile("s_waitcnt vmcnt(" #n ")" ::: "memory")
;     ...
;             const bool last = (t == nt - 2);
;             const char* a1 = cA + (ptrdiff_t)(t + 1) * ck;
;             const char* a2 = last ? nA : cA + (ptrdiff_t)(t + 2) * ck; const char* b2 = last ? nB : cB + (ptrdiff_t)(t + 2) * ck;
;             const ptrdiff_t k3 = last ? nk : ck;
;             const char* a3 = a2 + k3; const char* b3 = b2 + k3;
;             if (last && has_next) S.a_ready(nxt);
;             if constexpr (SP2) {
;             int pei = 0; if constexpr (PEEL) { pei = __builtin_amdgcn_readfirstlane((t == 0 && ui > 0) ? 1 : 0); asm volatile("" : "+s"(pei)); }
;             const bool pe = pei != 0;
;             PG8_LDB(B0, 0, 0); PG8_LDB(B1, 0, 1); PG8_SCHED; PG8_LDA(At, 0, 0); if (!pe) { PG8_STAGE_T(PG8_SA(1, 1), a1 + hstep, voffA, AUX_A); }
;             if (!pe) { PG8_WAIT_V(8); } PG8_WAIT_L(0); PG8_BAR; PG8_MMA(0, 0, At, B0); PG8_MMA(0, 1, At, B1); PG8_BAR; PG8_SCHED;
;             PG8_LDA(At, 0, 1); PG8_STAGE_T(PG8_SB(0, 0), b2, voffB, AUX_B); PG8_STAGE_T(PG8_SB(0, 1), b2 + hstep, voffB, AUX_B); PG8_STAGE_T(PG8_SA(0, 0), a2, voffA, AUX_A);
;             if (!pe) { PG8_WAIT_V(8); } PG8_WAIT_L(0); PG8_BAR; PG8_MMA(1, 0, At, B0); PG8_MMA(1, 1, At, B1); PG8_BAR; PG8_SCHED;
.LBB0_1353:
	ds_read_b128 v[144:147], v162
	ds_read_b128 v[148:151], v162 offset:1024
	ds_read_b128 v[152:155], v162 offset:2048
	ds_read_b128 v[166:169], v162 offset:3072
	ds_read_b128 v[170:173], v163
	ds_read_b128 v[174:177], v163 offset:1024
	ds_read_b128 v[178:181], v163 offset:2048
	ds_read_b128 v[182:185], v163 offset:3072
	s_add_u32 s44, s42, 0xfffc0080
	s_addc_u32 s45, s43, -1
	s_cmp_eq_u32 s70, 12
	s_cselect_b32 s47, s25, s45
	s_cselect_b32 s46, s41, s44
	s_cselect_b32 s45, s27, s69
	s_cselect_b32 s44, s67, s68
	v_lshl_add_u64 v[156:157], s[42:43], 0, v[136:137]
	s_add_i32 m0, s50, 0xc000
	ds_read_b128 v[186:189], v164
	ds_read_b128 v[190:193], v164 offset:1024
	ds_read_b128 v[196:199], v164 offset:2048
	ds_read_b128 v[200:203], v164 offset:3072
	ds_read_b128 v[204:207], v164 offset:4096
	ds_read_b128 v[208:211], v164 offset:5120
	ds_read_b128 v[212:215], v164 offset:6144
	ds_read_b128 v[216:219], v164 offset:7168
	global_load_lds_dwordx4 v[156:157], off
	v_lshl_add_u64 v[156:157], s[42:43], 0, v[138:139]
	s_add_i32 m0, s50, 0xe000
	s_nop 0
	global_load_lds_dwordx4 v[156:157], off
	s_waitcnt vmcnt(8)
	s_waitcnt lgkmcnt(0)
	s_barrier
	s_waitcnt lgkmcnt(0)
	v_mfma_f32_16x16x32_bf16 v[124:127], v[144:147], v[186:189], v[124:127]
	v_mfma_f32_16x16x32_bf16 v[120:123], v[152:155], v[186:189], v[120:123]
	v_mfma_f32_16x16x32_bf16 v[108:111], v[144:147], v[196:199], v[108:111]
	v_mfma_f32_16x16x32_bf16 v[104:107], v[152:155], v[196:199], v[104:107]
	v_mfma_f32_16x16x32_bf16 v[92:95], v[144:147], v[204:207], v[92:95]
	v_mfma_f32_16x16x32_bf16 v[88:91], v[152:155], v[204:207], v[88:91]
	v_mfma_f32_16x16x32_bf16 v[76:79], v[144:147], v[212:215], v[76:79]
	v_mfma_f32_16x16x32_bf16 v[72:75], v[152:155], v[212:215], v[72:75]
	v_mfma_f32_16x16x32_bf16 v[124:127], v[148:151], v[190:193], v[124:127]
	v_mfma_f32_16x16x32_bf16 v[120:123], v[166:169], v[190:193], v[120:123]
	v_mfma_f32_16x16x32_bf16 v[108:111], v[148:151], v[200:203], v[108:111]
	v_mfma_f32_16x16x32_bf16 v[104:107], v[166:169], v[200:203], v[104:107]
	v_mfma_f32_16x16x32_bf16 v[92:95], v[148:151], v[208:211], v[92:95]
	v_mfma_f32_16x16x32_bf16 v[88:91], v[166:169], v[208:211], v[88:91]
	v_mfma_f32_16x16x32_bf16 v[76:79], v[148:151], v[216:219], v[76:79]
	v_mfma_f32_16x16x32_bf16 v[72:75], v[166:169], v[216:219], v[72:75]
	v_mfma_f32_16x16x32_bf16 v[116:119], v[170:173], v[186:189], v[116:119]
	v_mfma_f32_16x16x32_bf16 v[112:115], v[178:181], v[186:189], v[112:115]
	v_mfma_f32_16x16x32_bf16 v[100:103], v[170:173], v[196:199], v[100:103]
	v_mfma_f32_16x16x32_bf16 v[96:99], v[178:181], v[196:199], v[96:99]
	v_mfma_f32_16x16x32_bf16 v[84:87], v[170:173], v[204:207], v[84:87]
	v_mfma_f32_16x16x32_bf16 v[80:83], v[178:181], v[204:207], v[80:83]
	v_mfma_f32_16x16x32_bf16 v[68:71], v[170:173], v[212:215], v[68:71]
	v_mfma_f32_16x16x32_bf16 v[64:67], v[178:181], v[212:215], v[64:67]
	v_mfma_f32_16x16x32_bf16 v[116:119], v[174:177], v[190:193], v[116:119]
	v_mfma_f32_16x16x32_bf16 v[112:115], v[182:185], v[190:193], v[112:115]
	v_mfma_f32_16x16x32_bf16 v[100:103], v[174:177], v[200:203], v[100:103]
	v_mfma_f32_16x16x32_bf16 v[96:99], v[182:185], v[200:203], v[96:99]
	v_mfma_f32_16x16x32_bf16 v[84:87], v[174:177], v[208:211], v[84:87]
	v_mfma_f32_16x16x32_bf16 v[80:83], v[182:185], v[208:211], v[80:83]
	v_mfma_f32_16x16x32_bf16 v[68:71], v[174:177], v[216:219], v[68:71]
	s_setprio 2
	s_barrier
	v_mfma_f32_16x16x32_bf16 v[64:67], v[182:185], v[216:219], v[64:67]
	s_setprio 0
	s_add_i32 s71, s57, s49
	v_lshl_add_u64 v[156:157], s[44:45], 0, v[130:131]
	s_mov_b32 m0, s71
	ds_read_b128 v[186:189], v164 offset:16384
	ds_read_b128 v[190:193], v164 offset:17408
	ds_read_b128 v[196:199], v164 offset:18432
	ds_read_b128 v[200:203], v164 offset:19456
	ds_read_b128 v[204:207], v164 offset:20480
	ds_read_b128 v[208:211], v164 offset:21504
	ds_read_b128 v[212:215], v164 offset:22528
	ds_read_b128 v[216:219], v164 offset:23552
	global_load_lds_dwordx4 v[156:157], off
	s_add_i32 m0, s71, 0x2000
	s_add_u32 s76, s44, 0x40000
	v_lshl_add_u64 v[220:221], s[44:45], 0, v[134:135]
	s_addc_u32 s77, s45, 0
	s_add_i32 s71, s58, s49
	global_load_lds_dwordx4 v[220:221], off
	v_lshl_add_u64 v[222:223], s[76:77], 0, v[130:131]
	s_mov_b32 m0, s71
	v_lshl_add_u64 v[224:225], s[46:47], 0, v[132:133]
	global_load_lds_dwordx4 v[222:223], off
	v_lshl_add_u64 v[222:223], s[76:77], 0, v[134:135]
	s_add_i32 m0, s71, 0x2000
	s_nop 0
	global_load_lds_dwordx4 v[222:223], off
	v_lshl_add_u64 v[222:223], s[46:47], 0, v[128:129]
	s_mov_b32 m0, s50
	s_nop 0
	global_load_lds_dwordx4 v[222:223], off
	s_mov_b32 m0, s51
	s_nop 0
	global_load_lds_dwordx4 v[224:225], off
	s_waitcnt vmcnt(8)
	s_waitcnt lgkmcnt(0)
	s_barrier
; #define PG8_STAGE_T(bufoff, gbase, voff, AUX) do { _Pragma("unroll") for (int _i = 0; _i < 2; ++_i) \
;         __builtin_amdgcn_global_load_lds((const unsigned*)((const char*)(gbase) + (voff)[_i]), (PG8_LAS unsigned*)(lds + (bufoff) + ldsw + _i * 8192), 16, 0, AUX); } while (0)
; #define PG8_LDA(dst, b, h) do { _Pragma("unroll") for (int m = 0; m < 4; ++m) _Pragma("unroll") for (int k = 0; k < 2; ++k) dst[m][k] = *(const PG8_LAS bf16x8*)(lds + PG8_SA(b, h) + aoff + m * 2048 + k * 1024); } while (0)
; #define PG8_LDB(dst, b, h) do { _Pragma("unroll") for (int n = 0; n < 2; ++n) _Pragma("unroll") for (int k = 0; k < 2; ++k) dst[n][k] = *(const PG8_LAS bf16x8*)(lds + PG8_SB(b, h) + boff + n * 2048 + k * 1024); } while (0)
; #define PG8_MMA(ai, bj, At, Bt) do { __builtin_amdgcn_s_setprio(1); _Pragma("unroll") for (int m = 0; m < 4; ++m) _Pragma("unroll") for (int n = 0; n < 2; ++n) _Pragma("unroll") for (int k = 0; k < 2; ++k) \
;         acc[ai][bj][m][n] = __builtin_amdgcn_mfma_f32_16x16x32_bf16(Bt[n][k], At[m][k], acc[ai][bj][m][n], 0, 0, 0); __builtin_amdgcn_s_setprio(0); } while (0)
; #define PG8_WAIT_V(n) asm volatile("s_waitcnt vmcnt(" #n ")" ::: "memory")
; #define PG8_WAIT_L(n) asm volatile("s_waitcnt lgkmcnt(" #n ")" ::: "memory")
; #define PG8_BAR __builtin_amdgcn_s_barrier()
; #define PG8_SCHED __builtin_amdgcn_sched_barrier(0)
;     ...
;             if (!pe) { PG8_WAIT_V(8); } PG8_WAIT_L(0); PG8_BAR; PG8_MMA(1, 0, At, B0); PG8_MMA(1, 1, At, B1); PG8_BAR; PG8_SCHED;
;             PG8_LDB(B0, 1, 0); PG8_LDB(B1, 1, 1); PG8_SCHED; PG8_LDA(At, 1, 0); PG8_STAGE_T(PG8_SA(0, 1), a2 + hstep, voffA, AUX_A);
;             if (!pe) { PG8_WAIT_V(8); } PG8_WAIT_L(0); PG8_BAR; PG8_MMA(0, 0, At, B0); PG8_MMA(0, 1, At, B1); PG8_BAR; PG8_SCHED;
	s_waitcnt lgkmcnt(0)
	v_mfma_f32_16x16x32_bf16 v[60:63], v[144:147], v[186:189], v[60:63]
	v_mfma_f32_16x16x32_bf16 v[56:59], v[152:155], v[186:189], v[56:59]
	v_mfma_f32_16x16x32_bf16 v[44:47], v[144:147], v[196:199], v[44:47]
	v_mfma_f32_16x16x32_bf16 v[40:43], v[152:155], v[196:199], v[40:43]
	v_mfma_f32_16x16x32_bf16 v[28:31], v[144:147], v[204:207], v[28:31]
	v_mfma_f32_16x16x32_bf16 v[24:27], v[152:155], v[204:207], v[24:27]
	v_mfma_f32_16x16x32_bf16 v[12:15], v[144:147], v[212:215], v[12:15]
	v_mfma_f32_16x16x32_bf16 v[8:11], v[152:155], v[212:215], v[8:11]
	v_mfma_f32_16x16x32_bf16 v[60:63], v[148:151], v[190:193], v[60:63]
	v_mfma_f32_16x16x32_bf16 v[56:59], v[166:169], v[190:193], v[56:59]
	v_mfma_f32_16x16x32_bf16 v[44:47], v[148:151], v[200:203], v[44:47]
	v_mfma_f32_16x16x32_bf16 v[40:43], v[166:169], v[200:203], v[40:43]
	v_mfma_f32_16x16x32_bf16 v[28:31], v[148:151], v[208:211], v[28:31]
	v_mfma_f32_16x16x32_bf16 v[24:27], v[166:169], v[208:211], v[24:27]
	v_mfma_f32_16x16x32_bf16 v[12:15], v[148:151], v[216:219], v[12:15]
	v_mfma_f32_16x16x32_bf16 v[8:11], v[166:169], v[216:219], v[8:11]
	v_mfma_f32_16x16x32_bf16 v[52:55], v[170:173], v[186:189], v[52:55]
	v_mfma_f32_16x16x32_bf16 v[48:51], v[178:181], v[186:189], v[48:51]
	v_mfma_f32_16x16x32_bf16 v[36:39], v[170:173], v[196:199], v[36:39]
	v_mfma_f32_16x16x32_bf16 v[32:35], v[178:181], v[196:199], v[32:35]
	v_mfma_f32_16x16x32_bf16 v[20:23], v[170:173], v[204:207], v[20:23]
	v_mfma_f32_16x16x32_bf16 v[16:19], v[178:181], v[204:207], v[16:19]
	v_mfma_f32_16x16x32_bf16 v[4:7], v[170:173], v[212:215], v[4:7]
	v_mfma_f32_16x16x32_bf16 v[0:3], v[178:181], v[212:215], v[0:3]
	v_mfma_f32_16x16x32_bf16 v[52:55], v[174:177], v[190:193], v[52:55]
	v_mfma_f32_16x16x32_bf16 v[48:51], v[182:185], v[190:193], v[48:51]
	v_mfma_f32_16x16x32_bf16 v[36:39], v[174:177], v[200:203], v[36:39]
	v_mfma_f32_16x16x32_bf16 v[32:35], v[182:185], v[200:203], v[32:35]
	v_mfma_f32_16x16x32_bf16 v[20:23], v[174:177], v[208:211], v[20:23]
	v_mfma_f32_16x16x32_bf16 v[16:19], v[182:185], v[208:211], v[16:19]
	v_mfma_f32_16x16x32_bf16 v[4:7], v[174:177], v[216:219], v[4:7]
	s_setprio 2
	s_barrier
	v_mfma_f32_16x16x32_bf16 v[0:3], v[182:185], v[216:219], v[0:3]
	s_setprio 0
	s_add_i32 s71, 0, 0x18000
	v_add_u32_e32 v165, s71, v159
	s_add_i32 s76, 0, 0x1c000
	ds_read_b128 v[144:147], v165
	ds_read_b128 v[148:151], v165 offset:1024
	ds_read_b128 v[152:155], v165 offset:2048
	ds_read_b128 v[166:169], v165 offset:3072
	v_add_u32_e32 v165, s76, v159
	ds_read_b128 v[170:173], v165
	ds_read_b128 v[174:177], v165 offset:1024
	ds_read_b128 v[178:181], v165 offset:2048
	ds_read_b128 v[182:185], v165 offset:3072
	s_add_u32 s46, s46, 0x40000
	s_addc_u32 s47, s47, 0
	s_mov_b32 m0, s52
	v_lshl_add_u64 v[226:227], s[46:47], 0, v[128:129]
	ds_read_b128 v[186:189], v164 offset:32768
	ds_read_b128 v[190:193], v164 offset:33792
	ds_read_b128 v[196:199], v164 offset:34816
	ds_read_b128 v[200:203], v164 offset:35840
	ds_read_b128 v[204:207], v164 offset:36864
	ds_read_b128 v[208:211], v164 offset:37888
	ds_read_b128 v[212:215], v164 offset:38912
	ds_read_b128 v[216:219], v164 offset:39936
	global_load_lds_dwordx4 v[226:227], off
	v_lshl_add_u64 v[226:227], s[46:47], 0, v[132:133]
	s_mov_b32 m0, s53
	s_nop 0
	global_load_lds_dwordx4 v[226:227], off
	s_waitcnt vmcnt(8)
	s_waitcnt lgkmcnt(0)
	s_barrier
	s_waitcnt lgkmcnt(0)
	v_mfma_f32_16x16x32_bf16 v[124:127], v[144:147], v[186:189], v[124:127]
	v_mfma_f32_16x16x32_bf16 v[120:123], v[152:155], v[186:189], v[120:123]
	v_mfma_f32_16x16x32_bf16 v[108:111], v[144:147], v[196:199], v[108:111]
	v_mfma_f32_16x16x32_bf16 v[104:107], v[152:155], v[196:199], v[104:107]
	v_mfma_f32_16x16x32_bf16 v[92:95], v[144:147], v[204:207], v[92:95]
	v_mfma_f32_16x16x32_bf16 v[88:91], v[152:155], v[204:207], v[88:91]
	v_mfma_f32_16x16x32_bf16 v[76:79], v[144:147], v[212:215], v[76:79]
	v_mfma_f32_16x16x32_bf16 v[72:75], v[152:155], v[212:215], v[72:75]
	v_mfma_f32_16x16x32_bf16 v[124:127], v[148:151], v[190:193], v[124:127]
	v_mfma_f32_16x16x32_bf16 v[120:123], v[166:169], v[190:193], v[120:123]
	v_mfma_f32_16x16x32_bf16 v[108:111], v[148:151], v[200:203], v[108:111]
	v_mfma_f32_16x16x32_bf16 v[104:107], v[166:169], v[200:203], v[104:107]
	v_mfma_f32_16x16x32_bf16 v[92:95], v[148:151], v[208:211], v[92:95]
	v_mfma_f32_16x16x32_bf16 v[88:91], v[166:169], v[208:211], v[88:91]
	v_mfma_f32_16x16x32_bf16 v[76:79], v[148:151], v[216:219], v[76:79]
	v_mfma_f32_16x16x32_bf16 v[72:75], v[166:169], v[216:219], v[72:75]
	v_mfma_f32_16x16x32_bf16 v[116:119], v[170:173], v[186:189], v[116:119]
	v_mfma_f32_16x16x32_bf16 v[112:115], v[178:181], v[186:189], v[112:115]
	v_mfma_f32_16x16x32_bf16 v[100:103], v[170:173], v[196:199], v[100:103]
	v_mfma_f32_16x16x32_bf16 v[96:99], v[178:181], v[196:199], v[96:99]
	v_mfma_f32_16x16x32_bf16 v[84:87], v[170:173], v[204:207], v[84:87]
	v_mfma_f32_16x16x32_bf16 v[80:83], v[178:181], v[204:207], v[80:83]
	v_mfma_f32_16x16x32_bf16 v[68:71], v[170:173], v[212:215], v[68:71]
	v_mfma_f32_16x16x32_bf16 v[64:67], v[178:181], v[212:215], v[64:67]
	v_mfma_f32_16x16x32_bf16 v[116:119], v[174:177], v[190:193], v[116:119]
	v_mfma_f32_16x16x32_bf16 v[112:115], v[182:185], v[190:193], v[112:115]
	v_mfma_f32_16x16x32_bf16 v[100:103], v[174:177], v[200:203], v[100:103]
	v_mfma_f32_16x16x32_bf16 v[96:99], v[182:185], v[200:203], v[96:99]
	v_mfma_f32_16x16x32_bf16 v[84:87], v[174:177], v[208:211], v[84:87]
	v_mfma_f32_16x16x32_bf16 v[80:83], v[182:185], v[208:211], v[80:83]
	v_mfma_f32_16x16x32_bf16 v[68:71], v[174:177], v[216:219], v[68:71]
	s_setprio 2
	s_barrier
; #define PG8_STAGE_T(bufoff, gbase, voff, AUX) do { _Pragma("unroll") for (int _i = 0; _i < 2; ++_i) \
;         __builtin_amdgcn_global_load_lds((const unsigned*)((const char*)(gbase) + (voff)[_i]), (PG8_LAS unsigned*)(lds + (bufoff) + ldsw + _i * 8192), 16, 0, AUX); } while (0)
; #define PG8_LDA(dst, b, h) do { _Pragma("unroll") for (int m = 0; m < 4; ++m) _Pragma("unroll") for (int k = 0; k < 2; ++k) dst[m][k] = *(const PG8_LAS bf16x8*)(lds + PG8_SA(b, h) + aoff + m * 2048 + k * 1024); } while (0)
; #define PG8_MMA(ai, bj, At, Bt) do { __builtin_amdgcn_s_setprio(1); _Pragma("unroll") for (int m = 0; m < 4; ++m) _Pragma("unroll") for (int n = 0; n < 2; ++n) _Pragma("unroll") for (int k = 0; k < 2; ++k) \
;         acc[ai][bj][m][n] = __builtin_amdgcn_mfma_f32_16x16x32_bf16(Bt[n][k], At[m][k], acc[ai][bj][m][n], 0, 0, 0); __builtin_amdgcn_s_setprio(0); } while (0)
; #define PG8_WAIT_V(n) asm volatile("s_waitcnt vmcnt(" #n ")" ::: "memory")
; #define PG8_WAIT_L(n) asm volatile("s_waitcnt lgkmcnt(" #n ")" ::: "memory")
; #define PG8_BAR __builtin_amdgcn_s_barrier()
; #define PG8_SCHED __builtin_amdgcn_sched_barrier(0)
;     ...
;             if (!pe) { PG8_WAIT_V(8); } PG8_WAIT_L(0); PG8_BAR; PG8_MMA(0, 0, At, B0); PG8_MMA(0, 1, At, B1); PG8_BAR; PG8_SCHED;
;             PG8_LDA(At, 1, 1); PG8_STAGE_T(PG8_SB(1, 0), b3, voffB, AUX_B); PG8_STAGE_T(PG8_SB(1, 1), b3 + hstep, voffB, AUX_B); PG8_STAGE_T(PG8_SA(1, 0), a3, voffA, AUX_A);
;             PG8_WAIT_V(8); PG8_WAIT_L(0); PG8_BAR; PG8_MMA(1, 0, At, B0); PG8_MMA(1, 1, At, B1); PG8_BAR; PG8_SCHED;
;     ...
;         if constexpr (ALIGN_EPI) { if (wr == 0) PG8_BAR; }
	v_mfma_f32_16x16x32_bf16 v[64:67], v[182:185], v[216:219], v[64:67]
	s_setprio 0
	s_add_i32 s46, s71, s49
	v_lshl_add_u64 v[156:157], v[156:157], 0, s[8:9]
	s_mov_b32 m0, s46
	ds_read_b128 v[186:189], v164 offset:49152
	ds_read_b128 v[190:193], v164 offset:50176
	ds_read_b128 v[196:199], v164 offset:51200
	ds_read_b128 v[200:203], v164 offset:52224
	ds_read_b128 v[204:207], v164 offset:53248
	ds_read_b128 v[208:211], v164 offset:54272
	ds_read_b128 v[212:215], v164 offset:55296
	ds_read_b128 v[216:219], v164 offset:56320
	global_load_lds_dwordx4 v[156:157], off
	s_add_i32 m0, s46, 0x2000
	s_add_u32 s44, s44, 0x40080
	v_lshl_add_u64 v[156:157], v[220:221], 0, s[8:9]
	s_addc_u32 s45, s45, 0
	s_add_i32 s46, s76, s49
	global_load_lds_dwordx4 v[156:157], off
	v_lshl_add_u64 v[156:157], s[44:45], 0, v[130:131]
	s_mov_b32 m0, s46
	s_nop 0
	global_load_lds_dwordx4 v[156:157], off
	v_lshl_add_u64 v[156:157], s[44:45], 0, v[134:135]
	s_add_i32 m0, s46, 0x2000
	s_nop 0
	global_load_lds_dwordx4 v[156:157], off
	v_lshl_add_u64 v[156:157], v[222:223], 0, s[8:9]
	s_mov_b32 m0, s55
	s_nop 0
	global_load_lds_dwordx4 v[156:157], off
	v_lshl_add_u64 v[156:157], v[224:225], 0, s[8:9]
	s_mov_b32 m0, s56
	s_nop 0
	global_load_lds_dwordx4 v[156:157], off
	s_waitcnt vmcnt(8)
	s_waitcnt lgkmcnt(0)
	s_barrier
	s_waitcnt lgkmcnt(0)
	v_mfma_f32_16x16x32_bf16 v[60:63], v[144:147], v[186:189], v[60:63]
	v_mfma_f32_16x16x32_bf16 v[56:59], v[152:155], v[186:189], v[56:59]
	v_mfma_f32_16x16x32_bf16 v[44:47], v[144:147], v[196:199], v[44:47]
	v_mfma_f32_16x16x32_bf16 v[40:43], v[152:155], v[196:199], v[40:43]
	v_mfma_f32_16x16x32_bf16 v[28:31], v[144:147], v[204:207], v[28:31]
	v_mfma_f32_16x16x32_bf16 v[24:27], v[152:155], v[204:207], v[24:27]
	v_mfma_f32_16x16x32_bf16 v[12:15], v[144:147], v[212:215], v[12:15]
	v_mfma_f32_16x16x32_bf16 v[8:11], v[152:155], v[212:215], v[8:11]
	v_mfma_f32_16x16x32_bf16 v[60:63], v[148:151], v[190:193], v[60:63]
	v_mfma_f32_16x16x32_bf16 v[56:59], v[166:169], v[190:193], v[56:59]
	v_mfma_f32_16x16x32_bf16 v[44:47], v[148:151], v[200:203], v[44:47]
	v_mfma_f32_16x16x32_bf16 v[40:43], v[166:169], v[200:203], v[40:43]
	v_mfma_f32_16x16x32_bf16 v[28:31], v[148:151], v[208:211], v[28:31]
	v_mfma_f32_16x16x32_bf16 v[24:27], v[166:169], v[208:211], v[24:27]
	v_mfma_f32_16x16x32_bf16 v[12:15], v[148:151], v[216:219], v[12:15]
	v_mfma_f32_16x16x32_bf16 v[8:11], v[166:169], v[216:219], v[8:11]
	v_mfma_f32_16x16x32_bf16 v[52:55], v[170:173], v[186:189], v[52:55]
	v_mfma_f32_16x16x32_bf16 v[48:51], v[178:181], v[186:189], v[48:51]
	v_mfma_f32_16x16x32_bf16 v[36:39], v[170:173], v[196:199], v[36:39]
	v_mfma_f32_16x16x32_bf16 v[32:35], v[178:181], v[196:199], v[32:35]
	v_mfma_f32_16x16x32_bf16 v[20:23], v[170:173], v[204:207], v[20:23]
	v_mfma_f32_16x16x32_bf16 v[16:19], v[178:181], v[204:207], v[16:19]
	v_mfma_f32_16x16x32_bf16 v[4:7], v[170:173], v[212:215], v[4:7]
	v_mfma_f32_16x16x32_bf16 v[0:3], v[178:181], v[212:215], v[0:3]
	v_mfma_f32_16x16x32_bf16 v[52:55], v[174:177], v[190:193], v[52:55]
	v_mfma_f32_16x16x32_bf16 v[48:51], v[182:185], v[190:193], v[48:51]
	v_mfma_f32_16x16x32_bf16 v[36:39], v[174:177], v[200:203], v[36:39]
	v_mfma_f32_16x16x32_bf16 v[32:35], v[182:185], v[200:203], v[32:35]
	v_mfma_f32_16x16x32_bf16 v[20:23], v[174:177], v[208:211], v[20:23]
	v_mfma_f32_16x16x32_bf16 v[16:19], v[182:185], v[208:211], v[16:19]
	v_mfma_f32_16x16x32_bf16 v[4:7], v[174:177], v[216:219], v[4:7]
	s_setprio 2
	s_barrier
	v_mfma_f32_16x16x32_bf16 v[0:3], v[182:185], v[216:219], v[0:3]
	s_setprio 0
	s_add_i32 s70, s70, 2
	s_add_u32 s42, s42, 0x100
	s_addc_u32 s43, s43, 0
	s_add_u32 s68, s68, 0x100
	s_addc_u32 s69, s69, 0
	s_cmp_gt_u32 s70, 13
	s_cbranch_scc0 .LBB0_1353
	s_and_b64 vcc, exec, s[10:11]
	s_cbranch_vccz .LBB0_1356
	s_barrier

; #define PG8_STAGE_T(bufoff, gbase, voff, AUX) do { _Pragma("unroll") for (int _i = 0; _i < 2; ++_i) \
;         __builtin_amdgcn_global_load_lds((const unsigned*)((const char*)(gbase) + (voff)[_i]), (PG8_LAS unsigned*)(lds + (bufoff) + ldsw + _i * 8192), 16, 0, AUX); } while (0)
; #define PG8_LDA(dst, b, h) do { _Pragma("unroll") for (int m = 0; m < 4; ++m) _Pragma("unroll") for (int k = 0; k < 2; ++k) dst[m][k] = *(const PG8_LAS bf16x8*)(lds + PG8_SA(b, h) + aoff + m * 2048 + k * 1024); } while (0)
; #define PG8_LDB(dst, b, h) do { _Pragma("unroll") for (int n = 0; n < 2; ++n) _Pragma("unroll") for (int k = 0; k < 2; ++k) dst[n][k] = *(const PG8_LAS bf16x8*)(lds + PG8_SB(b, h) + boff + n * 2048 + k * 1024); } while (0)
; #define PG8_MMA(ai, bj, At, Bt) do { __builtin_amdgcn_s_setprio(1); _Pragma("unroll") for (int m = 0; m < 4; ++m) _Pragma("unroll") for (int n = 0; n < 2; ++n) _Pragma("unroll") for (int k = 0; k < 2; ++k) \
;         acc[ai][bj][m][n] = __builtin_amdgcn_mfma_f32_16x16x32_bf16(Bt[n][k], At[m][k], acc[ai][bj][m][n], 0, 0, 0); __builtin_amdgcn_s_setprio(0); } while (0)
; #define PG8_WAIT_V(n) asm volatile("s_waitcnt vmcnt(" #n ")" ::: "memory")
;     ...
;             const bool last = (t == nt - 2);
;             const char* a1 = cA + (ptrdiff_t)(t + 1) * ck;
;             const char* a2 = last ? nA : cA + (ptrdiff_t)(t + 2) * ck; const char* b2 = last ? nB : cB + (ptrdiff_t)(t + 2) * ck;
;             const ptrdiff_t k3 = last ? nk : ck;
;             const char* a3 = a2 + k3; const char* b3 = b2 + k3;
;             if (last && has_next) S.a_ready(nxt);
;             if constexpr (SP2) {
;             int pei = 0; if constexpr (PEEL) { pei = __builtin_amdgcn_readfirstlane((t == 0 && ui > 0) ? 1 : 0); asm volatile("" : "+s"(pei)); }
;             const bool pe = pei != 0;
;             PG8_LDB(B0, 0, 0); PG8_LDB(B1, 0, 1); PG8_SCHED; PG8_LDA(At, 0, 0); if (!pe) { PG8_STAGE_T(PG8_SA(1, 1), a1 + hstep, voffA, AUX_A); }
;             if (!pe) { PG8_WAIT_V(8); } PG8_WAIT_L(0); PG8_BAR; PG8_MMA(0, 0, At, B0); PG8_MMA(0, 1, At, B1); PG8_BAR; PG8_SCHED;
;             PG8_LDA(At, 0, 1); PG8_STAGE_T(PG8_SB(0, 0), b2, voffB, AUX_B); PG8_STAGE_T(PG8_SB(0, 1), b2 + hstep, voffB, AUX_B); PG8_STAGE_T(PG8_SA(0, 0), a2, voffA, AUX_A);
;             if (!pe) { PG8_WAIT_V(8); } PG8_WAIT_L(0); PG8_BAR; PG8_MMA(1, 0, At, B0); PG8_MMA(1, 1, At, B1); PG8_BAR; PG8_SCHED;
.LBB0_1389:
	ds_read_b128 v[128:131], v173
	ds_read_b128 v[132:135], v173 offset:1024
	ds_read_b128 v[152:155], v173 offset:2048
	ds_read_b128 v[156:159], v173 offset:3072
	s_waitcnt lgkmcnt(0)
	ds_read_b128 v[160:163], v174
	ds_read_b128 v[164:167], v174 offset:1024
	ds_read_b128 v[178:181], v174 offset:2048
	ds_read_b128 v[182:185], v174 offset:3072
	s_add_i32 s61, s40, 2
	s_add_u32 s62, s38, 0x80
	s_addc_u32 s41, s39, 0
	s_cmp_eq_u32 s50, s40
	s_cselect_b32 s40, s6, s62
	s_cselect_b32 s41, s7, s41
	s_cselect_b32 s63, s37, s60
	s_cselect_b32 s62, s36, s59
	v_lshl_add_u64 v[168:169], s[38:39], 0, v[144:145]
	s_add_i32 m0, s43, 0xc000
	ds_read_b128 v[186:189], v175
	ds_read_b128 v[190:193], v175 offset:1024
	ds_read_b128 v[196:199], v175 offset:2048
	ds_read_b128 v[200:203], v175 offset:3072
	ds_read_b128 v[204:207], v175 offset:4096
	ds_read_b128 v[208:211], v175 offset:5120
	ds_read_b128 v[212:215], v175 offset:6144
	ds_read_b128 v[216:219], v175 offset:7168
	global_load_lds_dwordx4 v[168:169], off
	v_lshl_add_u64 v[168:169], s[38:39], 0, v[146:147]
	s_add_i32 m0, s43, 0xe000
	s_nop 0
	global_load_lds_dwordx4 v[168:169], off
	s_waitcnt vmcnt(8)
	s_waitcnt lgkmcnt(0)
	s_barrier
	s_waitcnt lgkmcnt(0)
	v_mfma_f32_16x16x32_bf16 v[124:127], v[128:131], v[186:189], v[124:127]
	v_mfma_f32_16x16x32_bf16 v[120:123], v[152:155], v[186:189], v[120:123]
	v_mfma_f32_16x16x32_bf16 v[108:111], v[128:131], v[196:199], v[108:111]
	v_mfma_f32_16x16x32_bf16 v[104:107], v[152:155], v[196:199], v[104:107]
	v_mfma_f32_16x16x32_bf16 v[92:95], v[128:131], v[204:207], v[92:95]
	v_mfma_f32_16x16x32_bf16 v[88:91], v[152:155], v[204:207], v[88:91]
	v_mfma_f32_16x16x32_bf16 v[76:79], v[128:131], v[212:215], v[76:79]
	v_mfma_f32_16x16x32_bf16 v[72:75], v[152:155], v[212:215], v[72:75]
	v_mfma_f32_16x16x32_bf16 v[124:127], v[132:135], v[190:193], v[124:127]
	v_mfma_f32_16x16x32_bf16 v[120:123], v[156:159], v[190:193], v[120:123]
	v_mfma_f32_16x16x32_bf16 v[108:111], v[132:135], v[200:203], v[108:111]
	v_mfma_f32_16x16x32_bf16 v[104:107], v[156:159], v[200:203], v[104:107]
	v_mfma_f32_16x16x32_bf16 v[92:95], v[132:135], v[208:211], v[92:95]
	v_mfma_f32_16x16x32_bf16 v[88:91], v[156:159], v[208:211], v[88:91]
	v_mfma_f32_16x16x32_bf16 v[76:79], v[132:135], v[216:219], v[76:79]
	v_mfma_f32_16x16x32_bf16 v[72:75], v[156:159], v[216:219], v[72:75]
	v_mfma_f32_16x16x32_bf16 v[116:119], v[160:163], v[186:189], v[116:119]
	v_mfma_f32_16x16x32_bf16 v[112:115], v[178:181], v[186:189], v[112:115]
	v_mfma_f32_16x16x32_bf16 v[100:103], v[160:163], v[196:199], v[100:103]
	v_mfma_f32_16x16x32_bf16 v[96:99], v[178:181], v[196:199], v[96:99]
	v_mfma_f32_16x16x32_bf16 v[84:87], v[160:163], v[204:207], v[84:87]
	v_mfma_f32_16x16x32_bf16 v[80:83], v[178:181], v[204:207], v[80:83]
	v_mfma_f32_16x16x32_bf16 v[68:71], v[160:163], v[212:215], v[68:71]
	v_mfma_f32_16x16x32_bf16 v[64:67], v[178:181], v[212:215], v[64:67]
	v_mfma_f32_16x16x32_bf16 v[116:119], v[164:167], v[190:193], v[116:119]
	v_mfma_f32_16x16x32_bf16 v[112:115], v[182:185], v[190:193], v[112:115]
	v_mfma_f32_16x16x32_bf16 v[100:103], v[164:167], v[200:203], v[100:103]
	v_mfma_f32_16x16x32_bf16 v[96:99], v[182:185], v[200:203], v[96:99]
	v_mfma_f32_16x16x32_bf16 v[84:87], v[164:167], v[208:211], v[84:87]
	v_mfma_f32_16x16x32_bf16 v[80:83], v[182:185], v[208:211], v[80:83]
	v_mfma_f32_16x16x32_bf16 v[68:71], v[164:167], v[216:219], v[68:71]
	s_setprio 2
	s_barrier
	v_mfma_f32_16x16x32_bf16 v[64:67], v[182:185], v[216:219], v[64:67]
	s_setprio 0
	s_add_i32 s64, s52, s42
	v_lshl_add_u64 v[168:169], s[62:63], 0, v[138:139]
	s_mov_b32 m0, s64
	ds_read_b128 v[186:189], v175 offset:16384
	ds_read_b128 v[190:193], v175 offset:17408
	ds_read_b128 v[196:199], v175 offset:18432
	ds_read_b128 v[200:203], v175 offset:19456
	ds_read_b128 v[204:207], v175 offset:20480
	ds_read_b128 v[208:211], v175 offset:21504
	ds_read_b128 v[212:215], v175 offset:22528
	ds_read_b128 v[216:219], v175 offset:23552
	global_load_lds_dwordx4 v[168:169], off
	s_add_i32 m0, s64, 0x2000
	v_lshl_add_u64 v[220:221], s[62:63], 0, v[142:143]
	s_add_u32 s62, s62, s10
	s_addc_u32 s63, s63, s11
	s_add_i32 s64, s53, s42
	global_load_lds_dwordx4 v[220:221], off
	v_lshl_add_u64 v[222:223], s[62:63], 0, v[138:139]
	s_mov_b32 m0, s64
	v_lshl_add_u64 v[224:225], s[62:63], 0, v[142:143]
	global_load_lds_dwordx4 v[222:223], off
	s_add_i32 m0, s64, 0x2000
	v_lshl_add_u64 v[226:227], s[40:41], 0, v[136:137]
	global_load_lds_dwordx4 v[224:225], off
	s_mov_b32 m0, s43
	v_lshl_add_u64 v[228:229], s[40:41], 0, v[140:141]
	global_load_lds_dwordx4 v[226:227], off
	s_mov_b32 m0, s44
	s_nop 0
	global_load_lds_dwordx4 v[228:229], off
	s_waitcnt vmcnt(8)
	s_waitcnt lgkmcnt(0)
	s_barrier
; #define PG8_STAGE_T(bufoff, gbase, voff, AUX) do { _Pragma("unroll") for (int _i = 0; _i < 2; ++_i) \
;         __builtin_amdgcn_global_load_lds((const unsigned*)((const char*)(gbase) + (voff)[_i]), (PG8_LAS unsigned*)(lds + (bufoff) + ldsw + _i * 8192), 16, 0, AUX); } while (0)
; #define PG8_LDA(dst, b, h) do { _Pragma("unroll") for (int m = 0; m < 4; ++m) _Pragma("unroll") for (int k = 0; k < 2; ++k) dst[m][k] = *(const PG8_LAS bf16x8*)(lds + PG8_SA(b, h) + aoff + m * 2048 + k * 1024); } while (0)
; #define PG8_LDB(dst, b, h) do { _Pragma("unroll") for (int n = 0; n < 2; ++n) _Pragma("unroll") for (int k = 0; k < 2; ++k) dst[n][k] = *(const PG8_LAS bf16x8*)(lds + PG8_SB(b, h) + boff + n * 2048 + k * 1024); } while (0)
; #define PG8_MMA(ai, bj, At, Bt) do { __builtin_amdgcn_s_setprio(1); _Pragma("unroll") for (int m = 0; m < 4; ++m) _Pragma("unroll") for (int n = 0; n < 2; ++n) _Pragma("unroll") for (int k = 0; k < 2; ++k) \
;         acc[ai][bj][m][n] = __builtin_amdgcn_mfma_f32_16x16x32_bf16(Bt[n][k], At[m][k], acc[ai][bj][m][n], 0, 0, 0); __builtin_amdgcn_s_setprio(0); } while (0)
; #define PG8_WAIT_V(n) asm volatile("s_waitcnt vmcnt(" #n ")" ::: "memory")
; #define PG8_WAIT_L(n) asm volatile("s_waitcnt lgkmcnt(" #n ")" ::: "memory")
; #define PG8_BAR __builtin_amdgcn_s_barrier()
; #define PG8_SCHED __builtin_amdgcn_sched_barrier(0)
;     ...
;             if (!pe) { PG8_WAIT_V(8); } PG8_WAIT_L(0); PG8_BAR; PG8_MMA(1, 0, At, B0); PG8_MMA(1, 1, At, B1); PG8_BAR; PG8_SCHED;
;             PG8_LDB(B0, 1, 0); PG8_LDB(B1, 1, 1); PG8_SCHED; PG8_LDA(At, 1, 0); PG8_STAGE_T(PG8_SA(0, 1), a2 + hstep, voffA, AUX_A);
;             if (!pe) { PG8_WAIT_V(8); } PG8_WAIT_L(0); PG8_BAR; PG8_MMA(0, 0, At, B0); PG8_MMA(0, 1, At, B1); PG8_BAR; PG8_SCHED;
	s_waitcnt lgkmcnt(0)
	v_mfma_f32_16x16x32_bf16 v[60:63], v[128:131], v[186:189], v[60:63]
	v_mfma_f32_16x16x32_bf16 v[56:59], v[152:155], v[186:189], v[56:59]
	v_mfma_f32_16x16x32_bf16 v[44:47], v[128:131], v[196:199], v[44:47]
	v_mfma_f32_16x16x32_bf16 v[40:43], v[152:155], v[196:199], v[40:43]
	v_mfma_f32_16x16x32_bf16 v[28:31], v[128:131], v[204:207], v[28:31]
	v_mfma_f32_16x16x32_bf16 v[24:27], v[152:155], v[204:207], v[24:27]
	v_mfma_f32_16x16x32_bf16 v[12:15], v[128:131], v[212:215], v[12:15]
	v_mfma_f32_16x16x32_bf16 v[8:11], v[152:155], v[212:215], v[8:11]
	v_mfma_f32_16x16x32_bf16 v[60:63], v[132:135], v[190:193], v[60:63]
	v_mfma_f32_16x16x32_bf16 v[56:59], v[156:159], v[190:193], v[56:59]
	v_mfma_f32_16x16x32_bf16 v[44:47], v[132:135], v[200:203], v[44:47]
	v_mfma_f32_16x16x32_bf16 v[40:43], v[156:159], v[200:203], v[40:43]
	v_mfma_f32_16x16x32_bf16 v[28:31], v[132:135], v[208:211], v[28:31]
	v_mfma_f32_16x16x32_bf16 v[24:27], v[156:159], v[208:211], v[24:27]
	v_mfma_f32_16x16x32_bf16 v[12:15], v[132:135], v[216:219], v[12:15]
	v_mfma_f32_16x16x32_bf16 v[8:11], v[156:159], v[216:219], v[8:11]
	v_mfma_f32_16x16x32_bf16 v[52:55], v[160:163], v[186:189], v[52:55]
	v_mfma_f32_16x16x32_bf16 v[48:51], v[178:181], v[186:189], v[48:51]
	v_mfma_f32_16x16x32_bf16 v[36:39], v[160:163], v[196:199], v[36:39]
	v_mfma_f32_16x16x32_bf16 v[32:35], v[178:181], v[196:199], v[32:35]
	v_mfma_f32_16x16x32_bf16 v[20:23], v[160:163], v[204:207], v[20:23]
	v_mfma_f32_16x16x32_bf16 v[16:19], v[178:181], v[204:207], v[16:19]
	v_mfma_f32_16x16x32_bf16 v[4:7], v[160:163], v[212:215], v[4:7]
	v_mfma_f32_16x16x32_bf16 v[0:3], v[178:181], v[212:215], v[0:3]
	v_mfma_f32_16x16x32_bf16 v[52:55], v[164:167], v[190:193], v[52:55]
	v_mfma_f32_16x16x32_bf16 v[48:51], v[182:185], v[190:193], v[48:51]
	v_mfma_f32_16x16x32_bf16 v[36:39], v[164:167], v[200:203], v[36:39]
	v_mfma_f32_16x16x32_bf16 v[32:35], v[182:185], v[200:203], v[32:35]
	v_mfma_f32_16x16x32_bf16 v[20:23], v[164:167], v[208:211], v[20:23]
	v_mfma_f32_16x16x32_bf16 v[16:19], v[182:185], v[208:211], v[16:19]
	v_mfma_f32_16x16x32_bf16 v[4:7], v[164:167], v[216:219], v[4:7]
	s_setprio 2
	s_barrier
	v_mfma_f32_16x16x32_bf16 v[0:3], v[182:185], v[216:219], v[0:3]
	s_setprio 0
	s_add_i32 s62, 0, 0x18000
	s_add_i32 s63, 0, 0x1c000
	v_add_u32_e32 v156, s62, v171
	v_add_u32_e32 v177, s63, v171
	ds_read_b128 v[128:131], v156
	ds_read_b128 v[132:135], v156 offset:1024
	ds_read_b128 v[152:155], v156 offset:2048
	ds_read_b128 v[156:159], v156 offset:3072
	ds_read_b128 v[160:163], v177
	ds_read_b128 v[164:167], v177 offset:1024
	ds_read_b128 v[178:181], v177 offset:2048
	ds_read_b128 v[182:185], v177 offset:3072
	s_add_u32 s40, s40, s10
	s_addc_u32 s41, s41, s11
	s_mov_b32 m0, s45
	v_lshl_add_u64 v[230:231], s[40:41], 0, v[136:137]
	ds_read_b128 v[186:189], v175 offset:32768
	ds_read_b128 v[190:193], v175 offset:33792
	ds_read_b128 v[196:199], v175 offset:34816
	ds_read_b128 v[200:203], v175 offset:35840
	ds_read_b128 v[204:207], v175 offset:36864
	ds_read_b128 v[208:211], v175 offset:37888
	ds_read_b128 v[212:215], v175 offset:38912
	ds_read_b128 v[216:219], v175 offset:39936
	global_load_lds_dwordx4 v[230:231], off
	v_lshl_add_u64 v[230:231], s[40:41], 0, v[140:141]
	s_mov_b32 m0, s46
	s_nop 0
	global_load_lds_dwordx4 v[230:231], off
	s_waitcnt vmcnt(8)
	s_waitcnt lgkmcnt(0)
	s_barrier
	s_waitcnt lgkmcnt(0)
	v_mfma_f32_16x16x32_bf16 v[124:127], v[128:131], v[186:189], v[124:127]
	v_mfma_f32_16x16x32_bf16 v[120:123], v[152:155], v[186:189], v[120:123]
	v_mfma_f32_16x16x32_bf16 v[108:111], v[128:131], v[196:199], v[108:111]
	v_mfma_f32_16x16x32_bf16 v[104:107], v[152:155], v[196:199], v[104:107]
	v_mfma_f32_16x16x32_bf16 v[92:95], v[128:131], v[204:207], v[92:95]
	v_mfma_f32_16x16x32_bf16 v[88:91], v[152:155], v[204:207], v[88:91]
	v_mfma_f32_16x16x32_bf16 v[76:79], v[128:131], v[212:215], v[76:79]
	v_mfma_f32_16x16x32_bf16 v[72:75], v[152:155], v[212:215], v[72:75]
	v_mfma_f32_16x16x32_bf16 v[124:127], v[132:135], v[190:193], v[124:127]
	v_mfma_f32_16x16x32_bf16 v[120:123], v[156:159], v[190:193], v[120:123]
	v_mfma_f32_16x16x32_bf16 v[108:111], v[132:135], v[200:203], v[108:111]
	v_mfma_f32_16x16x32_bf16 v[104:107], v[156:159], v[200:203], v[104:107]
	v_mfma_f32_16x16x32_bf16 v[92:95], v[132:135], v[208:211], v[92:95]
	v_mfma_f32_16x16x32_bf16 v[88:91], v[156:159], v[208:211], v[88:91]
	v_mfma_f32_16x16x32_bf16 v[76:79], v[132:135], v[216:219], v[76:79]
	v_mfma_f32_16x16x32_bf16 v[72:75], v[156:159], v[216:219], v[72:75]
	v_mfma_f32_16x16x32_bf16 v[116:119], v[160:163], v[186:189], v[116:119]
	v_mfma_f32_16x16x32_bf16 v[112:115], v[178:181], v[186:189], v[112:115]
	v_mfma_f32_16x16x32_bf16 v[100:103], v[160:163], v[196:199], v[100:103]
	v_mfma_f32_16x16x32_bf16 v[96:99], v[178:181], v[196:199], v[96:99]
	v_mfma_f32_16x16x32_bf16 v[84:87], v[160:163], v[204:207], v[84:87]
	v_mfma_f32_16x16x32_bf16 v[80:83], v[178:181], v[204:207], v[80:83]
	v_mfma_f32_16x16x32_bf16 v[68:71], v[160:163], v[212:215], v[68:71]
	v_mfma_f32_16x16x32_bf16 v[64:67], v[178:181], v[212:215], v[64:67]
	v_mfma_f32_16x16x32_bf16 v[116:119], v[164:167], v[190:193], v[116:119]
	v_mfma_f32_16x16x32_bf16 v[112:115], v[182:185], v[190:193], v[112:115]
	v_mfma_f32_16x16x32_bf16 v[100:103], v[164:167], v[200:203], v[100:103]
	v_mfma_f32_16x16x32_bf16 v[96:99], v[182:185], v[200:203], v[96:99]
	v_mfma_f32_16x16x32_bf16 v[84:87], v[164:167], v[208:211], v[84:87]
	v_mfma_f32_16x16x32_bf16 v[80:83], v[182:185], v[208:211], v[80:83]
	v_mfma_f32_16x16x32_bf16 v[68:71], v[164:167], v[216:219], v[68:71]
	s_setprio 2
	s_barrier
; #define PG8_STAGE_T(bufoff, gbase, voff, AUX) do { _Pragma("unroll") for (int _i = 0; _i < 2; ++_i) \
;         __builtin_amdgcn_global_load_lds((const unsigned*)((const char*)(gbase) + (voff)[_i]), (PG8_LAS unsigned*)(lds + (bufoff) + ldsw + _i * 8192), 16, 0, AUX); } while (0)
; #define PG8_LDA(dst, b, h) do { _Pragma("unroll") for (int m = 0; m < 4; ++m) _Pragma("unroll") for (int k = 0; k < 2; ++k) dst[m][k] = *(const PG8_LAS bf16x8*)(lds + PG8_SA(b, h) + aoff + m * 2048 + k * 1024); } while (0)
; #define PG8_MMA(ai, bj, At, Bt) do { __builtin_amdgcn_s_setprio(1); _Pragma("unroll") for (int m = 0; m < 4; ++m) _Pragma("unroll") for (int n = 0; n < 2; ++n) _Pragma("unroll") for (int k = 0; k < 2; ++k) \
;         acc[ai][bj][m][n] = __builtin_amdgcn_mfma_f32_16x16x32_bf16(Bt[n][k], At[m][k], acc[ai][bj][m][n], 0, 0, 0); __builtin_amdgcn_s_setprio(0); } while (0)
; #define PG8_WAIT_V(n) asm volatile("s_waitcnt vmcnt(" #n ")" ::: "memory")
; #define PG8_WAIT_L(n) asm volatile("s_waitcnt lgkmcnt(" #n ")" ::: "memory")
; #define PG8_BAR __builtin_amdgcn_s_barrier()
; #define PG8_SCHED __builtin_amdgcn_sched_barrier(0)
;     ...
;             if (!pe) { PG8_WAIT_V(8); } PG8_WAIT_L(0); PG8_BAR; PG8_MMA(0, 0, At, B0); PG8_MMA(0, 1, At, B1); PG8_BAR; PG8_SCHED;
;             PG8_LDA(At, 1, 1); PG8_STAGE_T(PG8_SB(1, 0), b3, voffB, AUX_B); PG8_STAGE_T(PG8_SB(1, 1), b3 + hstep, voffB, AUX_B); PG8_STAGE_T(PG8_SA(1, 0), a3, voffA, AUX_A);
;             PG8_WAIT_V(8); PG8_WAIT_L(0); PG8_BAR; PG8_MMA(1, 0, At, B0); PG8_MMA(1, 1, At, B1); PG8_BAR; PG8_SCHED;
	v_mfma_f32_16x16x32_bf16 v[64:67], v[182:185], v[216:219], v[64:67]
	s_setprio 0
	s_add_i32 s40, s62, s42
	v_lshl_add_u64 v[168:169], v[168:169], 0, s[24:25]
	s_mov_b32 m0, s40
	ds_read_b128 v[186:189], v175 offset:49152
	ds_read_b128 v[190:193], v175 offset:50176
	ds_read_b128 v[196:199], v175 offset:51200
	ds_read_b128 v[200:203], v175 offset:52224
	ds_read_b128 v[204:207], v175 offset:53248
	ds_read_b128 v[208:211], v175 offset:54272
	ds_read_b128 v[212:215], v175 offset:55296
	ds_read_b128 v[216:219], v175 offset:56320
	global_load_lds_dwordx4 v[168:169], off
	v_lshl_add_u64 v[168:169], v[220:221], 0, s[24:25]
	s_add_i32 m0, s40, 0x2000
	s_add_i32 s40, s63, s42
	global_load_lds_dwordx4 v[168:169], off
	v_lshl_add_u64 v[168:169], v[222:223], 0, s[24:25]
	s_mov_b32 m0, s40
	s_nop 0
	global_load_lds_dwordx4 v[168:169], off
	v_lshl_add_u64 v[168:169], v[224:225], 0, s[24:25]
	s_add_i32 m0, s40, 0x2000
	s_nop 0
	global_load_lds_dwordx4 v[168:169], off
	v_lshl_add_u64 v[168:169], v[226:227], 0, s[24:25]
	s_mov_b32 m0, s47
	s_nop 0
	global_load_lds_dwordx4 v[168:169], off
	v_lshl_add_u64 v[168:169], v[228:229], 0, s[24:25]
	s_mov_b32 m0, s48
	s_nop 0
	global_load_lds_dwordx4 v[168:169], off
	s_waitcnt vmcnt(8)
	s_waitcnt lgkmcnt(0)
	s_barrier
	s_waitcnt lgkmcnt(0)
	v_mfma_f32_16x16x32_bf16 v[60:63], v[128:131], v[186:189], v[60:63]
	v_mfma_f32_16x16x32_bf16 v[56:59], v[152:155], v[186:189], v[56:59]
	v_mfma_f32_16x16x32_bf16 v[44:47], v[128:131], v[196:199], v[44:47]
	v_mfma_f32_16x16x32_bf16 v[40:43], v[152:155], v[196:199], v[40:43]
	v_mfma_f32_16x16x32_bf16 v[28:31], v[128:131], v[204:207], v[28:31]
	v_mfma_f32_16x16x32_bf16 v[24:27], v[152:155], v[204:207], v[24:27]
	v_mfma_f32_16x16x32_bf16 v[12:15], v[128:131], v[212:215], v[12:15]
	v_mfma_f32_16x16x32_bf16 v[8:11], v[152:155], v[212:215], v[8:11]
	v_mfma_f32_16x16x32_bf16 v[60:63], v[132:135], v[190:193], v[60:63]
	v_mfma_f32_16x16x32_bf16 v[56:59], v[156:159], v[190:193], v[56:59]
	v_mfma_f32_16x16x32_bf16 v[44:47], v[132:135], v[200:203], v[44:47]
	v_mfma_f32_16x16x32_bf16 v[40:43], v[156:159], v[200:203], v[40:43]
	v_mfma_f32_16x16x32_bf16 v[28:31], v[132:135], v[208:211], v[28:31]
	v_mfma_f32_16x16x32_bf16 v[24:27], v[156:159], v[208:211], v[24:27]
	v_mfma_f32_16x16x32_bf16 v[12:15], v[132:135], v[216:219], v[12:15]
	v_mfma_f32_16x16x32_bf16 v[8:11], v[156:159], v[216:219], v[8:11]
	v_mfma_f32_16x16x32_bf16 v[52:55], v[160:163], v[186:189], v[52:55]
	v_mfma_f32_16x16x32_bf16 v[48:51], v[178:181], v[186:189], v[48:51]
	v_mfma_f32_16x16x32_bf16 v[36:39], v[160:163], v[196:199], v[36:39]
	v_mfma_f32_16x16x32_bf16 v[32:35], v[178:181], v[196:199], v[32:35]
	v_mfma_f32_16x16x32_bf16 v[20:23], v[160:163], v[204:207], v[20:23]
	v_mfma_f32_16x16x32_bf16 v[16:19], v[178:181], v[204:207], v[16:19]
	v_mfma_f32_16x16x32_bf16 v[4:7], v[160:163], v[212:215], v[4:7]
	v_mfma_f32_16x16x32_bf16 v[0:3], v[178:181], v[212:215], v[0:3]
	v_mfma_f32_16x16x32_bf16 v[52:55], v[164:167], v[190:193], v[52:55]
	v_mfma_f32_16x16x32_bf16 v[48:51], v[182:185], v[190:193], v[48:51]
	v_mfma_f32_16x16x32_bf16 v[36:39], v[164:167], v[200:203], v[36:39]
	v_mfma_f32_16x16x32_bf16 v[32:35], v[182:185], v[200:203], v[32:35]
	v_mfma_f32_16x16x32_bf16 v[20:23], v[164:167], v[208:211], v[20:23]
	v_mfma_f32_16x16x32_bf16 v[16:19], v[182:185], v[208:211], v[16:19]
	v_mfma_f32_16x16x32_bf16 v[4:7], v[164:167], v[216:219], v[4:7]
	s_setprio 2
	s_barrier
	v_mfma_f32_16x16x32_bf16 v[0:3], v[182:185], v[216:219], v[0:3]
	s_setprio 0
	s_add_u32 s38, s38, 0x100
	s_addc_u32 s39, s39, 0
	s_add_u32 s59, s59, 0x100
	s_addc_u32 s60, s60, 0
	s_cmp_ge_i32 s61, s49
	s_mov_b32 s40, s61
	s_cbranch_scc0 .LBB0_1389
